# scan loop v2: LDS operand loads interleaved with the VALU stream, y write without exec toggling; resid epilogue stat loads no longer drain the queue; rg gate rows prefetched per tile
# speedup vs baseline: 1.0142x; 1.0042x over previous
; #define LAS __attribute__((address_space(3)))
; __device__ __forceinline__ void rwkv_block(KP p, int o, int b, int hd, LAS unsigned char* lds, const bf16_t* P, bf16_t* YB) {
;     ...
;         const int L = wid * 64 + lane, rp = L >> 3, c = L & 7;
;         f32x2 s[2][4];
; #pragma unroll
;         for (int a = 0; a < 2; ++a)
; #pragma unroll
;             for (int j = 0; j < 4; ++j) s[a][j] = (f32x2){0.f, 0.f};
;         LDS_BAR();
; #pragma unroll 1
;         for (int n = 0; n < 256; ++n) {
;             LAS float* B = (LAS float*)(lds + BUF0 + (n & 1) * BUFSZ);
;             LAS float* Wd = B; LAS float* KK = B + 1024; LAS float* BB = B + 2048; LAS float* KM = B + 3072; LAS float* Rr = B + 4096; LAS float* Vv = B + 5120; LAS float* Yy = B + 7168;
;             f32x2 sv[2][4];
; #pragma unroll
;             for (int a = 0; a < 2; ++a)
; #pragma unroll
;                 for (int j = 0; j < 4; ++j) sv[a][j] = s[a][j];
; #pragma unroll 1
;             for (int rep2 = 0; rep2 < ((DUP_MASK & 128) ? 2 : 1); ++rep2) {
;             if (rep2 == 1) {
; #pragma unroll
;                 for (int a = 0; a < 2; ++a)
; #pragma unroll
;                     for (int j = 0; j < 4; ++j) s[a][j] = sv[a][j];
;             }
; #pragma unroll
;             for (int tt = 0; tt < 16; ++tt) {
;                 const int o8 = tt * 64 + c * 8;
;                 const f32x4 ka = *(const LAS f32x4*)(KK + o8), kb = *(const LAS f32x4*)(KK + o8 + 4);
;                 const f32x4 wa = *(const LAS f32x4*)(Wd + o8), wb = *(const LAS f32x4*)(Wd + o8 + 4);
;                 const f32x4 ba = *(const LAS f32x4*)(BB + o8), bb = *(const LAS f32x4*)(BB + o8 + 4);
;                 const f32x4 ma = *(const LAS f32x4*)(KM + o8), mb = *(const LAS f32x4*)(KM + o8 + 4);
;                 const f32x4 ra = *(const LAS f32x4*)(Rr + o8), rb = *(const LAS f32x4*)(Rr + o8 + 4);
;                 const f32x2 v01 = *(const LAS f32x2*)(Vv + tt * 64 + 2 * rp);
;                 const f32x2 k2[4] = {{ka[0], ka[1]}, {ka[2], ka[3]}, {kb[0], kb[1]}, {kb[2], kb[3]}};
;                 const f32x2 w2[4] = {{wa[0], wa[1]}, {wa[2], wa[3]}, {wb[0], wb[1]}, {wb[2], wb[3]}};
;                 const f32x2 b2[4] = {{ba[0], ba[1]}, {ba[2], ba[3]}, {bb[0], bb[1]}, {bb[2], bb[3]}};
;                 const f32x2 m2[4] = {{ma[0], ma[1]}, {ma[2], ma[3]}, {mb[0], mb[1]}, {mb[2], mb[3]}};
.LBB0_232:
	s_andn2_saveexec_b64 s[10:11], s[20:21]
	s_cbranch_execz .LBB0_156
	v_and_b32_e32 v3, 7, v2
	v_and_b32_e32 v185, 15, v2
	v_lshlrev_b32_e32 v185, 3, v185
	v_add_u32_e32 v185, 0x15520, v185
	s_waitcnt lgkmcnt(0)
	s_barrier
	s_setprio 2
	v_ashrrev_i32_e32 v2, 2, v2
	v_lshlrev_b32_e32 v182, 5, v3
	v_and_b32_e32 v2, -2, v2
	v_lshlrev_b32_e32 v183, 2, v2
	v_cmp_eq_u32_e32 vcc, 0, v3
	s_mov_b64 s[12:13], exec
	s_mov_b32 s1, 0
	v_mov_b32_e32 v2, 0
	v_mov_b32_e32 v3, 0
	v_mov_b32_e32 v4, 0
	v_mov_b32_e32 v5, 0
	v_mov_b32_e32 v6, 0
	v_mov_b32_e32 v7, 0
	v_mov_b32_e32 v8, 0
	v_mov_b32_e32 v9, 0
	v_mov_b32_e32 v10, 0
	v_mov_b32_e32 v11, 0
	v_mov_b32_e32 v12, 0
	v_mov_b32_e32 v13, 0
	v_mov_b32_e32 v14, 0
	v_mov_b32_e32 v15, 0
	v_mov_b32_e32 v16, 0
	v_mov_b32_e32 v17, 0
.Lrk_scan_loop:
	s_bitcmp1_b32 s1, 0
	s_cselect_b32 s7, 0x8040, 0
	s_add_i32 s7, s7, 0xc300
	v_add_u32_e32 v180, s7, v182
	v_add_u32_e32 v181, s7, v183
	v_cndmask_b32_e32 v184, v185, v181, vcc
	ds_read_b128 v[64:67], v180 offset:4096
	ds_read_b128 v[68:71], v180 offset:4112
	ds_read_b64 v[104:105], v181 offset:20480
	ds_read_b128 v[88:91], v180 offset:12288
	ds_read_b128 v[92:95], v180 offset:12304
	ds_read_b128 v[72:75], v180 offset:0
	ds_read_b128 v[76:79], v180 offset:16
	ds_read_b128 v[80:83], v180 offset:8192
	ds_read_b128 v[84:87], v180 offset:8208
	ds_read_b128 v[96:99], v180 offset:16384
	ds_read_b128 v[100:103], v180 offset:16400
	s_waitcnt lgkmcnt(0)
	v_pk_mul_f32 v[20:21], v[2:3], v[64:65] op_sel_hi:[1,0]
	v_pk_mul_f32 v[22:23], v[10:11], v[68:69] op_sel_hi:[1,0]
	ds_read_b128 v[110:113], v180 offset:4352
	v_pk_fma_f32 v[20:21], v[4:5], v[64:65], v[20:21] op_sel:[0,1,0]
	v_pk_fma_f32 v[22:23], v[12:13], v[68:69], v[22:23] op_sel:[0,1,0]
	ds_read_b128 v[114:117], v180 offset:4368
	v_pk_fma_f32 v[20:21], v[6:7], v[66:67], v[20:21] op_sel_hi:[1,0,1]
	v_pk_fma_f32 v[22:23], v[14:15], v[70:71], v[22:23] op_sel_hi:[1,0,1]
	ds_read_b64 v[150:151], v181 offset:20736
	v_pk_fma_f32 v[20:21], v[8:9], v[66:67], v[20:21] op_sel:[0,1,0]
	v_pk_fma_f32 v[22:23], v[16:17], v[70:71], v[22:23] op_sel:[0,1,0]
	ds_read_b128 v[134:137], v180 offset:12544
	ds_read_b128 v[138:141], v180 offset:12560
	v_pk_add_f32 v[20:21], v[20:21], v[22:23]
	ds_read_b128 v[118:121], v180 offset:256
	ds_read_b128 v[122:125], v180 offset:272
	v_add_f32_dpp v20, v20, v20 quad_perm:[1,0,3,2] row_mask:0xf bank_mask:0xf bound_ctrl:1
	v_add_f32_dpp v21, v21, v21 quad_perm:[1,0,3,2] row_mask:0xf bank_mask:0xf bound_ctrl:1
	ds_read_b128 v[126:129], v180 offset:8448
	v_add_f32_dpp v20, v20, v20 quad_perm:[2,3,0,1] row_mask:0xf bank_mask:0xf bound_ctrl:1
	v_add_f32_dpp v21, v21, v21 quad_perm:[2,3,0,1] row_mask:0xf bank_mask:0xf bound_ctrl:1
	ds_read_b128 v[130:133], v180 offset:8464
	v_add_f32_dpp v20, v20, v20 row_half_mirror row_mask:0xf bank_mask:0xf bound_ctrl:1
	v_add_f32_dpp v21, v21, v21 row_half_mirror row_mask:0xf bank_mask:0xf bound_ctrl:1
	ds_read_b128 v[142:145], v180 offset:16640
	ds_read_b128 v[146:149], v180 offset:16656
	v_pk_mul_f32 v[24:25], v[104:105], v[88:89] op_sel_hi:[1,0]
	v_pk_mul_f32 v[26:27], v[104:105], v[88:89] op_sel:[0,1]
	v_pk_mul_f32 v[28:29], v[104:105], v[90:91] op_sel_hi:[1,0]
	v_pk_fma_f32 v[24:25], v[2:3], v[72:73], v[24:25] op_sel_hi:[1,0,1]
	v_pk_fma_f32 v[26:27], v[4:5], v[72:73], v[26:27] op_sel:[0,1,0]
	v_pk_fma_f32 v[28:29], v[6:7], v[74:75], v[28:29] op_sel_hi:[1,0,1]
	v_pk_fma_f32 v[2:3], v[20:21], v[80:81], v[24:25] op_sel_hi:[1,0,1]
	v_pk_fma_f32 v[4:5], v[20:21], v[80:81], v[26:27] op_sel:[0,1,0]
	v_pk_fma_f32 v[6:7], v[20:21], v[82:83], v[28:29] op_sel_hi:[1,0,1]
	v_pk_mul_f32 v[30:31], v[104:105], v[90:91] op_sel:[0,1]
	v_pk_mul_f32 v[32:33], v[104:105], v[92:93] op_sel_hi:[1,0]
	v_pk_mul_f32 v[34:35], v[104:105], v[92:93] op_sel:[0,1]
	v_pk_fma_f32 v[30:31], v[8:9], v[74:75], v[30:31] op_sel:[0,1,0]
	v_pk_fma_f32 v[32:33], v[10:11], v[76:77], v[32:33] op_sel_hi:[1,0,1]
	v_pk_fma_f32 v[34:35], v[12:13], v[76:77], v[34:35] op_sel:[0,1,0]
	v_pk_fma_f32 v[8:9], v[20:21], v[82:83], v[30:31] op_sel:[0,1,0]
	v_pk_fma_f32 v[10:11], v[20:21], v[84:85], v[32:33] op_sel_hi:[1,0,1]
	v_pk_fma_f32 v[12:13], v[20:21], v[84:85], v[34:35] op_sel:[0,1,0]
	v_pk_mul_f32 v[36:37], v[104:105], v[94:95] op_sel_hi:[1,0]
	v_pk_mul_f32 v[38:39], v[104:105], v[94:95] op_sel:[0,1]
	v_pk_mul_f32 v[40:41], v[2:3], v[96:97] op_sel_hi:[1,0]
	v_pk_fma_f32 v[36:37], v[14:15], v[78:79], v[36:37] op_sel_hi:[1,0,1]
	v_pk_fma_f32 v[38:39], v[16:17], v[78:79], v[38:39] op_sel:[0,1,0]
	v_pk_mul_f32 v[44:45], v[10:11], v[100:101] op_sel_hi:[1,0]
	v_pk_fma_f32 v[14:15], v[20:21], v[86:87], v[36:37] op_sel_hi:[1,0,1]
	v_pk_fma_f32 v[16:17], v[20:21], v[86:87], v[38:39] op_sel:[0,1,0]
	v_pk_fma_f32 v[40:41], v[4:5], v[96:97], v[40:41] op_sel:[0,1,0]
	v_pk_fma_f32 v[44:45], v[12:13], v[100:101], v[44:45] op_sel:[0,1,0]
	v_pk_fma_f32 v[40:41], v[6:7], v[98:99], v[40:41] op_sel_hi:[1,0,1]
	v_pk_fma_f32 v[44:45], v[14:15], v[102:103], v[44:45] op_sel_hi:[1,0,1]
	v_pk_fma_f32 v[40:41], v[8:9], v[98:99], v[40:41] op_sel:[0,1,0]
	v_pk_fma_f32 v[44:45], v[16:17], v[102:103], v[44:45] op_sel:[0,1,0]
	v_pk_add_f32 v[40:41], v[40:41], v[44:45]
	s_waitcnt lgkmcnt(0)
; __device__ __forceinline__ void rwkv_block(KP p, int o, int b, int hd, LAS unsigned char* lds, const bf16_t* P, bf16_t* YB) {
;     ...
;             for (int tt = 0; tt < 16; ++tt) {
;                 const int o8 = tt * 64 + c * 8;
;                 const f32x4 ka = *(const LAS f32x4*)(KK + o8), kb = *(const LAS f32x4*)(KK + o8 + 4);
;                 const f32x4 wa = *(const LAS f32x4*)(Wd + o8), wb = *(const LAS f32x4*)(Wd + o8 + 4);
;                 const f32x4 ba = *(const LAS f32x4*)(BB + o8), bb = *(const LAS f32x4*)(BB + o8 + 4);
;                 const f32x4 ma = *(const LAS f32x4*)(KM + o8), mb = *(const LAS f32x4*)(KM + o8 + 4);
;                 const f32x4 ra = *(const LAS f32x4*)(Rr + o8), rb = *(const LAS f32x4*)(Rr + o8 + 4);
;                 const f32x2 v01 = *(const LAS f32x2*)(Vv + tt * 64 + 2 * rp);
;                 const f32x2 k2[4] = {{ka[0], ka[1]}, {ka[2], ka[3]}, {kb[0], kb[1]}, {kb[2], kb[3]}};
;                 const f32x2 w2[4] = {{wa[0], wa[1]}, {wa[2], wa[3]}, {wb[0], wb[1]}, {wb[2], wb[3]}};
;                 const f32x2 b2[4] = {{ba[0], ba[1]}, {ba[2], ba[3]}, {bb[0], bb[1]}, {bb[2], bb[3]}};
;                 const f32x2 m2[4] = {{ma[0], ma[1]}, {ma[2], ma[3]}, {mb[0], mb[1]}, {mb[2], mb[3]}};
;                 const f32x2 r2[4] = {{ra[0], ra[1]}, {ra[2], ra[3]}, {rb[0], rb[1]}, {rb[2], rb[3]}};
;                 f32x2 accA = s[0][0] * k2[0], accB = s[1][0] * k2[0], accA2 = s[0][2] * k2[2], accB2 = s[1][2] * k2[2];
;                 accA = s[0][1] * k2[1] + accA; accB = s[1][1] * k2[1] + accB; accA2 = s[0][3] * k2[3] + accA2; accB2 = s[1][3] * k2[3] + accB2;
;                 accA = accA + accA2; accB = accB + accB2;
;                 float sa0 = accA.x + accA.y, sa1 = accB.x + accB.y;
;                 sa0 += dpp_f<0xB1>(sa0); sa1 += dpp_f<0xB1>(sa1);
;                 sa0 += dpp_f<0x4E>(sa0); sa1 += dpp_f<0x4E>(sa1);
;                 sa0 += dpp_f<0x141>(sa0); sa1 += dpp_f<0x141>(sa1);
;                 const f32x2 saA = {sa0, sa0}, saB = {sa1, sa1}, vA = {v01.x, v01.x}, vB = {v01.y, v01.y};
;                 f32x2 yA, yB;
; #pragma unroll
;                 for (int j = 0; j < 4; ++j) {
;                     f32x2 tA = vA * m2[j], tB = vB * m2[j];
;                     tA = saA * b2[j] + tA; tB = saB * b2[j] + tB;
;                     s[0][j] = s[0][j] * w2[j] + tA; s[1][j] = s[1][j] * w2[j] + tB;
	v_pk_mul_f32 v[20:21], v[2:3], v[110:111] op_sel_hi:[1,0]
	v_pk_mul_f32 v[22:23], v[10:11], v[114:115] op_sel_hi:[1,0]
	ds_read_b128 v[64:67], v180 offset:4608
	v_pk_fma_f32 v[20:21], v[4:5], v[110:111], v[20:21] op_sel:[0,1,0]
	v_pk_fma_f32 v[22:23], v[12:13], v[114:115], v[22:23] op_sel:[0,1,0]
	ds_read_b128 v[68:71], v180 offset:4624
	v_pk_fma_f32 v[20:21], v[6:7], v[112:113], v[20:21] op_sel_hi:[1,0,1]
	v_pk_fma_f32 v[22:23], v[14:15], v[116:117], v[22:23] op_sel_hi:[1,0,1]
	ds_read_b64 v[104:105], v181 offset:20992
	v_pk_fma_f32 v[20:21], v[8:9], v[112:113], v[20:21] op_sel:[0,1,0]
	v_pk_fma_f32 v[22:23], v[16:17], v[116:117], v[22:23] op_sel:[0,1,0]
	ds_read_b128 v[88:91], v180 offset:12800
	ds_read_b128 v[92:95], v180 offset:12816
	v_pk_add_f32 v[20:21], v[20:21], v[22:23]
	ds_read_b128 v[72:75], v180 offset:512
	ds_read_b128 v[76:79], v180 offset:528
	v_add_f32_dpp v20, v20, v20 quad_perm:[1,0,3,2] row_mask:0xf bank_mask:0xf bound_ctrl:1
	v_add_f32_dpp v21, v21, v21 quad_perm:[1,0,3,2] row_mask:0xf bank_mask:0xf bound_ctrl:1
	ds_read_b128 v[80:83], v180 offset:8704
	v_add_f32_dpp v20, v20, v20 quad_perm:[2,3,0,1] row_mask:0xf bank_mask:0xf bound_ctrl:1
	v_add_f32_dpp v21, v21, v21 quad_perm:[2,3,0,1] row_mask:0xf bank_mask:0xf bound_ctrl:1
	ds_read_b128 v[84:87], v180 offset:8720
	v_add_f32_dpp v20, v20, v20 row_half_mirror row_mask:0xf bank_mask:0xf bound_ctrl:1
	v_add_f32_dpp v21, v21, v21 row_half_mirror row_mask:0xf bank_mask:0xf bound_ctrl:1
	ds_read_b128 v[96:99], v180 offset:16896
	ds_read_b128 v[100:103], v180 offset:16912
	v_add_f32_dpp v40, v40, v40 quad_perm:[1,0,3,2] row_mask:0xf bank_mask:0xf bound_ctrl:1
	v_add_f32_dpp v41, v41, v41 quad_perm:[1,0,3,2] row_mask:0xf bank_mask:0xf bound_ctrl:1
	v_pk_mul_f32 v[24:25], v[150:151], v[134:135] op_sel_hi:[1,0]
	v_add_f32_dpp v40, v40, v40 quad_perm:[2,3,0,1] row_mask:0xf bank_mask:0xf bound_ctrl:1
	v_add_f32_dpp v41, v41, v41 quad_perm:[2,3,0,1] row_mask:0xf bank_mask:0xf bound_ctrl:1
	v_pk_fma_f32 v[24:25], v[2:3], v[118:119], v[24:25] op_sel_hi:[1,0,1]
	v_add_f32_dpp v40, v40, v40 row_half_mirror row_mask:0xf bank_mask:0xf bound_ctrl:1
	v_add_f32_dpp v41, v41, v41 row_half_mirror row_mask:0xf bank_mask:0xf bound_ctrl:1
	v_pk_fma_f32 v[2:3], v[20:21], v[126:127], v[24:25] op_sel_hi:[1,0,1]
	v_pk_mul_f32 v[26:27], v[150:151], v[134:135] op_sel:[0,1]
	ds_write_b64 v184, v[40:41] offset:28672
	v_pk_mul_f32 v[28:29], v[150:151], v[136:137] op_sel_hi:[1,0]
	v_pk_fma_f32 v[26:27], v[4:5], v[118:119], v[26:27] op_sel:[0,1,0]
	v_pk_mul_f32 v[30:31], v[150:151], v[136:137] op_sel:[0,1]
	v_pk_fma_f32 v[28:29], v[6:7], v[120:121], v[28:29] op_sel_hi:[1,0,1]
	v_pk_fma_f32 v[4:5], v[20:21], v[126:127], v[26:27] op_sel:[0,1,0]
	v_pk_fma_f32 v[30:31], v[8:9], v[120:121], v[30:31] op_sel:[0,1,0]
	v_pk_fma_f32 v[6:7], v[20:21], v[128:129], v[28:29] op_sel_hi:[1,0,1]
	v_pk_mul_f32 v[32:33], v[150:151], v[138:139] op_sel_hi:[1,0]
	v_pk_fma_f32 v[8:9], v[20:21], v[128:129], v[30:31] op_sel:[0,1,0]
	v_pk_mul_f32 v[34:35], v[150:151], v[138:139] op_sel:[0,1]
	v_pk_fma_f32 v[32:33], v[10:11], v[122:123], v[32:33] op_sel_hi:[1,0,1]
	v_pk_mul_f32 v[36:37], v[150:151], v[140:141] op_sel_hi:[1,0]
	v_pk_fma_f32 v[34:35], v[12:13], v[122:123], v[34:35] op_sel:[0,1,0]
	v_pk_fma_f32 v[10:11], v[20:21], v[130:131], v[32:33] op_sel_hi:[1,0,1]
	v_pk_fma_f32 v[36:37], v[14:15], v[124:125], v[36:37] op_sel_hi:[1,0,1]
	v_pk_fma_f32 v[12:13], v[20:21], v[130:131], v[34:35] op_sel:[0,1,0]
	v_pk_mul_f32 v[38:39], v[150:151], v[140:141] op_sel:[0,1]
	v_pk_fma_f32 v[14:15], v[20:21], v[132:133], v[36:37] op_sel_hi:[1,0,1]
	v_pk_mul_f32 v[42:43], v[2:3], v[142:143] op_sel_hi:[1,0]
	v_pk_fma_f32 v[38:39], v[16:17], v[124:125], v[38:39] op_sel:[0,1,0]
	v_pk_mul_f32 v[44:45], v[10:11], v[146:147] op_sel_hi:[1,0]
	v_pk_fma_f32 v[42:43], v[4:5], v[142:143], v[42:43] op_sel:[0,1,0]
	v_pk_fma_f32 v[16:17], v[20:21], v[132:133], v[38:39] op_sel:[0,1,0]
	v_pk_fma_f32 v[44:45], v[12:13], v[146:147], v[44:45] op_sel:[0,1,0]
	v_pk_fma_f32 v[42:43], v[6:7], v[144:145], v[42:43] op_sel_hi:[1,0,1]
	v_pk_fma_f32 v[44:45], v[14:15], v[148:149], v[44:45] op_sel_hi:[1,0,1]
	v_pk_fma_f32 v[42:43], v[8:9], v[144:145], v[42:43] op_sel:[0,1,0]
	v_pk_fma_f32 v[44:45], v[16:17], v[148:149], v[44:45] op_sel:[0,1,0]
	v_pk_add_f32 v[42:43], v[42:43], v[44:45]
	s_waitcnt lgkmcnt(0)
; __device__ __forceinline__ void rwkv_block(KP p, int o, int b, int hd, LAS unsigned char* lds, const bf16_t* P, bf16_t* YB) {
;     ...
;             for (int tt = 0; tt < 16; ++tt) {
;                 const int o8 = tt * 64 + c * 8;
;                 const f32x4 ka = *(const LAS f32x4*)(KK + o8), kb = *(const LAS f32x4*)(KK + o8 + 4);
;                 const f32x4 wa = *(const LAS f32x4*)(Wd + o8), wb = *(const LAS f32x4*)(Wd + o8 + 4);
;                 const f32x4 ba = *(const LAS f32x4*)(BB + o8), bb = *(const LAS f32x4*)(BB + o8 + 4);
;                 const f32x4 ma = *(const LAS f32x4*)(KM + o8), mb = *(const LAS f32x4*)(KM + o8 + 4);
;                 const f32x4 ra = *(const LAS f32x4*)(Rr + o8), rb = *(const LAS f32x4*)(Rr + o8 + 4);
;                 const f32x2 v01 = *(const LAS f32x2*)(Vv + tt * 64 + 2 * rp);
;                 const f32x2 k2[4] = {{ka[0], ka[1]}, {ka[2], ka[3]}, {kb[0], kb[1]}, {kb[2], kb[3]}};
;                 const f32x2 w2[4] = {{wa[0], wa[1]}, {wa[2], wa[3]}, {wb[0], wb[1]}, {wb[2], wb[3]}};
;                 const f32x2 b2[4] = {{ba[0], ba[1]}, {ba[2], ba[3]}, {bb[0], bb[1]}, {bb[2], bb[3]}};
;                 const f32x2 m2[4] = {{ma[0], ma[1]}, {ma[2], ma[3]}, {mb[0], mb[1]}, {mb[2], mb[3]}};
;                 const f32x2 r2[4] = {{ra[0], ra[1]}, {ra[2], ra[3]}, {rb[0], rb[1]}, {rb[2], rb[3]}};
;                 f32x2 accA = s[0][0] * k2[0], accB = s[1][0] * k2[0], accA2 = s[0][2] * k2[2], accB2 = s[1][2] * k2[2];
;                 accA = s[0][1] * k2[1] + accA; accB = s[1][1] * k2[1] + accB; accA2 = s[0][3] * k2[3] + accA2; accB2 = s[1][3] * k2[3] + accB2;
;                 accA = accA + accA2; accB = accB + accB2;
;                 float sa0 = accA.x + accA.y, sa1 = accB.x + accB.y;
;                 sa0 += dpp_f<0xB1>(sa0); sa1 += dpp_f<0xB1>(sa1);
;                 sa0 += dpp_f<0x4E>(sa0); sa1 += dpp_f<0x4E>(sa1);
;                 sa0 += dpp_f<0x141>(sa0); sa1 += dpp_f<0x141>(sa1);
;                 const f32x2 saA = {sa0, sa0}, saB = {sa1, sa1}, vA = {v01.x, v01.x}, vB = {v01.y, v01.y};
;                 f32x2 yA, yB;
; #pragma unroll
;                 for (int j = 0; j < 4; ++j) {
;                     f32x2 tA = vA * m2[j], tB = vB * m2[j];
;                     tA = saA * b2[j] + tA; tB = saB * b2[j] + tB;
;                     s[0][j] = s[0][j] * w2[j] + tA; s[1][j] = s[1][j] * w2[j] + tB;
	v_pk_mul_f32 v[20:21], v[2:3], v[64:65] op_sel_hi:[1,0]
	v_pk_mul_f32 v[22:23], v[10:11], v[68:69] op_sel_hi:[1,0]
	ds_read_b128 v[110:113], v180 offset:4864
	v_pk_fma_f32 v[20:21], v[4:5], v[64:65], v[20:21] op_sel:[0,1,0]
	v_pk_fma_f32 v[22:23], v[12:13], v[68:69], v[22:23] op_sel:[0,1,0]
	ds_read_b128 v[114:117], v180 offset:4880
	v_pk_fma_f32 v[20:21], v[6:7], v[66:67], v[20:21] op_sel_hi:[1,0,1]
	v_pk_fma_f32 v[22:23], v[14:15], v[70:71], v[22:23] op_sel_hi:[1,0,1]
	ds_read_b64 v[150:151], v181 offset:21248
	v_pk_fma_f32 v[20:21], v[8:9], v[66:67], v[20:21] op_sel:[0,1,0]
	v_pk_fma_f32 v[22:23], v[16:17], v[70:71], v[22:23] op_sel:[0,1,0]
	ds_read_b128 v[134:137], v180 offset:13056
	ds_read_b128 v[138:141], v180 offset:13072
	v_pk_add_f32 v[20:21], v[20:21], v[22:23]
	ds_read_b128 v[118:121], v180 offset:768
	ds_read_b128 v[122:125], v180 offset:784
	v_add_f32_dpp v20, v20, v20 quad_perm:[1,0,3,2] row_mask:0xf bank_mask:0xf bound_ctrl:1
	v_add_f32_dpp v21, v21, v21 quad_perm:[1,0,3,2] row_mask:0xf bank_mask:0xf bound_ctrl:1
	ds_read_b128 v[126:129], v180 offset:8960
	v_add_f32_dpp v20, v20, v20 quad_perm:[2,3,0,1] row_mask:0xf bank_mask:0xf bound_ctrl:1
	v_add_f32_dpp v21, v21, v21 quad_perm:[2,3,0,1] row_mask:0xf bank_mask:0xf bound_ctrl:1
	ds_read_b128 v[130:133], v180 offset:8976
	v_add_f32_dpp v20, v20, v20 row_half_mirror row_mask:0xf bank_mask:0xf bound_ctrl:1
	v_add_f32_dpp v21, v21, v21 row_half_mirror row_mask:0xf bank_mask:0xf bound_ctrl:1
	ds_read_b128 v[142:145], v180 offset:17152
	ds_read_b128 v[146:149], v180 offset:17168
	v_add_f32_dpp v42, v42, v42 quad_perm:[1,0,3,2] row_mask:0xf bank_mask:0xf bound_ctrl:1
	v_add_f32_dpp v43, v43, v43 quad_perm:[1,0,3,2] row_mask:0xf bank_mask:0xf bound_ctrl:1
	v_pk_mul_f32 v[24:25], v[104:105], v[88:89] op_sel_hi:[1,0]
	v_add_f32_dpp v42, v42, v42 quad_perm:[2,3,0,1] row_mask:0xf bank_mask:0xf bound_ctrl:1
	v_add_f32_dpp v43, v43, v43 quad_perm:[2,3,0,1] row_mask:0xf bank_mask:0xf bound_ctrl:1
	v_pk_fma_f32 v[24:25], v[2:3], v[72:73], v[24:25] op_sel_hi:[1,0,1]
	v_add_f32_dpp v42, v42, v42 row_half_mirror row_mask:0xf bank_mask:0xf bound_ctrl:1
	v_add_f32_dpp v43, v43, v43 row_half_mirror row_mask:0xf bank_mask:0xf bound_ctrl:1
	v_pk_fma_f32 v[2:3], v[20:21], v[80:81], v[24:25] op_sel_hi:[1,0,1]
	v_pk_mul_f32 v[26:27], v[104:105], v[88:89] op_sel:[0,1]
	ds_write_b64 v184, v[42:43] offset:28928
	v_pk_mul_f32 v[28:29], v[104:105], v[90:91] op_sel_hi:[1,0]
	v_pk_fma_f32 v[26:27], v[4:5], v[72:73], v[26:27] op_sel:[0,1,0]
	v_pk_mul_f32 v[30:31], v[104:105], v[90:91] op_sel:[0,1]
	v_pk_fma_f32 v[28:29], v[6:7], v[74:75], v[28:29] op_sel_hi:[1,0,1]
	v_pk_fma_f32 v[4:5], v[20:21], v[80:81], v[26:27] op_sel:[0,1,0]
	v_pk_fma_f32 v[30:31], v[8:9], v[74:75], v[30:31] op_sel:[0,1,0]
	v_pk_fma_f32 v[6:7], v[20:21], v[82:83], v[28:29] op_sel_hi:[1,0,1]
	v_pk_mul_f32 v[32:33], v[104:105], v[92:93] op_sel_hi:[1,0]
	v_pk_fma_f32 v[8:9], v[20:21], v[82:83], v[30:31] op_sel:[0,1,0]
	v_pk_mul_f32 v[34:35], v[104:105], v[92:93] op_sel:[0,1]
	v_pk_fma_f32 v[32:33], v[10:11], v[76:77], v[32:33] op_sel_hi:[1,0,1]
	v_pk_mul_f32 v[36:37], v[104:105], v[94:95] op_sel_hi:[1,0]
	v_pk_fma_f32 v[34:35], v[12:13], v[76:77], v[34:35] op_sel:[0,1,0]
	v_pk_fma_f32 v[10:11], v[20:21], v[84:85], v[32:33] op_sel_hi:[1,0,1]
	v_pk_fma_f32 v[36:37], v[14:15], v[78:79], v[36:37] op_sel_hi:[1,0,1]
	v_pk_fma_f32 v[12:13], v[20:21], v[84:85], v[34:35] op_sel:[0,1,0]
	v_pk_mul_f32 v[38:39], v[104:105], v[94:95] op_sel:[0,1]
	v_pk_fma_f32 v[14:15], v[20:21], v[86:87], v[36:37] op_sel_hi:[1,0,1]
	v_pk_mul_f32 v[40:41], v[2:3], v[96:97] op_sel_hi:[1,0]
	v_pk_fma_f32 v[38:39], v[16:17], v[78:79], v[38:39] op_sel:[0,1,0]
	v_pk_mul_f32 v[44:45], v[10:11], v[100:101] op_sel_hi:[1,0]
	v_pk_fma_f32 v[40:41], v[4:5], v[96:97], v[40:41] op_sel:[0,1,0]
	v_pk_fma_f32 v[16:17], v[20:21], v[86:87], v[38:39] op_sel:[0,1,0]
	v_pk_fma_f32 v[44:45], v[12:13], v[100:101], v[44:45] op_sel:[0,1,0]
	v_pk_fma_f32 v[40:41], v[6:7], v[98:99], v[40:41] op_sel_hi:[1,0,1]
	v_pk_fma_f32 v[44:45], v[14:15], v[102:103], v[44:45] op_sel_hi:[1,0,1]
	v_pk_fma_f32 v[40:41], v[8:9], v[98:99], v[40:41] op_sel:[0,1,0]
	v_pk_fma_f32 v[44:45], v[16:17], v[102:103], v[44:45] op_sel:[0,1,0]
	v_pk_add_f32 v[40:41], v[40:41], v[44:45]
	s_waitcnt lgkmcnt(0)
; __device__ __forceinline__ void rwkv_block(KP p, int o, int b, int hd, LAS unsigned char* lds, const bf16_t* P, bf16_t* YB) {
;     ...
;             for (int tt = 0; tt < 16; ++tt) {
;                 const int o8 = tt * 64 + c * 8;
;                 const f32x4 ka = *(const LAS f32x4*)(KK + o8), kb = *(const LAS f32x4*)(KK + o8 + 4);
;                 const f32x4 wa = *(const LAS f32x4*)(Wd + o8), wb = *(const LAS f32x4*)(Wd + o8 + 4);
;                 const f32x4 ba = *(const LAS f32x4*)(BB + o8), bb = *(const LAS f32x4*)(BB + o8 + 4);
;                 const f32x4 ma = *(const LAS f32x4*)(KM + o8), mb = *(const LAS f32x4*)(KM + o8 + 4);
;                 const f32x4 ra = *(const LAS f32x4*)(Rr + o8), rb = *(const LAS f32x4*)(Rr + o8 + 4);
;                 const f32x2 v01 = *(const LAS f32x2*)(Vv + tt * 64 + 2 * rp);
;                 const f32x2 k2[4] = {{ka[0], ka[1]}, {ka[2], ka[3]}, {kb[0], kb[1]}, {kb[2], kb[3]}};
;                 const f32x2 w2[4] = {{wa[0], wa[1]}, {wa[2], wa[3]}, {wb[0], wb[1]}, {wb[2], wb[3]}};
;                 const f32x2 b2[4] = {{ba[0], ba[1]}, {ba[2], ba[3]}, {bb[0], bb[1]}, {bb[2], bb[3]}};
;                 const f32x2 m2[4] = {{ma[0], ma[1]}, {ma[2], ma[3]}, {mb[0], mb[1]}, {mb[2], mb[3]}};
;                 const f32x2 r2[4] = {{ra[0], ra[1]}, {ra[2], ra[3]}, {rb[0], rb[1]}, {rb[2], rb[3]}};
;                 f32x2 accA = s[0][0] * k2[0], accB = s[1][0] * k2[0], accA2 = s[0][2] * k2[2], accB2 = s[1][2] * k2[2];
;                 accA = s[0][1] * k2[1] + accA; accB = s[1][1] * k2[1] + accB; accA2 = s[0][3] * k2[3] + accA2; accB2 = s[1][3] * k2[3] + accB2;
;                 accA = accA + accA2; accB = accB + accB2;
;                 float sa0 = accA.x + accA.y, sa1 = accB.x + accB.y;
;                 sa0 += dpp_f<0xB1>(sa0); sa1 += dpp_f<0xB1>(sa1);
;                 sa0 += dpp_f<0x4E>(sa0); sa1 += dpp_f<0x4E>(sa1);
;                 sa0 += dpp_f<0x141>(sa0); sa1 += dpp_f<0x141>(sa1);
;                 const f32x2 saA = {sa0, sa0}, saB = {sa1, sa1}, vA = {v01.x, v01.x}, vB = {v01.y, v01.y};
;                 f32x2 yA, yB;
; #pragma unroll
;                 for (int j = 0; j < 4; ++j) {
;                     f32x2 tA = vA * m2[j], tB = vB * m2[j];
;                     tA = saA * b2[j] + tA; tB = saB * b2[j] + tB;
;                     s[0][j] = s[0][j] * w2[j] + tA; s[1][j] = s[1][j] * w2[j] + tB;
	v_pk_mul_f32 v[20:21], v[2:3], v[110:111] op_sel_hi:[1,0]
	v_pk_mul_f32 v[22:23], v[10:11], v[114:115] op_sel_hi:[1,0]
	ds_read_b128 v[64:67], v180 offset:5120
	v_pk_fma_f32 v[20:21], v[4:5], v[110:111], v[20:21] op_sel:[0,1,0]
	v_pk_fma_f32 v[22:23], v[12:13], v[114:115], v[22:23] op_sel:[0,1,0]
	ds_read_b128 v[68:71], v180 offset:5136
	v_pk_fma_f32 v[20:21], v[6:7], v[112:113], v[20:21] op_sel_hi:[1,0,1]
	v_pk_fma_f32 v[22:23], v[14:15], v[116:117], v[22:23] op_sel_hi:[1,0,1]
	ds_read_b64 v[104:105], v181 offset:21504
	v_pk_fma_f32 v[20:21], v[8:9], v[112:113], v[20:21] op_sel:[0,1,0]
	v_pk_fma_f32 v[22:23], v[16:17], v[116:117], v[22:23] op_sel:[0,1,0]
	ds_read_b128 v[88:91], v180 offset:13312
	ds_read_b128 v[92:95], v180 offset:13328
	v_pk_add_f32 v[20:21], v[20:21], v[22:23]
	ds_read_b128 v[72:75], v180 offset:1024
	ds_read_b128 v[76:79], v180 offset:1040
	v_add_f32_dpp v20, v20, v20 quad_perm:[1,0,3,2] row_mask:0xf bank_mask:0xf bound_ctrl:1
	v_add_f32_dpp v21, v21, v21 quad_perm:[1,0,3,2] row_mask:0xf bank_mask:0xf bound_ctrl:1
	ds_read_b128 v[80:83], v180 offset:9216
	v_add_f32_dpp v20, v20, v20 quad_perm:[2,3,0,1] row_mask:0xf bank_mask:0xf bound_ctrl:1
	v_add_f32_dpp v21, v21, v21 quad_perm:[2,3,0,1] row_mask:0xf bank_mask:0xf bound_ctrl:1
	ds_read_b128 v[84:87], v180 offset:9232
	v_add_f32_dpp v20, v20, v20 row_half_mirror row_mask:0xf bank_mask:0xf bound_ctrl:1
	v_add_f32_dpp v21, v21, v21 row_half_mirror row_mask:0xf bank_mask:0xf bound_ctrl:1
	ds_read_b128 v[96:99], v180 offset:17408
	ds_read_b128 v[100:103], v180 offset:17424
	v_add_f32_dpp v40, v40, v40 quad_perm:[1,0,3,2] row_mask:0xf bank_mask:0xf bound_ctrl:1
	v_add_f32_dpp v41, v41, v41 quad_perm:[1,0,3,2] row_mask:0xf bank_mask:0xf bound_ctrl:1
	v_pk_mul_f32 v[24:25], v[150:151], v[134:135] op_sel_hi:[1,0]
	v_add_f32_dpp v40, v40, v40 quad_perm:[2,3,0,1] row_mask:0xf bank_mask:0xf bound_ctrl:1
	v_add_f32_dpp v41, v41, v41 quad_perm:[2,3,0,1] row_mask:0xf bank_mask:0xf bound_ctrl:1
	v_pk_fma_f32 v[24:25], v[2:3], v[118:119], v[24:25] op_sel_hi:[1,0,1]
	v_add_f32_dpp v40, v40, v40 row_half_mirror row_mask:0xf bank_mask:0xf bound_ctrl:1
	v_add_f32_dpp v41, v41, v41 row_half_mirror row_mask:0xf bank_mask:0xf bound_ctrl:1
	v_pk_fma_f32 v[2:3], v[20:21], v[126:127], v[24:25] op_sel_hi:[1,0,1]
	v_pk_mul_f32 v[26:27], v[150:151], v[134:135] op_sel:[0,1]
	ds_write_b64 v184, v[40:41] offset:29184
	v_pk_mul_f32 v[28:29], v[150:151], v[136:137] op_sel_hi:[1,0]
	v_pk_fma_f32 v[26:27], v[4:5], v[118:119], v[26:27] op_sel:[0,1,0]
	v_pk_mul_f32 v[30:31], v[150:151], v[136:137] op_sel:[0,1]
	v_pk_fma_f32 v[28:29], v[6:7], v[120:121], v[28:29] op_sel_hi:[1,0,1]
	v_pk_fma_f32 v[4:5], v[20:21], v[126:127], v[26:27] op_sel:[0,1,0]
	v_pk_fma_f32 v[30:31], v[8:9], v[120:121], v[30:31] op_sel:[0,1,0]
	v_pk_fma_f32 v[6:7], v[20:21], v[128:129], v[28:29] op_sel_hi:[1,0,1]
	v_pk_mul_f32 v[32:33], v[150:151], v[138:139] op_sel_hi:[1,0]
	v_pk_fma_f32 v[8:9], v[20:21], v[128:129], v[30:31] op_sel:[0,1,0]
	v_pk_mul_f32 v[34:35], v[150:151], v[138:139] op_sel:[0,1]
	v_pk_fma_f32 v[32:33], v[10:11], v[122:123], v[32:33] op_sel_hi:[1,0,1]
	v_pk_mul_f32 v[36:37], v[150:151], v[140:141] op_sel_hi:[1,0]
	v_pk_fma_f32 v[34:35], v[12:13], v[122:123], v[34:35] op_sel:[0,1,0]
	v_pk_fma_f32 v[10:11], v[20:21], v[130:131], v[32:33] op_sel_hi:[1,0,1]
	v_pk_fma_f32 v[36:37], v[14:15], v[124:125], v[36:37] op_sel_hi:[1,0,1]
	v_pk_fma_f32 v[12:13], v[20:21], v[130:131], v[34:35] op_sel:[0,1,0]
	v_pk_mul_f32 v[38:39], v[150:151], v[140:141] op_sel:[0,1]
	v_pk_fma_f32 v[14:15], v[20:21], v[132:133], v[36:37] op_sel_hi:[1,0,1]
	v_pk_mul_f32 v[42:43], v[2:3], v[142:143] op_sel_hi:[1,0]
	v_pk_fma_f32 v[38:39], v[16:17], v[124:125], v[38:39] op_sel:[0,1,0]
	v_pk_mul_f32 v[44:45], v[10:11], v[146:147] op_sel_hi:[1,0]
	v_pk_fma_f32 v[42:43], v[4:5], v[142:143], v[42:43] op_sel:[0,1,0]
	v_pk_fma_f32 v[16:17], v[20:21], v[132:133], v[38:39] op_sel:[0,1,0]
	v_pk_fma_f32 v[44:45], v[12:13], v[146:147], v[44:45] op_sel:[0,1,0]
	v_pk_fma_f32 v[42:43], v[6:7], v[144:145], v[42:43] op_sel_hi:[1,0,1]
	v_pk_fma_f32 v[44:45], v[14:15], v[148:149], v[44:45] op_sel_hi:[1,0,1]
	v_pk_fma_f32 v[42:43], v[8:9], v[144:145], v[42:43] op_sel:[0,1,0]
	v_pk_fma_f32 v[44:45], v[16:17], v[148:149], v[44:45] op_sel:[0,1,0]
	v_pk_add_f32 v[42:43], v[42:43], v[44:45]
	s_waitcnt lgkmcnt(0)
; __device__ __forceinline__ void rwkv_block(KP p, int o, int b, int hd, LAS unsigned char* lds, const bf16_t* P, bf16_t* YB) {
;     ...
;             for (int tt = 0; tt < 16; ++tt) {
;                 const int o8 = tt * 64 + c * 8;
;                 const f32x4 ka = *(const LAS f32x4*)(KK + o8), kb = *(const LAS f32x4*)(KK + o8 + 4);
;                 const f32x4 wa = *(const LAS f32x4*)(Wd + o8), wb = *(const LAS f32x4*)(Wd + o8 + 4);
;                 const f32x4 ba = *(const LAS f32x4*)(BB + o8), bb = *(const LAS f32x4*)(BB + o8 + 4);
;                 const f32x4 ma = *(const LAS f32x4*)(KM + o8), mb = *(const LAS f32x4*)(KM + o8 + 4);
;                 const f32x4 ra = *(const LAS f32x4*)(Rr + o8), rb = *(const LAS f32x4*)(Rr + o8 + 4);
;                 const f32x2 v01 = *(const LAS f32x2*)(Vv + tt * 64 + 2 * rp);
;                 const f32x2 k2[4] = {{ka[0], ka[1]}, {ka[2], ka[3]}, {kb[0], kb[1]}, {kb[2], kb[3]}};
;                 const f32x2 w2[4] = {{wa[0], wa[1]}, {wa[2], wa[3]}, {wb[0], wb[1]}, {wb[2], wb[3]}};
;                 const f32x2 b2[4] = {{ba[0], ba[1]}, {ba[2], ba[3]}, {bb[0], bb[1]}, {bb[2], bb[3]}};
;                 const f32x2 m2[4] = {{ma[0], ma[1]}, {ma[2], ma[3]}, {mb[0], mb[1]}, {mb[2], mb[3]}};
;                 const f32x2 r2[4] = {{ra[0], ra[1]}, {ra[2], ra[3]}, {rb[0], rb[1]}, {rb[2], rb[3]}};
;                 f32x2 accA = s[0][0] * k2[0], accB = s[1][0] * k2[0], accA2 = s[0][2] * k2[2], accB2 = s[1][2] * k2[2];
;                 accA = s[0][1] * k2[1] + accA; accB = s[1][1] * k2[1] + accB; accA2 = s[0][3] * k2[3] + accA2; accB2 = s[1][3] * k2[3] + accB2;
;                 accA = accA + accA2; accB = accB + accB2;
;                 float sa0 = accA.x + accA.y, sa1 = accB.x + accB.y;
;                 sa0 += dpp_f<0xB1>(sa0); sa1 += dpp_f<0xB1>(sa1);
;                 sa0 += dpp_f<0x4E>(sa0); sa1 += dpp_f<0x4E>(sa1);
;                 sa0 += dpp_f<0x141>(sa0); sa1 += dpp_f<0x141>(sa1);
;                 const f32x2 saA = {sa0, sa0}, saB = {sa1, sa1}, vA = {v01.x, v01.x}, vB = {v01.y, v01.y};
;                 f32x2 yA, yB;
; #pragma unroll
;                 for (int j = 0; j < 4; ++j) {
;                     f32x2 tA = vA * m2[j], tB = vB * m2[j];
;                     tA = saA * b2[j] + tA; tB = saB * b2[j] + tB;
;                     s[0][j] = s[0][j] * w2[j] + tA; s[1][j] = s[1][j] * w2[j] + tB;
	v_pk_mul_f32 v[20:21], v[2:3], v[64:65] op_sel_hi:[1,0]
	v_pk_mul_f32 v[22:23], v[10:11], v[68:69] op_sel_hi:[1,0]
	ds_read_b128 v[110:113], v180 offset:5376
	v_pk_fma_f32 v[20:21], v[4:5], v[64:65], v[20:21] op_sel:[0,1,0]
	v_pk_fma_f32 v[22:23], v[12:13], v[68:69], v[22:23] op_sel:[0,1,0]
	ds_read_b128 v[114:117], v180 offset:5392
	v_pk_fma_f32 v[20:21], v[6:7], v[66:67], v[20:21] op_sel_hi:[1,0,1]
	v_pk_fma_f32 v[22:23], v[14:15], v[70:71], v[22:23] op_sel_hi:[1,0,1]
	ds_read_b64 v[150:151], v181 offset:21760
	v_pk_fma_f32 v[20:21], v[8:9], v[66:67], v[20:21] op_sel:[0,1,0]
	v_pk_fma_f32 v[22:23], v[16:17], v[70:71], v[22:23] op_sel:[0,1,0]
	ds_read_b128 v[134:137], v180 offset:13568
	ds_read_b128 v[138:141], v180 offset:13584
	v_pk_add_f32 v[20:21], v[20:21], v[22:23]
	ds_read_b128 v[118:121], v180 offset:1280
	ds_read_b128 v[122:125], v180 offset:1296
	v_add_f32_dpp v20, v20, v20 quad_perm:[1,0,3,2] row_mask:0xf bank_mask:0xf bound_ctrl:1
	v_add_f32_dpp v21, v21, v21 quad_perm:[1,0,3,2] row_mask:0xf bank_mask:0xf bound_ctrl:1
	ds_read_b128 v[126:129], v180 offset:9472
	v_add_f32_dpp v20, v20, v20 quad_perm:[2,3,0,1] row_mask:0xf bank_mask:0xf bound_ctrl:1
	v_add_f32_dpp v21, v21, v21 quad_perm:[2,3,0,1] row_mask:0xf bank_mask:0xf bound_ctrl:1
	ds_read_b128 v[130:133], v180 offset:9488
	v_add_f32_dpp v20, v20, v20 row_half_mirror row_mask:0xf bank_mask:0xf bound_ctrl:1
	v_add_f32_dpp v21, v21, v21 row_half_mirror row_mask:0xf bank_mask:0xf bound_ctrl:1
	ds_read_b128 v[142:145], v180 offset:17664
	ds_read_b128 v[146:149], v180 offset:17680
	v_add_f32_dpp v42, v42, v42 quad_perm:[1,0,3,2] row_mask:0xf bank_mask:0xf bound_ctrl:1
	v_add_f32_dpp v43, v43, v43 quad_perm:[1,0,3,2] row_mask:0xf bank_mask:0xf bound_ctrl:1
	v_pk_mul_f32 v[24:25], v[104:105], v[88:89] op_sel_hi:[1,0]
	v_add_f32_dpp v42, v42, v42 quad_perm:[2,3,0,1] row_mask:0xf bank_mask:0xf bound_ctrl:1
	v_add_f32_dpp v43, v43, v43 quad_perm:[2,3,0,1] row_mask:0xf bank_mask:0xf bound_ctrl:1
	v_pk_fma_f32 v[24:25], v[2:3], v[72:73], v[24:25] op_sel_hi:[1,0,1]
	v_add_f32_dpp v42, v42, v42 row_half_mirror row_mask:0xf bank_mask:0xf bound_ctrl:1
	v_add_f32_dpp v43, v43, v43 row_half_mirror row_mask:0xf bank_mask:0xf bound_ctrl:1
	v_pk_fma_f32 v[2:3], v[20:21], v[80:81], v[24:25] op_sel_hi:[1,0,1]
	v_pk_mul_f32 v[26:27], v[104:105], v[88:89] op_sel:[0,1]
	ds_write_b64 v184, v[42:43] offset:29440
	v_pk_mul_f32 v[28:29], v[104:105], v[90:91] op_sel_hi:[1,0]
	v_pk_fma_f32 v[26:27], v[4:5], v[72:73], v[26:27] op_sel:[0,1,0]
	v_pk_mul_f32 v[30:31], v[104:105], v[90:91] op_sel:[0,1]
	v_pk_fma_f32 v[28:29], v[6:7], v[74:75], v[28:29] op_sel_hi:[1,0,1]
	v_pk_fma_f32 v[4:5], v[20:21], v[80:81], v[26:27] op_sel:[0,1,0]
	v_pk_fma_f32 v[30:31], v[8:9], v[74:75], v[30:31] op_sel:[0,1,0]
	v_pk_fma_f32 v[6:7], v[20:21], v[82:83], v[28:29] op_sel_hi:[1,0,1]
	v_pk_mul_f32 v[32:33], v[104:105], v[92:93] op_sel_hi:[1,0]
	v_pk_fma_f32 v[8:9], v[20:21], v[82:83], v[30:31] op_sel:[0,1,0]
	v_pk_mul_f32 v[34:35], v[104:105], v[92:93] op_sel:[0,1]
	v_pk_fma_f32 v[32:33], v[10:11], v[76:77], v[32:33] op_sel_hi:[1,0,1]
	v_pk_mul_f32 v[36:37], v[104:105], v[94:95] op_sel_hi:[1,0]
	v_pk_fma_f32 v[34:35], v[12:13], v[76:77], v[34:35] op_sel:[0,1,0]
	v_pk_fma_f32 v[10:11], v[20:21], v[84:85], v[32:33] op_sel_hi:[1,0,1]
	v_pk_fma_f32 v[36:37], v[14:15], v[78:79], v[36:37] op_sel_hi:[1,0,1]
	v_pk_fma_f32 v[12:13], v[20:21], v[84:85], v[34:35] op_sel:[0,1,0]
	v_pk_mul_f32 v[38:39], v[104:105], v[94:95] op_sel:[0,1]
	v_pk_fma_f32 v[14:15], v[20:21], v[86:87], v[36:37] op_sel_hi:[1,0,1]
	v_pk_mul_f32 v[40:41], v[2:3], v[96:97] op_sel_hi:[1,0]
	v_pk_fma_f32 v[38:39], v[16:17], v[78:79], v[38:39] op_sel:[0,1,0]
	v_pk_mul_f32 v[44:45], v[10:11], v[100:101] op_sel_hi:[1,0]
	v_pk_fma_f32 v[40:41], v[4:5], v[96:97], v[40:41] op_sel:[0,1,0]
	v_pk_fma_f32 v[16:17], v[20:21], v[86:87], v[38:39] op_sel:[0,1,0]
	v_pk_fma_f32 v[44:45], v[12:13], v[100:101], v[44:45] op_sel:[0,1,0]
	v_pk_fma_f32 v[40:41], v[6:7], v[98:99], v[40:41] op_sel_hi:[1,0,1]
	v_pk_fma_f32 v[44:45], v[14:15], v[102:103], v[44:45] op_sel_hi:[1,0,1]
	v_pk_fma_f32 v[40:41], v[8:9], v[98:99], v[40:41] op_sel:[0,1,0]
	v_pk_fma_f32 v[44:45], v[16:17], v[102:103], v[44:45] op_sel:[0,1,0]
	v_pk_add_f32 v[40:41], v[40:41], v[44:45]
	s_waitcnt lgkmcnt(0)
; __device__ __forceinline__ void rwkv_block(KP p, int o, int b, int hd, LAS unsigned char* lds, const bf16_t* P, bf16_t* YB) {
;     ...
;             for (int tt = 0; tt < 16; ++tt) {
;                 const int o8 = tt * 64 + c * 8;
;                 const f32x4 ka = *(const LAS f32x4*)(KK + o8), kb = *(const LAS f32x4*)(KK + o8 + 4);
;                 const f32x4 wa = *(const LAS f32x4*)(Wd + o8), wb = *(const LAS f32x4*)(Wd + o8 + 4);
;                 const f32x4 ba = *(const LAS f32x4*)(BB + o8), bb = *(const LAS f32x4*)(BB + o8 + 4);
;                 const f32x4 ma = *(const LAS f32x4*)(KM + o8), mb = *(const LAS f32x4*)(KM + o8 + 4);
;                 const f32x4 ra = *(const LAS f32x4*)(Rr + o8), rb = *(const LAS f32x4*)(Rr + o8 + 4);
;                 const f32x2 v01 = *(const LAS f32x2*)(Vv + tt * 64 + 2 * rp);
;                 const f32x2 k2[4] = {{ka[0], ka[1]}, {ka[2], ka[3]}, {kb[0], kb[1]}, {kb[2], kb[3]}};
;                 const f32x2 w2[4] = {{wa[0], wa[1]}, {wa[2], wa[3]}, {wb[0], wb[1]}, {wb[2], wb[3]}};
;                 const f32x2 b2[4] = {{ba[0], ba[1]}, {ba[2], ba[3]}, {bb[0], bb[1]}, {bb[2], bb[3]}};
;                 const f32x2 m2[4] = {{ma[0], ma[1]}, {ma[2], ma[3]}, {mb[0], mb[1]}, {mb[2], mb[3]}};
;                 const f32x2 r2[4] = {{ra[0], ra[1]}, {ra[2], ra[3]}, {rb[0], rb[1]}, {rb[2], rb[3]}};
;                 f32x2 accA = s[0][0] * k2[0], accB = s[1][0] * k2[0], accA2 = s[0][2] * k2[2], accB2 = s[1][2] * k2[2];
;                 accA = s[0][1] * k2[1] + accA; accB = s[1][1] * k2[1] + accB; accA2 = s[0][3] * k2[3] + accA2; accB2 = s[1][3] * k2[3] + accB2;
;                 accA = accA + accA2; accB = accB + accB2;
;                 float sa0 = accA.x + accA.y, sa1 = accB.x + accB.y;
;                 sa0 += dpp_f<0xB1>(sa0); sa1 += dpp_f<0xB1>(sa1);
;                 sa0 += dpp_f<0x4E>(sa0); sa1 += dpp_f<0x4E>(sa1);
;                 sa0 += dpp_f<0x141>(sa0); sa1 += dpp_f<0x141>(sa1);
;                 const f32x2 saA = {sa0, sa0}, saB = {sa1, sa1}, vA = {v01.x, v01.x}, vB = {v01.y, v01.y};
;                 f32x2 yA, yB;
; #pragma unroll
;                 for (int j = 0; j < 4; ++j) {
;                     f32x2 tA = vA * m2[j], tB = vB * m2[j];
;                     tA = saA * b2[j] + tA; tB = saB * b2[j] + tB;
;                     s[0][j] = s[0][j] * w2[j] + tA; s[1][j] = s[1][j] * w2[j] + tB;
	v_pk_mul_f32 v[20:21], v[2:3], v[110:111] op_sel_hi:[1,0]
	v_pk_mul_f32 v[22:23], v[10:11], v[114:115] op_sel_hi:[1,0]
	ds_read_b128 v[64:67], v180 offset:5632
	v_pk_fma_f32 v[20:21], v[4:5], v[110:111], v[20:21] op_sel:[0,1,0]
	v_pk_fma_f32 v[22:23], v[12:13], v[114:115], v[22:23] op_sel:[0,1,0]
	ds_read_b128 v[68:71], v180 offset:5648
	v_pk_fma_f32 v[20:21], v[6:7], v[112:113], v[20:21] op_sel_hi:[1,0,1]
	v_pk_fma_f32 v[22:23], v[14:15], v[116:117], v[22:23] op_sel_hi:[1,0,1]
	ds_read_b64 v[104:105], v181 offset:22016
	v_pk_fma_f32 v[20:21], v[8:9], v[112:113], v[20:21] op_sel:[0,1,0]
	v_pk_fma_f32 v[22:23], v[16:17], v[116:117], v[22:23] op_sel:[0,1,0]
	ds_read_b128 v[88:91], v180 offset:13824
	ds_read_b128 v[92:95], v180 offset:13840
	v_pk_add_f32 v[20:21], v[20:21], v[22:23]
	ds_read_b128 v[72:75], v180 offset:1536
	ds_read_b128 v[76:79], v180 offset:1552
	v_add_f32_dpp v20, v20, v20 quad_perm:[1,0,3,2] row_mask:0xf bank_mask:0xf bound_ctrl:1
	v_add_f32_dpp v21, v21, v21 quad_perm:[1,0,3,2] row_mask:0xf bank_mask:0xf bound_ctrl:1
	ds_read_b128 v[80:83], v180 offset:9728
	v_add_f32_dpp v20, v20, v20 quad_perm:[2,3,0,1] row_mask:0xf bank_mask:0xf bound_ctrl:1
	v_add_f32_dpp v21, v21, v21 quad_perm:[2,3,0,1] row_mask:0xf bank_mask:0xf bound_ctrl:1
	ds_read_b128 v[84:87], v180 offset:9744
	v_add_f32_dpp v20, v20, v20 row_half_mirror row_mask:0xf bank_mask:0xf bound_ctrl:1
	v_add_f32_dpp v21, v21, v21 row_half_mirror row_mask:0xf bank_mask:0xf bound_ctrl:1
	ds_read_b128 v[96:99], v180 offset:17920
	ds_read_b128 v[100:103], v180 offset:17936
	v_add_f32_dpp v40, v40, v40 quad_perm:[1,0,3,2] row_mask:0xf bank_mask:0xf bound_ctrl:1
	v_add_f32_dpp v41, v41, v41 quad_perm:[1,0,3,2] row_mask:0xf bank_mask:0xf bound_ctrl:1
	v_pk_mul_f32 v[24:25], v[150:151], v[134:135] op_sel_hi:[1,0]
	v_add_f32_dpp v40, v40, v40 quad_perm:[2,3,0,1] row_mask:0xf bank_mask:0xf bound_ctrl:1
	v_add_f32_dpp v41, v41, v41 quad_perm:[2,3,0,1] row_mask:0xf bank_mask:0xf bound_ctrl:1
	v_pk_fma_f32 v[24:25], v[2:3], v[118:119], v[24:25] op_sel_hi:[1,0,1]
	v_add_f32_dpp v40, v40, v40 row_half_mirror row_mask:0xf bank_mask:0xf bound_ctrl:1
	v_add_f32_dpp v41, v41, v41 row_half_mirror row_mask:0xf bank_mask:0xf bound_ctrl:1
	v_pk_fma_f32 v[2:3], v[20:21], v[126:127], v[24:25] op_sel_hi:[1,0,1]
	v_pk_mul_f32 v[26:27], v[150:151], v[134:135] op_sel:[0,1]
	ds_write_b64 v184, v[40:41] offset:29696
	v_pk_mul_f32 v[28:29], v[150:151], v[136:137] op_sel_hi:[1,0]
	v_pk_fma_f32 v[26:27], v[4:5], v[118:119], v[26:27] op_sel:[0,1,0]
	v_pk_mul_f32 v[30:31], v[150:151], v[136:137] op_sel:[0,1]
	v_pk_fma_f32 v[28:29], v[6:7], v[120:121], v[28:29] op_sel_hi:[1,0,1]
	v_pk_fma_f32 v[4:5], v[20:21], v[126:127], v[26:27] op_sel:[0,1,0]
	v_pk_fma_f32 v[30:31], v[8:9], v[120:121], v[30:31] op_sel:[0,1,0]
	v_pk_fma_f32 v[6:7], v[20:21], v[128:129], v[28:29] op_sel_hi:[1,0,1]
	v_pk_mul_f32 v[32:33], v[150:151], v[138:139] op_sel_hi:[1,0]
	v_pk_fma_f32 v[8:9], v[20:21], v[128:129], v[30:31] op_sel:[0,1,0]
	v_pk_mul_f32 v[34:35], v[150:151], v[138:139] op_sel:[0,1]
	v_pk_fma_f32 v[32:33], v[10:11], v[122:123], v[32:33] op_sel_hi:[1,0,1]
	v_pk_mul_f32 v[36:37], v[150:151], v[140:141] op_sel_hi:[1,0]
	v_pk_fma_f32 v[34:35], v[12:13], v[122:123], v[34:35] op_sel:[0,1,0]
	v_pk_fma_f32 v[10:11], v[20:21], v[130:131], v[32:33] op_sel_hi:[1,0,1]
	v_pk_fma_f32 v[36:37], v[14:15], v[124:125], v[36:37] op_sel_hi:[1,0,1]
	v_pk_fma_f32 v[12:13], v[20:21], v[130:131], v[34:35] op_sel:[0,1,0]
	v_pk_mul_f32 v[38:39], v[150:151], v[140:141] op_sel:[0,1]
	v_pk_fma_f32 v[14:15], v[20:21], v[132:133], v[36:37] op_sel_hi:[1,0,1]
	v_pk_mul_f32 v[42:43], v[2:3], v[142:143] op_sel_hi:[1,0]
	v_pk_fma_f32 v[38:39], v[16:17], v[124:125], v[38:39] op_sel:[0,1,0]
	v_pk_mul_f32 v[44:45], v[10:11], v[146:147] op_sel_hi:[1,0]
	v_pk_fma_f32 v[42:43], v[4:5], v[142:143], v[42:43] op_sel:[0,1,0]
	v_pk_fma_f32 v[16:17], v[20:21], v[132:133], v[38:39] op_sel:[0,1,0]
	v_pk_fma_f32 v[44:45], v[12:13], v[146:147], v[44:45] op_sel:[0,1,0]
	v_pk_fma_f32 v[42:43], v[6:7], v[144:145], v[42:43] op_sel_hi:[1,0,1]
	v_pk_fma_f32 v[44:45], v[14:15], v[148:149], v[44:45] op_sel_hi:[1,0,1]
	v_pk_fma_f32 v[42:43], v[8:9], v[144:145], v[42:43] op_sel:[0,1,0]
	v_pk_fma_f32 v[44:45], v[16:17], v[148:149], v[44:45] op_sel:[0,1,0]
	v_pk_add_f32 v[42:43], v[42:43], v[44:45]
	s_waitcnt lgkmcnt(0)
; __device__ __forceinline__ void rwkv_block(KP p, int o, int b, int hd, LAS unsigned char* lds, const bf16_t* P, bf16_t* YB) {
;     ...
;             for (int tt = 0; tt < 16; ++tt) {
;                 const int o8 = tt * 64 + c * 8;
;                 const f32x4 ka = *(const LAS f32x4*)(KK + o8), kb = *(const LAS f32x4*)(KK + o8 + 4);
;                 const f32x4 wa = *(const LAS f32x4*)(Wd + o8), wb = *(const LAS f32x4*)(Wd + o8 + 4);
;                 const f32x4 ba = *(const LAS f32x4*)(BB + o8), bb = *(const LAS f32x4*)(BB + o8 + 4);
;                 const f32x4 ma = *(const LAS f32x4*)(KM + o8), mb = *(const LAS f32x4*)(KM + o8 + 4);
;                 const f32x4 ra = *(const LAS f32x4*)(Rr + o8), rb = *(const LAS f32x4*)(Rr + o8 + 4);
;                 const f32x2 v01 = *(const LAS f32x2*)(Vv + tt * 64 + 2 * rp);
;                 const f32x2 k2[4] = {{ka[0], ka[1]}, {ka[2], ka[3]}, {kb[0], kb[1]}, {kb[2], kb[3]}};
;                 const f32x2 w2[4] = {{wa[0], wa[1]}, {wa[2], wa[3]}, {wb[0], wb[1]}, {wb[2], wb[3]}};
;                 const f32x2 b2[4] = {{ba[0], ba[1]}, {ba[2], ba[3]}, {bb[0], bb[1]}, {bb[2], bb[3]}};
;                 const f32x2 m2[4] = {{ma[0], ma[1]}, {ma[2], ma[3]}, {mb[0], mb[1]}, {mb[2], mb[3]}};
;                 const f32x2 r2[4] = {{ra[0], ra[1]}, {ra[2], ra[3]}, {rb[0], rb[1]}, {rb[2], rb[3]}};
;                 f32x2 accA = s[0][0] * k2[0], accB = s[1][0] * k2[0], accA2 = s[0][2] * k2[2], accB2 = s[1][2] * k2[2];
;                 accA = s[0][1] * k2[1] + accA; accB = s[1][1] * k2[1] + accB; accA2 = s[0][3] * k2[3] + accA2; accB2 = s[1][3] * k2[3] + accB2;
;                 accA = accA + accA2; accB = accB + accB2;
;                 float sa0 = accA.x + accA.y, sa1 = accB.x + accB.y;
;                 sa0 += dpp_f<0xB1>(sa0); sa1 += dpp_f<0xB1>(sa1);
;                 sa0 += dpp_f<0x4E>(sa0); sa1 += dpp_f<0x4E>(sa1);
;                 sa0 += dpp_f<0x141>(sa0); sa1 += dpp_f<0x141>(sa1);
;                 const f32x2 saA = {sa0, sa0}, saB = {sa1, sa1}, vA = {v01.x, v01.x}, vB = {v01.y, v01.y};
;                 f32x2 yA, yB;
; #pragma unroll
;                 for (int j = 0; j < 4; ++j) {
;                     f32x2 tA = vA * m2[j], tB = vB * m2[j];
;                     tA = saA * b2[j] + tA; tB = saB * b2[j] + tB;
;                     s[0][j] = s[0][j] * w2[j] + tA; s[1][j] = s[1][j] * w2[j] + tB;
	v_pk_mul_f32 v[20:21], v[2:3], v[64:65] op_sel_hi:[1,0]
	v_pk_mul_f32 v[22:23], v[10:11], v[68:69] op_sel_hi:[1,0]
	ds_read_b128 v[110:113], v180 offset:5888
	v_pk_fma_f32 v[20:21], v[4:5], v[64:65], v[20:21] op_sel:[0,1,0]
	v_pk_fma_f32 v[22:23], v[12:13], v[68:69], v[22:23] op_sel:[0,1,0]
	ds_read_b128 v[114:117], v180 offset:5904
	v_pk_fma_f32 v[20:21], v[6:7], v[66:67], v[20:21] op_sel_hi:[1,0,1]
	v_pk_fma_f32 v[22:23], v[14:15], v[70:71], v[22:23] op_sel_hi:[1,0,1]
	ds_read_b64 v[150:151], v181 offset:22272
	v_pk_fma_f32 v[20:21], v[8:9], v[66:67], v[20:21] op_sel:[0,1,0]
	v_pk_fma_f32 v[22:23], v[16:17], v[70:71], v[22:23] op_sel:[0,1,0]
	ds_read_b128 v[134:137], v180 offset:14080
	ds_read_b128 v[138:141], v180 offset:14096
	v_pk_add_f32 v[20:21], v[20:21], v[22:23]
	ds_read_b128 v[118:121], v180 offset:1792
	ds_read_b128 v[122:125], v180 offset:1808
	v_add_f32_dpp v20, v20, v20 quad_perm:[1,0,3,2] row_mask:0xf bank_mask:0xf bound_ctrl:1
	v_add_f32_dpp v21, v21, v21 quad_perm:[1,0,3,2] row_mask:0xf bank_mask:0xf bound_ctrl:1
	ds_read_b128 v[126:129], v180 offset:9984
	v_add_f32_dpp v20, v20, v20 quad_perm:[2,3,0,1] row_mask:0xf bank_mask:0xf bound_ctrl:1
	v_add_f32_dpp v21, v21, v21 quad_perm:[2,3,0,1] row_mask:0xf bank_mask:0xf bound_ctrl:1
	ds_read_b128 v[130:133], v180 offset:10000
	v_add_f32_dpp v20, v20, v20 row_half_mirror row_mask:0xf bank_mask:0xf bound_ctrl:1
	v_add_f32_dpp v21, v21, v21 row_half_mirror row_mask:0xf bank_mask:0xf bound_ctrl:1
	ds_read_b128 v[142:145], v180 offset:18176
	ds_read_b128 v[146:149], v180 offset:18192
	v_add_f32_dpp v42, v42, v42 quad_perm:[1,0,3,2] row_mask:0xf bank_mask:0xf bound_ctrl:1
	v_add_f32_dpp v43, v43, v43 quad_perm:[1,0,3,2] row_mask:0xf bank_mask:0xf bound_ctrl:1
	v_pk_mul_f32 v[24:25], v[104:105], v[88:89] op_sel_hi:[1,0]
	v_add_f32_dpp v42, v42, v42 quad_perm:[2,3,0,1] row_mask:0xf bank_mask:0xf bound_ctrl:1
	v_add_f32_dpp v43, v43, v43 quad_perm:[2,3,0,1] row_mask:0xf bank_mask:0xf bound_ctrl:1
	v_pk_fma_f32 v[24:25], v[2:3], v[72:73], v[24:25] op_sel_hi:[1,0,1]
	v_add_f32_dpp v42, v42, v42 row_half_mirror row_mask:0xf bank_mask:0xf bound_ctrl:1
	v_add_f32_dpp v43, v43, v43 row_half_mirror row_mask:0xf bank_mask:0xf bound_ctrl:1
	v_pk_fma_f32 v[2:3], v[20:21], v[80:81], v[24:25] op_sel_hi:[1,0,1]
	v_pk_mul_f32 v[26:27], v[104:105], v[88:89] op_sel:[0,1]
	ds_write_b64 v184, v[42:43] offset:29952
	v_pk_mul_f32 v[28:29], v[104:105], v[90:91] op_sel_hi:[1,0]
	v_pk_fma_f32 v[26:27], v[4:5], v[72:73], v[26:27] op_sel:[0,1,0]
	v_pk_mul_f32 v[30:31], v[104:105], v[90:91] op_sel:[0,1]
	v_pk_fma_f32 v[28:29], v[6:7], v[74:75], v[28:29] op_sel_hi:[1,0,1]
	v_pk_fma_f32 v[4:5], v[20:21], v[80:81], v[26:27] op_sel:[0,1,0]
	v_pk_fma_f32 v[30:31], v[8:9], v[74:75], v[30:31] op_sel:[0,1,0]
	v_pk_fma_f32 v[6:7], v[20:21], v[82:83], v[28:29] op_sel_hi:[1,0,1]
	v_pk_mul_f32 v[32:33], v[104:105], v[92:93] op_sel_hi:[1,0]
	v_pk_fma_f32 v[8:9], v[20:21], v[82:83], v[30:31] op_sel:[0,1,0]
	v_pk_mul_f32 v[34:35], v[104:105], v[92:93] op_sel:[0,1]
	v_pk_fma_f32 v[32:33], v[10:11], v[76:77], v[32:33] op_sel_hi:[1,0,1]
	v_pk_mul_f32 v[36:37], v[104:105], v[94:95] op_sel_hi:[1,0]
	v_pk_fma_f32 v[34:35], v[12:13], v[76:77], v[34:35] op_sel:[0,1,0]
	v_pk_fma_f32 v[10:11], v[20:21], v[84:85], v[32:33] op_sel_hi:[1,0,1]
	v_pk_fma_f32 v[36:37], v[14:15], v[78:79], v[36:37] op_sel_hi:[1,0,1]
	v_pk_fma_f32 v[12:13], v[20:21], v[84:85], v[34:35] op_sel:[0,1,0]
	v_pk_mul_f32 v[38:39], v[104:105], v[94:95] op_sel:[0,1]
	v_pk_fma_f32 v[14:15], v[20:21], v[86:87], v[36:37] op_sel_hi:[1,0,1]
	v_pk_mul_f32 v[40:41], v[2:3], v[96:97] op_sel_hi:[1,0]
	v_pk_fma_f32 v[38:39], v[16:17], v[78:79], v[38:39] op_sel:[0,1,0]
	v_pk_mul_f32 v[44:45], v[10:11], v[100:101] op_sel_hi:[1,0]
	v_pk_fma_f32 v[40:41], v[4:5], v[96:97], v[40:41] op_sel:[0,1,0]
	v_pk_fma_f32 v[16:17], v[20:21], v[86:87], v[38:39] op_sel:[0,1,0]
	v_pk_fma_f32 v[44:45], v[12:13], v[100:101], v[44:45] op_sel:[0,1,0]
	v_pk_fma_f32 v[40:41], v[6:7], v[98:99], v[40:41] op_sel_hi:[1,0,1]
	v_pk_fma_f32 v[44:45], v[14:15], v[102:103], v[44:45] op_sel_hi:[1,0,1]
	v_pk_fma_f32 v[40:41], v[8:9], v[98:99], v[40:41] op_sel:[0,1,0]
	v_pk_fma_f32 v[44:45], v[16:17], v[102:103], v[44:45] op_sel:[0,1,0]
	v_pk_add_f32 v[40:41], v[40:41], v[44:45]
	s_waitcnt lgkmcnt(0)
; __device__ __forceinline__ void rwkv_block(KP p, int o, int b, int hd, LAS unsigned char* lds, const bf16_t* P, bf16_t* YB) {
;     ...
;             for (int tt = 0; tt < 16; ++tt) {
;                 const int o8 = tt * 64 + c * 8;
;                 const f32x4 ka = *(const LAS f32x4*)(KK + o8), kb = *(const LAS f32x4*)(KK + o8 + 4);
;                 const f32x4 wa = *(const LAS f32x4*)(Wd + o8), wb = *(const LAS f32x4*)(Wd + o8 + 4);
;                 const f32x4 ba = *(const LAS f32x4*)(BB + o8), bb = *(const LAS f32x4*)(BB + o8 + 4);
;                 const f32x4 ma = *(const LAS f32x4*)(KM + o8), mb = *(const LAS f32x4*)(KM + o8 + 4);
;                 const f32x4 ra = *(const LAS f32x4*)(Rr + o8), rb = *(const LAS f32x4*)(Rr + o8 + 4);
;                 const f32x2 v01 = *(const LAS f32x2*)(Vv + tt * 64 + 2 * rp);
;                 const f32x2 k2[4] = {{ka[0], ka[1]}, {ka[2], ka[3]}, {kb[0], kb[1]}, {kb[2], kb[3]}};
;                 const f32x2 w2[4] = {{wa[0], wa[1]}, {wa[2], wa[3]}, {wb[0], wb[1]}, {wb[2], wb[3]}};
;                 const f32x2 b2[4] = {{ba[0], ba[1]}, {ba[2], ba[3]}, {bb[0], bb[1]}, {bb[2], bb[3]}};
;                 const f32x2 m2[4] = {{ma[0], ma[1]}, {ma[2], ma[3]}, {mb[0], mb[1]}, {mb[2], mb[3]}};
;                 const f32x2 r2[4] = {{ra[0], ra[1]}, {ra[2], ra[3]}, {rb[0], rb[1]}, {rb[2], rb[3]}};
;                 f32x2 accA = s[0][0] * k2[0], accB = s[1][0] * k2[0], accA2 = s[0][2] * k2[2], accB2 = s[1][2] * k2[2];
;                 accA = s[0][1] * k2[1] + accA; accB = s[1][1] * k2[1] + accB; accA2 = s[0][3] * k2[3] + accA2; accB2 = s[1][3] * k2[3] + accB2;
;                 accA = accA + accA2; accB = accB + accB2;
;                 float sa0 = accA.x + accA.y, sa1 = accB.x + accB.y;
;                 sa0 += dpp_f<0xB1>(sa0); sa1 += dpp_f<0xB1>(sa1);
;                 sa0 += dpp_f<0x4E>(sa0); sa1 += dpp_f<0x4E>(sa1);
;                 sa0 += dpp_f<0x141>(sa0); sa1 += dpp_f<0x141>(sa1);
;                 const f32x2 saA = {sa0, sa0}, saB = {sa1, sa1}, vA = {v01.x, v01.x}, vB = {v01.y, v01.y};
;                 f32x2 yA, yB;
; #pragma unroll
;                 for (int j = 0; j < 4; ++j) {
;                     f32x2 tA = vA * m2[j], tB = vB * m2[j];
;                     tA = saA * b2[j] + tA; tB = saB * b2[j] + tB;
;                     s[0][j] = s[0][j] * w2[j] + tA; s[1][j] = s[1][j] * w2[j] + tB;
	v_pk_mul_f32 v[20:21], v[2:3], v[110:111] op_sel_hi:[1,0]
	v_pk_mul_f32 v[22:23], v[10:11], v[114:115] op_sel_hi:[1,0]
	ds_read_b128 v[64:67], v180 offset:6144
	v_pk_fma_f32 v[20:21], v[4:5], v[110:111], v[20:21] op_sel:[0,1,0]
	v_pk_fma_f32 v[22:23], v[12:13], v[114:115], v[22:23] op_sel:[0,1,0]
	ds_read_b128 v[68:71], v180 offset:6160
	v_pk_fma_f32 v[20:21], v[6:7], v[112:113], v[20:21] op_sel_hi:[1,0,1]
	v_pk_fma_f32 v[22:23], v[14:15], v[116:117], v[22:23] op_sel_hi:[1,0,1]
	ds_read_b64 v[104:105], v181 offset:22528
	v_pk_fma_f32 v[20:21], v[8:9], v[112:113], v[20:21] op_sel:[0,1,0]
	v_pk_fma_f32 v[22:23], v[16:17], v[116:117], v[22:23] op_sel:[0,1,0]
	ds_read_b128 v[88:91], v180 offset:14336
	ds_read_b128 v[92:95], v180 offset:14352
	v_pk_add_f32 v[20:21], v[20:21], v[22:23]
	ds_read_b128 v[72:75], v180 offset:2048
	ds_read_b128 v[76:79], v180 offset:2064
	v_add_f32_dpp v20, v20, v20 quad_perm:[1,0,3,2] row_mask:0xf bank_mask:0xf bound_ctrl:1
	v_add_f32_dpp v21, v21, v21 quad_perm:[1,0,3,2] row_mask:0xf bank_mask:0xf bound_ctrl:1
	ds_read_b128 v[80:83], v180 offset:10240
	v_add_f32_dpp v20, v20, v20 quad_perm:[2,3,0,1] row_mask:0xf bank_mask:0xf bound_ctrl:1
	v_add_f32_dpp v21, v21, v21 quad_perm:[2,3,0,1] row_mask:0xf bank_mask:0xf bound_ctrl:1
	ds_read_b128 v[84:87], v180 offset:10256
	v_add_f32_dpp v20, v20, v20 row_half_mirror row_mask:0xf bank_mask:0xf bound_ctrl:1
	v_add_f32_dpp v21, v21, v21 row_half_mirror row_mask:0xf bank_mask:0xf bound_ctrl:1
	ds_read_b128 v[96:99], v180 offset:18432
	ds_read_b128 v[100:103], v180 offset:18448
	v_add_f32_dpp v40, v40, v40 quad_perm:[1,0,3,2] row_mask:0xf bank_mask:0xf bound_ctrl:1
	v_add_f32_dpp v41, v41, v41 quad_perm:[1,0,3,2] row_mask:0xf bank_mask:0xf bound_ctrl:1
	v_pk_mul_f32 v[24:25], v[150:151], v[134:135] op_sel_hi:[1,0]
	v_add_f32_dpp v40, v40, v40 quad_perm:[2,3,0,1] row_mask:0xf bank_mask:0xf bound_ctrl:1
	v_add_f32_dpp v41, v41, v41 quad_perm:[2,3,0,1] row_mask:0xf bank_mask:0xf bound_ctrl:1
	v_pk_fma_f32 v[24:25], v[2:3], v[118:119], v[24:25] op_sel_hi:[1,0,1]
	v_add_f32_dpp v40, v40, v40 row_half_mirror row_mask:0xf bank_mask:0xf bound_ctrl:1
	v_add_f32_dpp v41, v41, v41 row_half_mirror row_mask:0xf bank_mask:0xf bound_ctrl:1
	v_pk_fma_f32 v[2:3], v[20:21], v[126:127], v[24:25] op_sel_hi:[1,0,1]
	v_pk_mul_f32 v[26:27], v[150:151], v[134:135] op_sel:[0,1]
	ds_write_b64 v184, v[40:41] offset:30208
	v_pk_mul_f32 v[28:29], v[150:151], v[136:137] op_sel_hi:[1,0]
	v_pk_fma_f32 v[26:27], v[4:5], v[118:119], v[26:27] op_sel:[0,1,0]
	v_pk_mul_f32 v[30:31], v[150:151], v[136:137] op_sel:[0,1]
	v_pk_fma_f32 v[28:29], v[6:7], v[120:121], v[28:29] op_sel_hi:[1,0,1]
	v_pk_fma_f32 v[4:5], v[20:21], v[126:127], v[26:27] op_sel:[0,1,0]
	v_pk_fma_f32 v[30:31], v[8:9], v[120:121], v[30:31] op_sel:[0,1,0]
	v_pk_fma_f32 v[6:7], v[20:21], v[128:129], v[28:29] op_sel_hi:[1,0,1]
	v_pk_mul_f32 v[32:33], v[150:151], v[138:139] op_sel_hi:[1,0]
	v_pk_fma_f32 v[8:9], v[20:21], v[128:129], v[30:31] op_sel:[0,1,0]
	v_pk_mul_f32 v[34:35], v[150:151], v[138:139] op_sel:[0,1]
	v_pk_fma_f32 v[32:33], v[10:11], v[122:123], v[32:33] op_sel_hi:[1,0,1]
	v_pk_mul_f32 v[36:37], v[150:151], v[140:141] op_sel_hi:[1,0]
	v_pk_fma_f32 v[34:35], v[12:13], v[122:123], v[34:35] op_sel:[0,1,0]
	v_pk_fma_f32 v[10:11], v[20:21], v[130:131], v[32:33] op_sel_hi:[1,0,1]
	v_pk_fma_f32 v[36:37], v[14:15], v[124:125], v[36:37] op_sel_hi:[1,0,1]
	v_pk_fma_f32 v[12:13], v[20:21], v[130:131], v[34:35] op_sel:[0,1,0]
	v_pk_mul_f32 v[38:39], v[150:151], v[140:141] op_sel:[0,1]
	v_pk_fma_f32 v[14:15], v[20:21], v[132:133], v[36:37] op_sel_hi:[1,0,1]
	v_pk_mul_f32 v[42:43], v[2:3], v[142:143] op_sel_hi:[1,0]
	v_pk_fma_f32 v[38:39], v[16:17], v[124:125], v[38:39] op_sel:[0,1,0]
	v_pk_mul_f32 v[44:45], v[10:11], v[146:147] op_sel_hi:[1,0]
	v_pk_fma_f32 v[42:43], v[4:5], v[142:143], v[42:43] op_sel:[0,1,0]
	v_pk_fma_f32 v[16:17], v[20:21], v[132:133], v[38:39] op_sel:[0,1,0]
	v_pk_fma_f32 v[44:45], v[12:13], v[146:147], v[44:45] op_sel:[0,1,0]
	v_pk_fma_f32 v[42:43], v[6:7], v[144:145], v[42:43] op_sel_hi:[1,0,1]
	v_pk_fma_f32 v[44:45], v[14:15], v[148:149], v[44:45] op_sel_hi:[1,0,1]
	v_pk_fma_f32 v[42:43], v[8:9], v[144:145], v[42:43] op_sel:[0,1,0]
	v_pk_fma_f32 v[44:45], v[16:17], v[148:149], v[44:45] op_sel:[0,1,0]
	v_pk_add_f32 v[42:43], v[42:43], v[44:45]
	s_waitcnt lgkmcnt(0)
; __device__ __forceinline__ void rwkv_block(KP p, int o, int b, int hd, LAS unsigned char* lds, const bf16_t* P, bf16_t* YB) {
;     ...
;             for (int tt = 0; tt < 16; ++tt) {
;                 const int o8 = tt * 64 + c * 8;
;                 const f32x4 ka = *(const LAS f32x4*)(KK + o8), kb = *(const LAS f32x4*)(KK + o8 + 4);
;                 const f32x4 wa = *(const LAS f32x4*)(Wd + o8), wb = *(const LAS f32x4*)(Wd + o8 + 4);
;                 const f32x4 ba = *(const LAS f32x4*)(BB + o8), bb = *(const LAS f32x4*)(BB + o8 + 4);
;                 const f32x4 ma = *(const LAS f32x4*)(KM + o8), mb = *(const LAS f32x4*)(KM + o8 + 4);
;                 const f32x4 ra = *(const LAS f32x4*)(Rr + o8), rb = *(const LAS f32x4*)(Rr + o8 + 4);
;                 const f32x2 v01 = *(const LAS f32x2*)(Vv + tt * 64 + 2 * rp);
;                 const f32x2 k2[4] = {{ka[0], ka[1]}, {ka[2], ka[3]}, {kb[0], kb[1]}, {kb[2], kb[3]}};
;                 const f32x2 w2[4] = {{wa[0], wa[1]}, {wa[2], wa[3]}, {wb[0], wb[1]}, {wb[2], wb[3]}};
;                 const f32x2 b2[4] = {{ba[0], ba[1]}, {ba[2], ba[3]}, {bb[0], bb[1]}, {bb[2], bb[3]}};
;                 const f32x2 m2[4] = {{ma[0], ma[1]}, {ma[2], ma[3]}, {mb[0], mb[1]}, {mb[2], mb[3]}};
;                 const f32x2 r2[4] = {{ra[0], ra[1]}, {ra[2], ra[3]}, {rb[0], rb[1]}, {rb[2], rb[3]}};
;                 f32x2 accA = s[0][0] * k2[0], accB = s[1][0] * k2[0], accA2 = s[0][2] * k2[2], accB2 = s[1][2] * k2[2];
;                 accA = s[0][1] * k2[1] + accA; accB = s[1][1] * k2[1] + accB; accA2 = s[0][3] * k2[3] + accA2; accB2 = s[1][3] * k2[3] + accB2;
;                 accA = accA + accA2; accB = accB + accB2;
;                 float sa0 = accA.x + accA.y, sa1 = accB.x + accB.y;
;                 sa0 += dpp_f<0xB1>(sa0); sa1 += dpp_f<0xB1>(sa1);
;                 sa0 += dpp_f<0x4E>(sa0); sa1 += dpp_f<0x4E>(sa1);
;                 sa0 += dpp_f<0x141>(sa0); sa1 += dpp_f<0x141>(sa1);
;                 const f32x2 saA = {sa0, sa0}, saB = {sa1, sa1}, vA = {v01.x, v01.x}, vB = {v01.y, v01.y};
;                 f32x2 yA, yB;
; #pragma unroll
;                 for (int j = 0; j < 4; ++j) {
;                     f32x2 tA = vA * m2[j], tB = vB * m2[j];
;                     tA = saA * b2[j] + tA; tB = saB * b2[j] + tB;
;                     s[0][j] = s[0][j] * w2[j] + tA; s[1][j] = s[1][j] * w2[j] + tB;
	v_pk_mul_f32 v[20:21], v[2:3], v[64:65] op_sel_hi:[1,0]
	v_pk_mul_f32 v[22:23], v[10:11], v[68:69] op_sel_hi:[1,0]
	ds_read_b128 v[110:113], v180 offset:6400
	v_pk_fma_f32 v[20:21], v[4:5], v[64:65], v[20:21] op_sel:[0,1,0]
	v_pk_fma_f32 v[22:23], v[12:13], v[68:69], v[22:23] op_sel:[0,1,0]
	ds_read_b128 v[114:117], v180 offset:6416
	v_pk_fma_f32 v[20:21], v[6:7], v[66:67], v[20:21] op_sel_hi:[1,0,1]
	v_pk_fma_f32 v[22:23], v[14:15], v[70:71], v[22:23] op_sel_hi:[1,0,1]
	ds_read_b64 v[150:151], v181 offset:22784
	v_pk_fma_f32 v[20:21], v[8:9], v[66:67], v[20:21] op_sel:[0,1,0]
	v_pk_fma_f32 v[22:23], v[16:17], v[70:71], v[22:23] op_sel:[0,1,0]
	ds_read_b128 v[134:137], v180 offset:14592
	ds_read_b128 v[138:141], v180 offset:14608
	v_pk_add_f32 v[20:21], v[20:21], v[22:23]
	ds_read_b128 v[118:121], v180 offset:2304
	ds_read_b128 v[122:125], v180 offset:2320
	v_add_f32_dpp v20, v20, v20 quad_perm:[1,0,3,2] row_mask:0xf bank_mask:0xf bound_ctrl:1
	v_add_f32_dpp v21, v21, v21 quad_perm:[1,0,3,2] row_mask:0xf bank_mask:0xf bound_ctrl:1
	ds_read_b128 v[126:129], v180 offset:10496
	v_add_f32_dpp v20, v20, v20 quad_perm:[2,3,0,1] row_mask:0xf bank_mask:0xf bound_ctrl:1
	v_add_f32_dpp v21, v21, v21 quad_perm:[2,3,0,1] row_mask:0xf bank_mask:0xf bound_ctrl:1
	ds_read_b128 v[130:133], v180 offset:10512
	v_add_f32_dpp v20, v20, v20 row_half_mirror row_mask:0xf bank_mask:0xf bound_ctrl:1
	v_add_f32_dpp v21, v21, v21 row_half_mirror row_mask:0xf bank_mask:0xf bound_ctrl:1
	ds_read_b128 v[142:145], v180 offset:18688
	ds_read_b128 v[146:149], v180 offset:18704
	v_add_f32_dpp v42, v42, v42 quad_perm:[1,0,3,2] row_mask:0xf bank_mask:0xf bound_ctrl:1
	v_add_f32_dpp v43, v43, v43 quad_perm:[1,0,3,2] row_mask:0xf bank_mask:0xf bound_ctrl:1
	v_pk_mul_f32 v[24:25], v[104:105], v[88:89] op_sel_hi:[1,0]
	v_add_f32_dpp v42, v42, v42 quad_perm:[2,3,0,1] row_mask:0xf bank_mask:0xf bound_ctrl:1
	v_add_f32_dpp v43, v43, v43 quad_perm:[2,3,0,1] row_mask:0xf bank_mask:0xf bound_ctrl:1
	v_pk_fma_f32 v[24:25], v[2:3], v[72:73], v[24:25] op_sel_hi:[1,0,1]
	v_add_f32_dpp v42, v42, v42 row_half_mirror row_mask:0xf bank_mask:0xf bound_ctrl:1
	v_add_f32_dpp v43, v43, v43 row_half_mirror row_mask:0xf bank_mask:0xf bound_ctrl:1
	v_pk_fma_f32 v[2:3], v[20:21], v[80:81], v[24:25] op_sel_hi:[1,0,1]
	v_pk_mul_f32 v[26:27], v[104:105], v[88:89] op_sel:[0,1]
	ds_write_b64 v184, v[42:43] offset:30464
	v_pk_mul_f32 v[28:29], v[104:105], v[90:91] op_sel_hi:[1,0]
	v_pk_fma_f32 v[26:27], v[4:5], v[72:73], v[26:27] op_sel:[0,1,0]
	v_pk_mul_f32 v[30:31], v[104:105], v[90:91] op_sel:[0,1]
	v_pk_fma_f32 v[28:29], v[6:7], v[74:75], v[28:29] op_sel_hi:[1,0,1]
	v_pk_fma_f32 v[4:5], v[20:21], v[80:81], v[26:27] op_sel:[0,1,0]
	v_pk_fma_f32 v[30:31], v[8:9], v[74:75], v[30:31] op_sel:[0,1,0]
	v_pk_fma_f32 v[6:7], v[20:21], v[82:83], v[28:29] op_sel_hi:[1,0,1]
	v_pk_mul_f32 v[32:33], v[104:105], v[92:93] op_sel_hi:[1,0]
	v_pk_fma_f32 v[8:9], v[20:21], v[82:83], v[30:31] op_sel:[0,1,0]
	v_pk_mul_f32 v[34:35], v[104:105], v[92:93] op_sel:[0,1]
	v_pk_fma_f32 v[32:33], v[10:11], v[76:77], v[32:33] op_sel_hi:[1,0,1]
	v_pk_mul_f32 v[36:37], v[104:105], v[94:95] op_sel_hi:[1,0]
	v_pk_fma_f32 v[34:35], v[12:13], v[76:77], v[34:35] op_sel:[0,1,0]
	v_pk_fma_f32 v[10:11], v[20:21], v[84:85], v[32:33] op_sel_hi:[1,0,1]
	v_pk_fma_f32 v[36:37], v[14:15], v[78:79], v[36:37] op_sel_hi:[1,0,1]
	v_pk_fma_f32 v[12:13], v[20:21], v[84:85], v[34:35] op_sel:[0,1,0]
	v_pk_mul_f32 v[38:39], v[104:105], v[94:95] op_sel:[0,1]
	v_pk_fma_f32 v[14:15], v[20:21], v[86:87], v[36:37] op_sel_hi:[1,0,1]
	v_pk_mul_f32 v[40:41], v[2:3], v[96:97] op_sel_hi:[1,0]
	v_pk_fma_f32 v[38:39], v[16:17], v[78:79], v[38:39] op_sel:[0,1,0]
	v_pk_mul_f32 v[44:45], v[10:11], v[100:101] op_sel_hi:[1,0]
	v_pk_fma_f32 v[40:41], v[4:5], v[96:97], v[40:41] op_sel:[0,1,0]
	v_pk_fma_f32 v[16:17], v[20:21], v[86:87], v[38:39] op_sel:[0,1,0]
	v_pk_fma_f32 v[44:45], v[12:13], v[100:101], v[44:45] op_sel:[0,1,0]
	v_pk_fma_f32 v[40:41], v[6:7], v[98:99], v[40:41] op_sel_hi:[1,0,1]
	v_pk_fma_f32 v[44:45], v[14:15], v[102:103], v[44:45] op_sel_hi:[1,0,1]
	v_pk_fma_f32 v[40:41], v[8:9], v[98:99], v[40:41] op_sel:[0,1,0]
	v_pk_fma_f32 v[44:45], v[16:17], v[102:103], v[44:45] op_sel:[0,1,0]
	v_pk_add_f32 v[40:41], v[40:41], v[44:45]
	s_waitcnt lgkmcnt(0)
; __device__ __forceinline__ void rwkv_block(KP p, int o, int b, int hd, LAS unsigned char* lds, const bf16_t* P, bf16_t* YB) {
;     ...
;             for (int tt = 0; tt < 16; ++tt) {
;                 const int o8 = tt * 64 + c * 8;
;                 const f32x4 ka = *(const LAS f32x4*)(KK + o8), kb = *(const LAS f32x4*)(KK + o8 + 4);
;                 const f32x4 wa = *(const LAS f32x4*)(Wd + o8), wb = *(const LAS f32x4*)(Wd + o8 + 4);
;                 const f32x4 ba = *(const LAS f32x4*)(BB + o8), bb = *(const LAS f32x4*)(BB + o8 + 4);
;                 const f32x4 ma = *(const LAS f32x4*)(KM + o8), mb = *(const LAS f32x4*)(KM + o8 + 4);
;                 const f32x4 ra = *(const LAS f32x4*)(Rr + o8), rb = *(const LAS f32x4*)(Rr + o8 + 4);
;                 const f32x2 v01 = *(const LAS f32x2*)(Vv + tt * 64 + 2 * rp);
;                 const f32x2 k2[4] = {{ka[0], ka[1]}, {ka[2], ka[3]}, {kb[0], kb[1]}, {kb[2], kb[3]}};
;                 const f32x2 w2[4] = {{wa[0], wa[1]}, {wa[2], wa[3]}, {wb[0], wb[1]}, {wb[2], wb[3]}};
;                 const f32x2 b2[4] = {{ba[0], ba[1]}, {ba[2], ba[3]}, {bb[0], bb[1]}, {bb[2], bb[3]}};
;                 const f32x2 m2[4] = {{ma[0], ma[1]}, {ma[2], ma[3]}, {mb[0], mb[1]}, {mb[2], mb[3]}};
;                 const f32x2 r2[4] = {{ra[0], ra[1]}, {ra[2], ra[3]}, {rb[0], rb[1]}, {rb[2], rb[3]}};
;                 f32x2 accA = s[0][0] * k2[0], accB = s[1][0] * k2[0], accA2 = s[0][2] * k2[2], accB2 = s[1][2] * k2[2];
;                 accA = s[0][1] * k2[1] + accA; accB = s[1][1] * k2[1] + accB; accA2 = s[0][3] * k2[3] + accA2; accB2 = s[1][3] * k2[3] + accB2;
;                 accA = accA + accA2; accB = accB + accB2;
;                 float sa0 = accA.x + accA.y, sa1 = accB.x + accB.y;
;                 sa0 += dpp_f<0xB1>(sa0); sa1 += dpp_f<0xB1>(sa1);
;                 sa0 += dpp_f<0x4E>(sa0); sa1 += dpp_f<0x4E>(sa1);
;                 sa0 += dpp_f<0x141>(sa0); sa1 += dpp_f<0x141>(sa1);
;                 const f32x2 saA = {sa0, sa0}, saB = {sa1, sa1}, vA = {v01.x, v01.x}, vB = {v01.y, v01.y};
;                 f32x2 yA, yB;
; #pragma unroll
;                 for (int j = 0; j < 4; ++j) {
;                     f32x2 tA = vA * m2[j], tB = vB * m2[j];
;                     tA = saA * b2[j] + tA; tB = saB * b2[j] + tB;
;                     s[0][j] = s[0][j] * w2[j] + tA; s[1][j] = s[1][j] * w2[j] + tB;
	v_pk_mul_f32 v[20:21], v[2:3], v[110:111] op_sel_hi:[1,0]
	v_pk_mul_f32 v[22:23], v[10:11], v[114:115] op_sel_hi:[1,0]
	ds_read_b128 v[64:67], v180 offset:6656
	v_pk_fma_f32 v[20:21], v[4:5], v[110:111], v[20:21] op_sel:[0,1,0]
	v_pk_fma_f32 v[22:23], v[12:13], v[114:115], v[22:23] op_sel:[0,1,0]
	ds_read_b128 v[68:71], v180 offset:6672
	v_pk_fma_f32 v[20:21], v[6:7], v[112:113], v[20:21] op_sel_hi:[1,0,1]
	v_pk_fma_f32 v[22:23], v[14:15], v[116:117], v[22:23] op_sel_hi:[1,0,1]
	ds_read_b64 v[104:105], v181 offset:23040
	v_pk_fma_f32 v[20:21], v[8:9], v[112:113], v[20:21] op_sel:[0,1,0]
	v_pk_fma_f32 v[22:23], v[16:17], v[116:117], v[22:23] op_sel:[0,1,0]
	ds_read_b128 v[88:91], v180 offset:14848
	ds_read_b128 v[92:95], v180 offset:14864
	v_pk_add_f32 v[20:21], v[20:21], v[22:23]
	ds_read_b128 v[72:75], v180 offset:2560
	ds_read_b128 v[76:79], v180 offset:2576
	v_add_f32_dpp v20, v20, v20 quad_perm:[1,0,3,2] row_mask:0xf bank_mask:0xf bound_ctrl:1
	v_add_f32_dpp v21, v21, v21 quad_perm:[1,0,3,2] row_mask:0xf bank_mask:0xf bound_ctrl:1
	ds_read_b128 v[80:83], v180 offset:10752
	v_add_f32_dpp v20, v20, v20 quad_perm:[2,3,0,1] row_mask:0xf bank_mask:0xf bound_ctrl:1
	v_add_f32_dpp v21, v21, v21 quad_perm:[2,3,0,1] row_mask:0xf bank_mask:0xf bound_ctrl:1
	ds_read_b128 v[84:87], v180 offset:10768
	v_add_f32_dpp v20, v20, v20 row_half_mirror row_mask:0xf bank_mask:0xf bound_ctrl:1
	v_add_f32_dpp v21, v21, v21 row_half_mirror row_mask:0xf bank_mask:0xf bound_ctrl:1
	ds_read_b128 v[96:99], v180 offset:18944
	ds_read_b128 v[100:103], v180 offset:18960
	v_add_f32_dpp v40, v40, v40 quad_perm:[1,0,3,2] row_mask:0xf bank_mask:0xf bound_ctrl:1
	v_add_f32_dpp v41, v41, v41 quad_perm:[1,0,3,2] row_mask:0xf bank_mask:0xf bound_ctrl:1
	v_pk_mul_f32 v[24:25], v[150:151], v[134:135] op_sel_hi:[1,0]
	v_add_f32_dpp v40, v40, v40 quad_perm:[2,3,0,1] row_mask:0xf bank_mask:0xf bound_ctrl:1
	v_add_f32_dpp v41, v41, v41 quad_perm:[2,3,0,1] row_mask:0xf bank_mask:0xf bound_ctrl:1
	v_pk_fma_f32 v[24:25], v[2:3], v[118:119], v[24:25] op_sel_hi:[1,0,1]
	v_add_f32_dpp v40, v40, v40 row_half_mirror row_mask:0xf bank_mask:0xf bound_ctrl:1
	v_add_f32_dpp v41, v41, v41 row_half_mirror row_mask:0xf bank_mask:0xf bound_ctrl:1
	v_pk_fma_f32 v[2:3], v[20:21], v[126:127], v[24:25] op_sel_hi:[1,0,1]
	v_pk_mul_f32 v[26:27], v[150:151], v[134:135] op_sel:[0,1]
	ds_write_b64 v184, v[40:41] offset:30720
	v_pk_mul_f32 v[28:29], v[150:151], v[136:137] op_sel_hi:[1,0]
	v_pk_fma_f32 v[26:27], v[4:5], v[118:119], v[26:27] op_sel:[0,1,0]
	v_pk_mul_f32 v[30:31], v[150:151], v[136:137] op_sel:[0,1]
	v_pk_fma_f32 v[28:29], v[6:7], v[120:121], v[28:29] op_sel_hi:[1,0,1]
	v_pk_fma_f32 v[4:5], v[20:21], v[126:127], v[26:27] op_sel:[0,1,0]
	v_pk_fma_f32 v[30:31], v[8:9], v[120:121], v[30:31] op_sel:[0,1,0]
	v_pk_fma_f32 v[6:7], v[20:21], v[128:129], v[28:29] op_sel_hi:[1,0,1]
	v_pk_mul_f32 v[32:33], v[150:151], v[138:139] op_sel_hi:[1,0]
	v_pk_fma_f32 v[8:9], v[20:21], v[128:129], v[30:31] op_sel:[0,1,0]
	v_pk_mul_f32 v[34:35], v[150:151], v[138:139] op_sel:[0,1]
	v_pk_fma_f32 v[32:33], v[10:11], v[122:123], v[32:33] op_sel_hi:[1,0,1]
	v_pk_mul_f32 v[36:37], v[150:151], v[140:141] op_sel_hi:[1,0]
	v_pk_fma_f32 v[34:35], v[12:13], v[122:123], v[34:35] op_sel:[0,1,0]
	v_pk_fma_f32 v[10:11], v[20:21], v[130:131], v[32:33] op_sel_hi:[1,0,1]
	v_pk_fma_f32 v[36:37], v[14:15], v[124:125], v[36:37] op_sel_hi:[1,0,1]
	v_pk_fma_f32 v[12:13], v[20:21], v[130:131], v[34:35] op_sel:[0,1,0]
	v_pk_mul_f32 v[38:39], v[150:151], v[140:141] op_sel:[0,1]
	v_pk_fma_f32 v[14:15], v[20:21], v[132:133], v[36:37] op_sel_hi:[1,0,1]
	v_pk_mul_f32 v[42:43], v[2:3], v[142:143] op_sel_hi:[1,0]
	v_pk_fma_f32 v[38:39], v[16:17], v[124:125], v[38:39] op_sel:[0,1,0]
	v_pk_mul_f32 v[44:45], v[10:11], v[146:147] op_sel_hi:[1,0]
	v_pk_fma_f32 v[42:43], v[4:5], v[142:143], v[42:43] op_sel:[0,1,0]
	v_pk_fma_f32 v[16:17], v[20:21], v[132:133], v[38:39] op_sel:[0,1,0]
	v_pk_fma_f32 v[44:45], v[12:13], v[146:147], v[44:45] op_sel:[0,1,0]
	v_pk_fma_f32 v[42:43], v[6:7], v[144:145], v[42:43] op_sel_hi:[1,0,1]
	v_pk_fma_f32 v[44:45], v[14:15], v[148:149], v[44:45] op_sel_hi:[1,0,1]
	v_pk_fma_f32 v[42:43], v[8:9], v[144:145], v[42:43] op_sel:[0,1,0]
	v_pk_fma_f32 v[44:45], v[16:17], v[148:149], v[44:45] op_sel:[0,1,0]
	v_pk_add_f32 v[42:43], v[42:43], v[44:45]
	s_waitcnt lgkmcnt(0)
; __device__ __forceinline__ void rwkv_block(KP p, int o, int b, int hd, LAS unsigned char* lds, const bf16_t* P, bf16_t* YB) {
;     ...
;             for (int tt = 0; tt < 16; ++tt) {
;                 const int o8 = tt * 64 + c * 8;
;                 const f32x4 ka = *(const LAS f32x4*)(KK + o8), kb = *(const LAS f32x4*)(KK + o8 + 4);
;                 const f32x4 wa = *(const LAS f32x4*)(Wd + o8), wb = *(const LAS f32x4*)(Wd + o8 + 4);
;                 const f32x4 ba = *(const LAS f32x4*)(BB + o8), bb = *(const LAS f32x4*)(BB + o8 + 4);
;                 const f32x4 ma = *(const LAS f32x4*)(KM + o8), mb = *(const LAS f32x4*)(KM + o8 + 4);
;                 const f32x4 ra = *(const LAS f32x4*)(Rr + o8), rb = *(const LAS f32x4*)(Rr + o8 + 4);
;                 const f32x2 v01 = *(const LAS f32x2*)(Vv + tt * 64 + 2 * rp);
;                 const f32x2 k2[4] = {{ka[0], ka[1]}, {ka[2], ka[3]}, {kb[0], kb[1]}, {kb[2], kb[3]}};
;                 const f32x2 w2[4] = {{wa[0], wa[1]}, {wa[2], wa[3]}, {wb[0], wb[1]}, {wb[2], wb[3]}};
;                 const f32x2 b2[4] = {{ba[0], ba[1]}, {ba[2], ba[3]}, {bb[0], bb[1]}, {bb[2], bb[3]}};
;                 const f32x2 m2[4] = {{ma[0], ma[1]}, {ma[2], ma[3]}, {mb[0], mb[1]}, {mb[2], mb[3]}};
;                 const f32x2 r2[4] = {{ra[0], ra[1]}, {ra[2], ra[3]}, {rb[0], rb[1]}, {rb[2], rb[3]}};
;                 f32x2 accA = s[0][0] * k2[0], accB = s[1][0] * k2[0], accA2 = s[0][2] * k2[2], accB2 = s[1][2] * k2[2];
;                 accA = s[0][1] * k2[1] + accA; accB = s[1][1] * k2[1] + accB; accA2 = s[0][3] * k2[3] + accA2; accB2 = s[1][3] * k2[3] + accB2;
;                 accA = accA + accA2; accB = accB + accB2;
;                 float sa0 = accA.x + accA.y, sa1 = accB.x + accB.y;
;                 sa0 += dpp_f<0xB1>(sa0); sa1 += dpp_f<0xB1>(sa1);
;                 sa0 += dpp_f<0x4E>(sa0); sa1 += dpp_f<0x4E>(sa1);
;                 sa0 += dpp_f<0x141>(sa0); sa1 += dpp_f<0x141>(sa1);
;                 const f32x2 saA = {sa0, sa0}, saB = {sa1, sa1}, vA = {v01.x, v01.x}, vB = {v01.y, v01.y};
;                 f32x2 yA, yB;
; #pragma unroll
;                 for (int j = 0; j < 4; ++j) {
;                     f32x2 tA = vA * m2[j], tB = vB * m2[j];
;                     tA = saA * b2[j] + tA; tB = saB * b2[j] + tB;
;                     s[0][j] = s[0][j] * w2[j] + tA; s[1][j] = s[1][j] * w2[j] + tB;
	v_pk_mul_f32 v[20:21], v[2:3], v[64:65] op_sel_hi:[1,0]
	v_pk_mul_f32 v[22:23], v[10:11], v[68:69] op_sel_hi:[1,0]
	ds_read_b128 v[110:113], v180 offset:6912
	v_pk_fma_f32 v[20:21], v[4:5], v[64:65], v[20:21] op_sel:[0,1,0]
	v_pk_fma_f32 v[22:23], v[12:13], v[68:69], v[22:23] op_sel:[0,1,0]
	ds_read_b128 v[114:117], v180 offset:6928
	v_pk_fma_f32 v[20:21], v[6:7], v[66:67], v[20:21] op_sel_hi:[1,0,1]
	v_pk_fma_f32 v[22:23], v[14:15], v[70:71], v[22:23] op_sel_hi:[1,0,1]
	ds_read_b64 v[150:151], v181 offset:23296
	v_pk_fma_f32 v[20:21], v[8:9], v[66:67], v[20:21] op_sel:[0,1,0]
	v_pk_fma_f32 v[22:23], v[16:17], v[70:71], v[22:23] op_sel:[0,1,0]
	ds_read_b128 v[134:137], v180 offset:15104
	ds_read_b128 v[138:141], v180 offset:15120
	v_pk_add_f32 v[20:21], v[20:21], v[22:23]
	ds_read_b128 v[118:121], v180 offset:2816
	ds_read_b128 v[122:125], v180 offset:2832
	v_add_f32_dpp v20, v20, v20 quad_perm:[1,0,3,2] row_mask:0xf bank_mask:0xf bound_ctrl:1
	v_add_f32_dpp v21, v21, v21 quad_perm:[1,0,3,2] row_mask:0xf bank_mask:0xf bound_ctrl:1
	ds_read_b128 v[126:129], v180 offset:11008
	v_add_f32_dpp v20, v20, v20 quad_perm:[2,3,0,1] row_mask:0xf bank_mask:0xf bound_ctrl:1
	v_add_f32_dpp v21, v21, v21 quad_perm:[2,3,0,1] row_mask:0xf bank_mask:0xf bound_ctrl:1
	ds_read_b128 v[130:133], v180 offset:11024
	v_add_f32_dpp v20, v20, v20 row_half_mirror row_mask:0xf bank_mask:0xf bound_ctrl:1
	v_add_f32_dpp v21, v21, v21 row_half_mirror row_mask:0xf bank_mask:0xf bound_ctrl:1
	ds_read_b128 v[142:145], v180 offset:19200
	ds_read_b128 v[146:149], v180 offset:19216
	v_add_f32_dpp v42, v42, v42 quad_perm:[1,0,3,2] row_mask:0xf bank_mask:0xf bound_ctrl:1
	v_add_f32_dpp v43, v43, v43 quad_perm:[1,0,3,2] row_mask:0xf bank_mask:0xf bound_ctrl:1
	v_pk_mul_f32 v[24:25], v[104:105], v[88:89] op_sel_hi:[1,0]
	v_add_f32_dpp v42, v42, v42 quad_perm:[2,3,0,1] row_mask:0xf bank_mask:0xf bound_ctrl:1
	v_add_f32_dpp v43, v43, v43 quad_perm:[2,3,0,1] row_mask:0xf bank_mask:0xf bound_ctrl:1
	v_pk_fma_f32 v[24:25], v[2:3], v[72:73], v[24:25] op_sel_hi:[1,0,1]
	v_add_f32_dpp v42, v42, v42 row_half_mirror row_mask:0xf bank_mask:0xf bound_ctrl:1
	v_add_f32_dpp v43, v43, v43 row_half_mirror row_mask:0xf bank_mask:0xf bound_ctrl:1
	v_pk_fma_f32 v[2:3], v[20:21], v[80:81], v[24:25] op_sel_hi:[1,0,1]
	v_pk_mul_f32 v[26:27], v[104:105], v[88:89] op_sel:[0,1]
	ds_write_b64 v184, v[42:43] offset:30976
	v_pk_mul_f32 v[28:29], v[104:105], v[90:91] op_sel_hi:[1,0]
	v_pk_fma_f32 v[26:27], v[4:5], v[72:73], v[26:27] op_sel:[0,1,0]
	v_pk_mul_f32 v[30:31], v[104:105], v[90:91] op_sel:[0,1]
	v_pk_fma_f32 v[28:29], v[6:7], v[74:75], v[28:29] op_sel_hi:[1,0,1]
	v_pk_fma_f32 v[4:5], v[20:21], v[80:81], v[26:27] op_sel:[0,1,0]
	v_pk_fma_f32 v[30:31], v[8:9], v[74:75], v[30:31] op_sel:[0,1,0]
	v_pk_fma_f32 v[6:7], v[20:21], v[82:83], v[28:29] op_sel_hi:[1,0,1]
	v_pk_mul_f32 v[32:33], v[104:105], v[92:93] op_sel_hi:[1,0]
	v_pk_fma_f32 v[8:9], v[20:21], v[82:83], v[30:31] op_sel:[0,1,0]
	v_pk_mul_f32 v[34:35], v[104:105], v[92:93] op_sel:[0,1]
	v_pk_fma_f32 v[32:33], v[10:11], v[76:77], v[32:33] op_sel_hi:[1,0,1]
	v_pk_mul_f32 v[36:37], v[104:105], v[94:95] op_sel_hi:[1,0]
	v_pk_fma_f32 v[34:35], v[12:13], v[76:77], v[34:35] op_sel:[0,1,0]
	v_pk_fma_f32 v[10:11], v[20:21], v[84:85], v[32:33] op_sel_hi:[1,0,1]
	v_pk_fma_f32 v[36:37], v[14:15], v[78:79], v[36:37] op_sel_hi:[1,0,1]
	v_pk_fma_f32 v[12:13], v[20:21], v[84:85], v[34:35] op_sel:[0,1,0]
	v_pk_mul_f32 v[38:39], v[104:105], v[94:95] op_sel:[0,1]
	v_pk_fma_f32 v[14:15], v[20:21], v[86:87], v[36:37] op_sel_hi:[1,0,1]
	v_pk_mul_f32 v[40:41], v[2:3], v[96:97] op_sel_hi:[1,0]
	v_pk_fma_f32 v[38:39], v[16:17], v[78:79], v[38:39] op_sel:[0,1,0]
	v_pk_mul_f32 v[44:45], v[10:11], v[100:101] op_sel_hi:[1,0]
	v_pk_fma_f32 v[40:41], v[4:5], v[96:97], v[40:41] op_sel:[0,1,0]
	v_pk_fma_f32 v[16:17], v[20:21], v[86:87], v[38:39] op_sel:[0,1,0]
	v_pk_fma_f32 v[44:45], v[12:13], v[100:101], v[44:45] op_sel:[0,1,0]
	v_pk_fma_f32 v[40:41], v[6:7], v[98:99], v[40:41] op_sel_hi:[1,0,1]
	v_pk_fma_f32 v[44:45], v[14:15], v[102:103], v[44:45] op_sel_hi:[1,0,1]
	v_pk_fma_f32 v[40:41], v[8:9], v[98:99], v[40:41] op_sel:[0,1,0]
	v_pk_fma_f32 v[44:45], v[16:17], v[102:103], v[44:45] op_sel:[0,1,0]
	v_pk_add_f32 v[40:41], v[40:41], v[44:45]
	s_waitcnt lgkmcnt(0)
; __device__ __forceinline__ void rwkv_block(KP p, int o, int b, int hd, LAS unsigned char* lds, const bf16_t* P, bf16_t* YB) {
;     ...
;             for (int tt = 0; tt < 16; ++tt) {
;                 const int o8 = tt * 64 + c * 8;
;                 const f32x4 ka = *(const LAS f32x4*)(KK + o8), kb = *(const LAS f32x4*)(KK + o8 + 4);
;                 const f32x4 wa = *(const LAS f32x4*)(Wd + o8), wb = *(const LAS f32x4*)(Wd + o8 + 4);
;                 const f32x4 ba = *(const LAS f32x4*)(BB + o8), bb = *(const LAS f32x4*)(BB + o8 + 4);
;                 const f32x4 ma = *(const LAS f32x4*)(KM + o8), mb = *(const LAS f32x4*)(KM + o8 + 4);
;                 const f32x4 ra = *(const LAS f32x4*)(Rr + o8), rb = *(const LAS f32x4*)(Rr + o8 + 4);
;                 const f32x2 v01 = *(const LAS f32x2*)(Vv + tt * 64 + 2 * rp);
;                 const f32x2 k2[4] = {{ka[0], ka[1]}, {ka[2], ka[3]}, {kb[0], kb[1]}, {kb[2], kb[3]}};
;                 const f32x2 w2[4] = {{wa[0], wa[1]}, {wa[2], wa[3]}, {wb[0], wb[1]}, {wb[2], wb[3]}};
;                 const f32x2 b2[4] = {{ba[0], ba[1]}, {ba[2], ba[3]}, {bb[0], bb[1]}, {bb[2], bb[3]}};
;                 const f32x2 m2[4] = {{ma[0], ma[1]}, {ma[2], ma[3]}, {mb[0], mb[1]}, {mb[2], mb[3]}};
;                 const f32x2 r2[4] = {{ra[0], ra[1]}, {ra[2], ra[3]}, {rb[0], rb[1]}, {rb[2], rb[3]}};
;                 f32x2 accA = s[0][0] * k2[0], accB = s[1][0] * k2[0], accA2 = s[0][2] * k2[2], accB2 = s[1][2] * k2[2];
;                 accA = s[0][1] * k2[1] + accA; accB = s[1][1] * k2[1] + accB; accA2 = s[0][3] * k2[3] + accA2; accB2 = s[1][3] * k2[3] + accB2;
;                 accA = accA + accA2; accB = accB + accB2;
;                 float sa0 = accA.x + accA.y, sa1 = accB.x + accB.y;
;                 sa0 += dpp_f<0xB1>(sa0); sa1 += dpp_f<0xB1>(sa1);
;                 sa0 += dpp_f<0x4E>(sa0); sa1 += dpp_f<0x4E>(sa1);
;                 sa0 += dpp_f<0x141>(sa0); sa1 += dpp_f<0x141>(sa1);
;                 const f32x2 saA = {sa0, sa0}, saB = {sa1, sa1}, vA = {v01.x, v01.x}, vB = {v01.y, v01.y};
;                 f32x2 yA, yB;
; #pragma unroll
;                 for (int j = 0; j < 4; ++j) {
;                     f32x2 tA = vA * m2[j], tB = vB * m2[j];
;                     tA = saA * b2[j] + tA; tB = saB * b2[j] + tB;
;                     s[0][j] = s[0][j] * w2[j] + tA; s[1][j] = s[1][j] * w2[j] + tB;
	v_pk_mul_f32 v[20:21], v[2:3], v[110:111] op_sel_hi:[1,0]
	v_pk_mul_f32 v[22:23], v[10:11], v[114:115] op_sel_hi:[1,0]
	ds_read_b128 v[64:67], v180 offset:7168
	v_pk_fma_f32 v[20:21], v[4:5], v[110:111], v[20:21] op_sel:[0,1,0]
	v_pk_fma_f32 v[22:23], v[12:13], v[114:115], v[22:23] op_sel:[0,1,0]
	ds_read_b128 v[68:71], v180 offset:7184
	v_pk_fma_f32 v[20:21], v[6:7], v[112:113], v[20:21] op_sel_hi:[1,0,1]
	v_pk_fma_f32 v[22:23], v[14:15], v[116:117], v[22:23] op_sel_hi:[1,0,1]
	ds_read_b64 v[104:105], v181 offset:23552
	v_pk_fma_f32 v[20:21], v[8:9], v[112:113], v[20:21] op_sel:[0,1,0]
	v_pk_fma_f32 v[22:23], v[16:17], v[116:117], v[22:23] op_sel:[0,1,0]
	ds_read_b128 v[88:91], v180 offset:15360
	ds_read_b128 v[92:95], v180 offset:15376
	v_pk_add_f32 v[20:21], v[20:21], v[22:23]
	ds_read_b128 v[72:75], v180 offset:3072
	ds_read_b128 v[76:79], v180 offset:3088
	v_add_f32_dpp v20, v20, v20 quad_perm:[1,0,3,2] row_mask:0xf bank_mask:0xf bound_ctrl:1
	v_add_f32_dpp v21, v21, v21 quad_perm:[1,0,3,2] row_mask:0xf bank_mask:0xf bound_ctrl:1
	ds_read_b128 v[80:83], v180 offset:11264
	v_add_f32_dpp v20, v20, v20 quad_perm:[2,3,0,1] row_mask:0xf bank_mask:0xf bound_ctrl:1
	v_add_f32_dpp v21, v21, v21 quad_perm:[2,3,0,1] row_mask:0xf bank_mask:0xf bound_ctrl:1
	ds_read_b128 v[84:87], v180 offset:11280
	v_add_f32_dpp v20, v20, v20 row_half_mirror row_mask:0xf bank_mask:0xf bound_ctrl:1
	v_add_f32_dpp v21, v21, v21 row_half_mirror row_mask:0xf bank_mask:0xf bound_ctrl:1
	ds_read_b128 v[96:99], v180 offset:19456
	ds_read_b128 v[100:103], v180 offset:19472
	v_add_f32_dpp v40, v40, v40 quad_perm:[1,0,3,2] row_mask:0xf bank_mask:0xf bound_ctrl:1
	v_add_f32_dpp v41, v41, v41 quad_perm:[1,0,3,2] row_mask:0xf bank_mask:0xf bound_ctrl:1
	v_pk_mul_f32 v[24:25], v[150:151], v[134:135] op_sel_hi:[1,0]
	v_add_f32_dpp v40, v40, v40 quad_perm:[2,3,0,1] row_mask:0xf bank_mask:0xf bound_ctrl:1
	v_add_f32_dpp v41, v41, v41 quad_perm:[2,3,0,1] row_mask:0xf bank_mask:0xf bound_ctrl:1
	v_pk_fma_f32 v[24:25], v[2:3], v[118:119], v[24:25] op_sel_hi:[1,0,1]
	v_add_f32_dpp v40, v40, v40 row_half_mirror row_mask:0xf bank_mask:0xf bound_ctrl:1
	v_add_f32_dpp v41, v41, v41 row_half_mirror row_mask:0xf bank_mask:0xf bound_ctrl:1
	v_pk_fma_f32 v[2:3], v[20:21], v[126:127], v[24:25] op_sel_hi:[1,0,1]
	v_pk_mul_f32 v[26:27], v[150:151], v[134:135] op_sel:[0,1]
	ds_write_b64 v184, v[40:41] offset:31232
	v_pk_mul_f32 v[28:29], v[150:151], v[136:137] op_sel_hi:[1,0]
	v_pk_fma_f32 v[26:27], v[4:5], v[118:119], v[26:27] op_sel:[0,1,0]
	v_pk_mul_f32 v[30:31], v[150:151], v[136:137] op_sel:[0,1]
	v_pk_fma_f32 v[28:29], v[6:7], v[120:121], v[28:29] op_sel_hi:[1,0,1]
	v_pk_fma_f32 v[4:5], v[20:21], v[126:127], v[26:27] op_sel:[0,1,0]
	v_pk_fma_f32 v[30:31], v[8:9], v[120:121], v[30:31] op_sel:[0,1,0]
	v_pk_fma_f32 v[6:7], v[20:21], v[128:129], v[28:29] op_sel_hi:[1,0,1]
	v_pk_mul_f32 v[32:33], v[150:151], v[138:139] op_sel_hi:[1,0]
	v_pk_fma_f32 v[8:9], v[20:21], v[128:129], v[30:31] op_sel:[0,1,0]
	v_pk_mul_f32 v[34:35], v[150:151], v[138:139] op_sel:[0,1]
	v_pk_fma_f32 v[32:33], v[10:11], v[122:123], v[32:33] op_sel_hi:[1,0,1]
	v_pk_mul_f32 v[36:37], v[150:151], v[140:141] op_sel_hi:[1,0]
	v_pk_fma_f32 v[34:35], v[12:13], v[122:123], v[34:35] op_sel:[0,1,0]
	v_pk_fma_f32 v[10:11], v[20:21], v[130:131], v[32:33] op_sel_hi:[1,0,1]
	v_pk_fma_f32 v[36:37], v[14:15], v[124:125], v[36:37] op_sel_hi:[1,0,1]
	v_pk_fma_f32 v[12:13], v[20:21], v[130:131], v[34:35] op_sel:[0,1,0]
	v_pk_mul_f32 v[38:39], v[150:151], v[140:141] op_sel:[0,1]
	v_pk_fma_f32 v[14:15], v[20:21], v[132:133], v[36:37] op_sel_hi:[1,0,1]
	v_pk_mul_f32 v[42:43], v[2:3], v[142:143] op_sel_hi:[1,0]
	v_pk_fma_f32 v[38:39], v[16:17], v[124:125], v[38:39] op_sel:[0,1,0]
	v_pk_mul_f32 v[44:45], v[10:11], v[146:147] op_sel_hi:[1,0]
	v_pk_fma_f32 v[42:43], v[4:5], v[142:143], v[42:43] op_sel:[0,1,0]
	v_pk_fma_f32 v[16:17], v[20:21], v[132:133], v[38:39] op_sel:[0,1,0]
	v_pk_fma_f32 v[44:45], v[12:13], v[146:147], v[44:45] op_sel:[0,1,0]
	v_pk_fma_f32 v[42:43], v[6:7], v[144:145], v[42:43] op_sel_hi:[1,0,1]
	v_pk_fma_f32 v[44:45], v[14:15], v[148:149], v[44:45] op_sel_hi:[1,0,1]
	v_pk_fma_f32 v[42:43], v[8:9], v[144:145], v[42:43] op_sel:[0,1,0]
	v_pk_fma_f32 v[44:45], v[16:17], v[148:149], v[44:45] op_sel:[0,1,0]
	v_pk_add_f32 v[42:43], v[42:43], v[44:45]
	s_waitcnt lgkmcnt(0)
; __device__ __forceinline__ void rwkv_block(KP p, int o, int b, int hd, LAS unsigned char* lds, const bf16_t* P, bf16_t* YB) {
;     ...
;             for (int tt = 0; tt < 16; ++tt) {
;                 const int o8 = tt * 64 + c * 8;
;                 const f32x4 ka = *(const LAS f32x4*)(KK + o8), kb = *(const LAS f32x4*)(KK + o8 + 4);
;                 const f32x4 wa = *(const LAS f32x4*)(Wd + o8), wb = *(const LAS f32x4*)(Wd + o8 + 4);
;                 const f32x4 ba = *(const LAS f32x4*)(BB + o8), bb = *(const LAS f32x4*)(BB + o8 + 4);
;                 const f32x4 ma = *(const LAS f32x4*)(KM + o8), mb = *(const LAS f32x4*)(KM + o8 + 4);
;                 const f32x4 ra = *(const LAS f32x4*)(Rr + o8), rb = *(const LAS f32x4*)(Rr + o8 + 4);
;                 const f32x2 v01 = *(const LAS f32x2*)(Vv + tt * 64 + 2 * rp);
;                 const f32x2 k2[4] = {{ka[0], ka[1]}, {ka[2], ka[3]}, {kb[0], kb[1]}, {kb[2], kb[3]}};
;                 const f32x2 w2[4] = {{wa[0], wa[1]}, {wa[2], wa[3]}, {wb[0], wb[1]}, {wb[2], wb[3]}};
;                 const f32x2 b2[4] = {{ba[0], ba[1]}, {ba[2], ba[3]}, {bb[0], bb[1]}, {bb[2], bb[3]}};
;                 const f32x2 m2[4] = {{ma[0], ma[1]}, {ma[2], ma[3]}, {mb[0], mb[1]}, {mb[2], mb[3]}};
;                 const f32x2 r2[4] = {{ra[0], ra[1]}, {ra[2], ra[3]}, {rb[0], rb[1]}, {rb[2], rb[3]}};
;                 f32x2 accA = s[0][0] * k2[0], accB = s[1][0] * k2[0], accA2 = s[0][2] * k2[2], accB2 = s[1][2] * k2[2];
;                 accA = s[0][1] * k2[1] + accA; accB = s[1][1] * k2[1] + accB; accA2 = s[0][3] * k2[3] + accA2; accB2 = s[1][3] * k2[3] + accB2;
;                 accA = accA + accA2; accB = accB + accB2;
;                 float sa0 = accA.x + accA.y, sa1 = accB.x + accB.y;
;                 sa0 += dpp_f<0xB1>(sa0); sa1 += dpp_f<0xB1>(sa1);
;                 sa0 += dpp_f<0x4E>(sa0); sa1 += dpp_f<0x4E>(sa1);
;                 sa0 += dpp_f<0x141>(sa0); sa1 += dpp_f<0x141>(sa1);
;                 const f32x2 saA = {sa0, sa0}, saB = {sa1, sa1}, vA = {v01.x, v01.x}, vB = {v01.y, v01.y};
;                 f32x2 yA, yB;
; #pragma unroll
;                 for (int j = 0; j < 4; ++j) {
;                     f32x2 tA = vA * m2[j], tB = vB * m2[j];
;                     tA = saA * b2[j] + tA; tB = saB * b2[j] + tB;
;                     s[0][j] = s[0][j] * w2[j] + tA; s[1][j] = s[1][j] * w2[j] + tB;
	v_pk_mul_f32 v[20:21], v[2:3], v[64:65] op_sel_hi:[1,0]
	v_pk_mul_f32 v[22:23], v[10:11], v[68:69] op_sel_hi:[1,0]
	ds_read_b128 v[110:113], v180 offset:7424
	v_pk_fma_f32 v[20:21], v[4:5], v[64:65], v[20:21] op_sel:[0,1,0]
	v_pk_fma_f32 v[22:23], v[12:13], v[68:69], v[22:23] op_sel:[0,1,0]
	ds_read_b128 v[114:117], v180 offset:7440
	v_pk_fma_f32 v[20:21], v[6:7], v[66:67], v[20:21] op_sel_hi:[1,0,1]
	v_pk_fma_f32 v[22:23], v[14:15], v[70:71], v[22:23] op_sel_hi:[1,0,1]
	ds_read_b64 v[150:151], v181 offset:23808
	v_pk_fma_f32 v[20:21], v[8:9], v[66:67], v[20:21] op_sel:[0,1,0]
	v_pk_fma_f32 v[22:23], v[16:17], v[70:71], v[22:23] op_sel:[0,1,0]
	ds_read_b128 v[134:137], v180 offset:15616
	ds_read_b128 v[138:141], v180 offset:15632
	v_pk_add_f32 v[20:21], v[20:21], v[22:23]
	ds_read_b128 v[118:121], v180 offset:3328
	ds_read_b128 v[122:125], v180 offset:3344
	v_add_f32_dpp v20, v20, v20 quad_perm:[1,0,3,2] row_mask:0xf bank_mask:0xf bound_ctrl:1
	v_add_f32_dpp v21, v21, v21 quad_perm:[1,0,3,2] row_mask:0xf bank_mask:0xf bound_ctrl:1
	ds_read_b128 v[126:129], v180 offset:11520
	v_add_f32_dpp v20, v20, v20 quad_perm:[2,3,0,1] row_mask:0xf bank_mask:0xf bound_ctrl:1
	v_add_f32_dpp v21, v21, v21 quad_perm:[2,3,0,1] row_mask:0xf bank_mask:0xf bound_ctrl:1
	ds_read_b128 v[130:133], v180 offset:11536
	v_add_f32_dpp v20, v20, v20 row_half_mirror row_mask:0xf bank_mask:0xf bound_ctrl:1
	v_add_f32_dpp v21, v21, v21 row_half_mirror row_mask:0xf bank_mask:0xf bound_ctrl:1
	ds_read_b128 v[142:145], v180 offset:19712
	ds_read_b128 v[146:149], v180 offset:19728
	v_add_f32_dpp v42, v42, v42 quad_perm:[1,0,3,2] row_mask:0xf bank_mask:0xf bound_ctrl:1
	v_add_f32_dpp v43, v43, v43 quad_perm:[1,0,3,2] row_mask:0xf bank_mask:0xf bound_ctrl:1
	v_pk_mul_f32 v[24:25], v[104:105], v[88:89] op_sel_hi:[1,0]
	v_add_f32_dpp v42, v42, v42 quad_perm:[2,3,0,1] row_mask:0xf bank_mask:0xf bound_ctrl:1
	v_add_f32_dpp v43, v43, v43 quad_perm:[2,3,0,1] row_mask:0xf bank_mask:0xf bound_ctrl:1
	v_pk_fma_f32 v[24:25], v[2:3], v[72:73], v[24:25] op_sel_hi:[1,0,1]
	v_add_f32_dpp v42, v42, v42 row_half_mirror row_mask:0xf bank_mask:0xf bound_ctrl:1
	v_add_f32_dpp v43, v43, v43 row_half_mirror row_mask:0xf bank_mask:0xf bound_ctrl:1
	v_pk_fma_f32 v[2:3], v[20:21], v[80:81], v[24:25] op_sel_hi:[1,0,1]
	v_pk_mul_f32 v[26:27], v[104:105], v[88:89] op_sel:[0,1]
	ds_write_b64 v184, v[42:43] offset:31488
	v_pk_mul_f32 v[28:29], v[104:105], v[90:91] op_sel_hi:[1,0]
	v_pk_fma_f32 v[26:27], v[4:5], v[72:73], v[26:27] op_sel:[0,1,0]
	v_pk_mul_f32 v[30:31], v[104:105], v[90:91] op_sel:[0,1]
	v_pk_fma_f32 v[28:29], v[6:7], v[74:75], v[28:29] op_sel_hi:[1,0,1]
	v_pk_fma_f32 v[4:5], v[20:21], v[80:81], v[26:27] op_sel:[0,1,0]
	v_pk_fma_f32 v[30:31], v[8:9], v[74:75], v[30:31] op_sel:[0,1,0]
	v_pk_fma_f32 v[6:7], v[20:21], v[82:83], v[28:29] op_sel_hi:[1,0,1]
	v_pk_mul_f32 v[32:33], v[104:105], v[92:93] op_sel_hi:[1,0]
	v_pk_fma_f32 v[8:9], v[20:21], v[82:83], v[30:31] op_sel:[0,1,0]
	v_pk_mul_f32 v[34:35], v[104:105], v[92:93] op_sel:[0,1]
	v_pk_fma_f32 v[32:33], v[10:11], v[76:77], v[32:33] op_sel_hi:[1,0,1]
	v_pk_mul_f32 v[36:37], v[104:105], v[94:95] op_sel_hi:[1,0]
	v_pk_fma_f32 v[34:35], v[12:13], v[76:77], v[34:35] op_sel:[0,1,0]
	v_pk_fma_f32 v[10:11], v[20:21], v[84:85], v[32:33] op_sel_hi:[1,0,1]
	v_pk_fma_f32 v[36:37], v[14:15], v[78:79], v[36:37] op_sel_hi:[1,0,1]
	v_pk_fma_f32 v[12:13], v[20:21], v[84:85], v[34:35] op_sel:[0,1,0]
	v_pk_mul_f32 v[38:39], v[104:105], v[94:95] op_sel:[0,1]
	v_pk_fma_f32 v[14:15], v[20:21], v[86:87], v[36:37] op_sel_hi:[1,0,1]
	v_pk_mul_f32 v[40:41], v[2:3], v[96:97] op_sel_hi:[1,0]
	v_pk_fma_f32 v[38:39], v[16:17], v[78:79], v[38:39] op_sel:[0,1,0]
	v_pk_mul_f32 v[44:45], v[10:11], v[100:101] op_sel_hi:[1,0]
	v_pk_fma_f32 v[40:41], v[4:5], v[96:97], v[40:41] op_sel:[0,1,0]
	v_pk_fma_f32 v[16:17], v[20:21], v[86:87], v[38:39] op_sel:[0,1,0]
	v_pk_fma_f32 v[44:45], v[12:13], v[100:101], v[44:45] op_sel:[0,1,0]
	v_pk_fma_f32 v[40:41], v[6:7], v[98:99], v[40:41] op_sel_hi:[1,0,1]
	v_pk_fma_f32 v[44:45], v[14:15], v[102:103], v[44:45] op_sel_hi:[1,0,1]
	v_pk_fma_f32 v[40:41], v[8:9], v[98:99], v[40:41] op_sel:[0,1,0]
	v_pk_fma_f32 v[44:45], v[16:17], v[102:103], v[44:45] op_sel:[0,1,0]
	v_pk_add_f32 v[40:41], v[40:41], v[44:45]
	s_waitcnt lgkmcnt(0)
; __device__ __forceinline__ void rwkv_block(KP p, int o, int b, int hd, LAS unsigned char* lds, const bf16_t* P, bf16_t* YB) {
;     ...
;             for (int tt = 0; tt < 16; ++tt) {
;                 const int o8 = tt * 64 + c * 8;
;                 const f32x4 ka = *(const LAS f32x4*)(KK + o8), kb = *(const LAS f32x4*)(KK + o8 + 4);
;                 const f32x4 wa = *(const LAS f32x4*)(Wd + o8), wb = *(const LAS f32x4*)(Wd + o8 + 4);
;                 const f32x4 ba = *(const LAS f32x4*)(BB + o8), bb = *(const LAS f32x4*)(BB + o8 + 4);
;                 const f32x4 ma = *(const LAS f32x4*)(KM + o8), mb = *(const LAS f32x4*)(KM + o8 + 4);
;                 const f32x4 ra = *(const LAS f32x4*)(Rr + o8), rb = *(const LAS f32x4*)(Rr + o8 + 4);
;                 const f32x2 v01 = *(const LAS f32x2*)(Vv + tt * 64 + 2 * rp);
;                 const f32x2 k2[4] = {{ka[0], ka[1]}, {ka[2], ka[3]}, {kb[0], kb[1]}, {kb[2], kb[3]}};
;                 const f32x2 w2[4] = {{wa[0], wa[1]}, {wa[2], wa[3]}, {wb[0], wb[1]}, {wb[2], wb[3]}};
;                 const f32x2 b2[4] = {{ba[0], ba[1]}, {ba[2], ba[3]}, {bb[0], bb[1]}, {bb[2], bb[3]}};
;                 const f32x2 m2[4] = {{ma[0], ma[1]}, {ma[2], ma[3]}, {mb[0], mb[1]}, {mb[2], mb[3]}};
;                 const f32x2 r2[4] = {{ra[0], ra[1]}, {ra[2], ra[3]}, {rb[0], rb[1]}, {rb[2], rb[3]}};
;                 f32x2 accA = s[0][0] * k2[0], accB = s[1][0] * k2[0], accA2 = s[0][2] * k2[2], accB2 = s[1][2] * k2[2];
;                 accA = s[0][1] * k2[1] + accA; accB = s[1][1] * k2[1] + accB; accA2 = s[0][3] * k2[3] + accA2; accB2 = s[1][3] * k2[3] + accB2;
;                 accA = accA + accA2; accB = accB + accB2;
;                 float sa0 = accA.x + accA.y, sa1 = accB.x + accB.y;
;                 sa0 += dpp_f<0xB1>(sa0); sa1 += dpp_f<0xB1>(sa1);
;                 sa0 += dpp_f<0x4E>(sa0); sa1 += dpp_f<0x4E>(sa1);
;                 sa0 += dpp_f<0x141>(sa0); sa1 += dpp_f<0x141>(sa1);
;                 const f32x2 saA = {sa0, sa0}, saB = {sa1, sa1}, vA = {v01.x, v01.x}, vB = {v01.y, v01.y};
;                 f32x2 yA, yB;
; #pragma unroll
;                 for (int j = 0; j < 4; ++j) {
;                     f32x2 tA = vA * m2[j], tB = vB * m2[j];
;                     tA = saA * b2[j] + tA; tB = saB * b2[j] + tB;
;                     s[0][j] = s[0][j] * w2[j] + tA; s[1][j] = s[1][j] * w2[j] + tB;
	v_pk_mul_f32 v[20:21], v[2:3], v[110:111] op_sel_hi:[1,0]
	v_pk_mul_f32 v[22:23], v[10:11], v[114:115] op_sel_hi:[1,0]
	ds_read_b128 v[64:67], v180 offset:7680
	v_pk_fma_f32 v[20:21], v[4:5], v[110:111], v[20:21] op_sel:[0,1,0]
	v_pk_fma_f32 v[22:23], v[12:13], v[114:115], v[22:23] op_sel:[0,1,0]
	ds_read_b128 v[68:71], v180 offset:7696
	v_pk_fma_f32 v[20:21], v[6:7], v[112:113], v[20:21] op_sel_hi:[1,0,1]
	v_pk_fma_f32 v[22:23], v[14:15], v[116:117], v[22:23] op_sel_hi:[1,0,1]
	ds_read_b64 v[104:105], v181 offset:24064
	v_pk_fma_f32 v[20:21], v[8:9], v[112:113], v[20:21] op_sel:[0,1,0]
	v_pk_fma_f32 v[22:23], v[16:17], v[116:117], v[22:23] op_sel:[0,1,0]
	ds_read_b128 v[88:91], v180 offset:15872
	ds_read_b128 v[92:95], v180 offset:15888
	v_pk_add_f32 v[20:21], v[20:21], v[22:23]
	ds_read_b128 v[72:75], v180 offset:3584
	ds_read_b128 v[76:79], v180 offset:3600
	v_add_f32_dpp v20, v20, v20 quad_perm:[1,0,3,2] row_mask:0xf bank_mask:0xf bound_ctrl:1
	v_add_f32_dpp v21, v21, v21 quad_perm:[1,0,3,2] row_mask:0xf bank_mask:0xf bound_ctrl:1
	ds_read_b128 v[80:83], v180 offset:11776
	v_add_f32_dpp v20, v20, v20 quad_perm:[2,3,0,1] row_mask:0xf bank_mask:0xf bound_ctrl:1
	v_add_f32_dpp v21, v21, v21 quad_perm:[2,3,0,1] row_mask:0xf bank_mask:0xf bound_ctrl:1
	ds_read_b128 v[84:87], v180 offset:11792
	v_add_f32_dpp v20, v20, v20 row_half_mirror row_mask:0xf bank_mask:0xf bound_ctrl:1
	v_add_f32_dpp v21, v21, v21 row_half_mirror row_mask:0xf bank_mask:0xf bound_ctrl:1
	ds_read_b128 v[96:99], v180 offset:19968
	ds_read_b128 v[100:103], v180 offset:19984
	v_add_f32_dpp v40, v40, v40 quad_perm:[1,0,3,2] row_mask:0xf bank_mask:0xf bound_ctrl:1
	v_add_f32_dpp v41, v41, v41 quad_perm:[1,0,3,2] row_mask:0xf bank_mask:0xf bound_ctrl:1
	v_pk_mul_f32 v[24:25], v[150:151], v[134:135] op_sel_hi:[1,0]
	v_add_f32_dpp v40, v40, v40 quad_perm:[2,3,0,1] row_mask:0xf bank_mask:0xf bound_ctrl:1
	v_add_f32_dpp v41, v41, v41 quad_perm:[2,3,0,1] row_mask:0xf bank_mask:0xf bound_ctrl:1
	v_pk_fma_f32 v[24:25], v[2:3], v[118:119], v[24:25] op_sel_hi:[1,0,1]
	v_add_f32_dpp v40, v40, v40 row_half_mirror row_mask:0xf bank_mask:0xf bound_ctrl:1
	v_add_f32_dpp v41, v41, v41 row_half_mirror row_mask:0xf bank_mask:0xf bound_ctrl:1
	v_pk_fma_f32 v[2:3], v[20:21], v[126:127], v[24:25] op_sel_hi:[1,0,1]
	v_pk_mul_f32 v[26:27], v[150:151], v[134:135] op_sel:[0,1]
	ds_write_b64 v184, v[40:41] offset:31744
	v_pk_mul_f32 v[28:29], v[150:151], v[136:137] op_sel_hi:[1,0]
	v_pk_fma_f32 v[26:27], v[4:5], v[118:119], v[26:27] op_sel:[0,1,0]
	v_pk_mul_f32 v[30:31], v[150:151], v[136:137] op_sel:[0,1]
	v_pk_fma_f32 v[28:29], v[6:7], v[120:121], v[28:29] op_sel_hi:[1,0,1]
	v_pk_fma_f32 v[4:5], v[20:21], v[126:127], v[26:27] op_sel:[0,1,0]
	v_pk_fma_f32 v[30:31], v[8:9], v[120:121], v[30:31] op_sel:[0,1,0]
	v_pk_fma_f32 v[6:7], v[20:21], v[128:129], v[28:29] op_sel_hi:[1,0,1]
	v_pk_mul_f32 v[32:33], v[150:151], v[138:139] op_sel_hi:[1,0]
	v_pk_fma_f32 v[8:9], v[20:21], v[128:129], v[30:31] op_sel:[0,1,0]
	v_pk_mul_f32 v[34:35], v[150:151], v[138:139] op_sel:[0,1]
	v_pk_fma_f32 v[32:33], v[10:11], v[122:123], v[32:33] op_sel_hi:[1,0,1]
	v_pk_mul_f32 v[36:37], v[150:151], v[140:141] op_sel_hi:[1,0]
	v_pk_fma_f32 v[34:35], v[12:13], v[122:123], v[34:35] op_sel:[0,1,0]
	v_pk_fma_f32 v[10:11], v[20:21], v[130:131], v[32:33] op_sel_hi:[1,0,1]
	v_pk_fma_f32 v[36:37], v[14:15], v[124:125], v[36:37] op_sel_hi:[1,0,1]
	v_pk_fma_f32 v[12:13], v[20:21], v[130:131], v[34:35] op_sel:[0,1,0]
	v_pk_mul_f32 v[38:39], v[150:151], v[140:141] op_sel:[0,1]
	v_pk_fma_f32 v[14:15], v[20:21], v[132:133], v[36:37] op_sel_hi:[1,0,1]
	v_pk_mul_f32 v[42:43], v[2:3], v[142:143] op_sel_hi:[1,0]
	v_pk_fma_f32 v[38:39], v[16:17], v[124:125], v[38:39] op_sel:[0,1,0]
	v_pk_mul_f32 v[44:45], v[10:11], v[146:147] op_sel_hi:[1,0]
	v_pk_fma_f32 v[42:43], v[4:5], v[142:143], v[42:43] op_sel:[0,1,0]
	v_pk_fma_f32 v[16:17], v[20:21], v[132:133], v[38:39] op_sel:[0,1,0]
	v_pk_fma_f32 v[44:45], v[12:13], v[146:147], v[44:45] op_sel:[0,1,0]
	v_pk_fma_f32 v[42:43], v[6:7], v[144:145], v[42:43] op_sel_hi:[1,0,1]
	v_pk_fma_f32 v[44:45], v[14:15], v[148:149], v[44:45] op_sel_hi:[1,0,1]
	v_pk_fma_f32 v[42:43], v[8:9], v[144:145], v[42:43] op_sel:[0,1,0]
	v_pk_fma_f32 v[44:45], v[16:17], v[148:149], v[44:45] op_sel:[0,1,0]
	v_pk_add_f32 v[42:43], v[42:43], v[44:45]
	s_waitcnt lgkmcnt(0)
; __device__ __forceinline__ void rwkv_block(KP p, int o, int b, int hd, LAS unsigned char* lds, const bf16_t* P, bf16_t* YB) {
;     ...
;             for (int tt = 0; tt < 16; ++tt) {
;                 const int o8 = tt * 64 + c * 8;
;                 const f32x4 ka = *(const LAS f32x4*)(KK + o8), kb = *(const LAS f32x4*)(KK + o8 + 4);
;                 const f32x4 wa = *(const LAS f32x4*)(Wd + o8), wb = *(const LAS f32x4*)(Wd + o8 + 4);
;                 const f32x4 ba = *(const LAS f32x4*)(BB + o8), bb = *(const LAS f32x4*)(BB + o8 + 4);
;                 const f32x4 ma = *(const LAS f32x4*)(KM + o8), mb = *(const LAS f32x4*)(KM + o8 + 4);
;                 const f32x4 ra = *(const LAS f32x4*)(Rr + o8), rb = *(const LAS f32x4*)(Rr + o8 + 4);
;                 const f32x2 v01 = *(const LAS f32x2*)(Vv + tt * 64 + 2 * rp);
;                 const f32x2 k2[4] = {{ka[0], ka[1]}, {ka[2], ka[3]}, {kb[0], kb[1]}, {kb[2], kb[3]}};
;                 const f32x2 w2[4] = {{wa[0], wa[1]}, {wa[2], wa[3]}, {wb[0], wb[1]}, {wb[2], wb[3]}};
;                 const f32x2 b2[4] = {{ba[0], ba[1]}, {ba[2], ba[3]}, {bb[0], bb[1]}, {bb[2], bb[3]}};
;                 const f32x2 m2[4] = {{ma[0], ma[1]}, {ma[2], ma[3]}, {mb[0], mb[1]}, {mb[2], mb[3]}};
;                 const f32x2 r2[4] = {{ra[0], ra[1]}, {ra[2], ra[3]}, {rb[0], rb[1]}, {rb[2], rb[3]}};
;                 f32x2 accA = s[0][0] * k2[0], accB = s[1][0] * k2[0], accA2 = s[0][2] * k2[2], accB2 = s[1][2] * k2[2];
;                 accA = s[0][1] * k2[1] + accA; accB = s[1][1] * k2[1] + accB; accA2 = s[0][3] * k2[3] + accA2; accB2 = s[1][3] * k2[3] + accB2;
;                 accA = accA + accA2; accB = accB + accB2;
;                 float sa0 = accA.x + accA.y, sa1 = accB.x + accB.y;
;                 sa0 += dpp_f<0xB1>(sa0); sa1 += dpp_f<0xB1>(sa1);
;                 sa0 += dpp_f<0x4E>(sa0); sa1 += dpp_f<0x4E>(sa1);
;                 sa0 += dpp_f<0x141>(sa0); sa1 += dpp_f<0x141>(sa1);
;                 const f32x2 saA = {sa0, sa0}, saB = {sa1, sa1}, vA = {v01.x, v01.x}, vB = {v01.y, v01.y};
;                 f32x2 yA, yB;
; #pragma unroll
;                 for (int j = 0; j < 4; ++j) {
;                     f32x2 tA = vA * m2[j], tB = vB * m2[j];
;                     tA = saA * b2[j] + tA; tB = saB * b2[j] + tB;
;                     s[0][j] = s[0][j] * w2[j] + tA; s[1][j] = s[1][j] * w2[j] + tB;
	v_pk_mul_f32 v[20:21], v[2:3], v[64:65] op_sel_hi:[1,0]
	v_pk_mul_f32 v[22:23], v[10:11], v[68:69] op_sel_hi:[1,0]
	ds_read_b128 v[110:113], v180 offset:7936
	v_pk_fma_f32 v[20:21], v[4:5], v[64:65], v[20:21] op_sel:[0,1,0]
	v_pk_fma_f32 v[22:23], v[12:13], v[68:69], v[22:23] op_sel:[0,1,0]
	ds_read_b128 v[114:117], v180 offset:7952
	v_pk_fma_f32 v[20:21], v[6:7], v[66:67], v[20:21] op_sel_hi:[1,0,1]
	v_pk_fma_f32 v[22:23], v[14:15], v[70:71], v[22:23] op_sel_hi:[1,0,1]
	ds_read_b64 v[150:151], v181 offset:24320
	v_pk_fma_f32 v[20:21], v[8:9], v[66:67], v[20:21] op_sel:[0,1,0]
	v_pk_fma_f32 v[22:23], v[16:17], v[70:71], v[22:23] op_sel:[0,1,0]
	ds_read_b128 v[134:137], v180 offset:16128
	ds_read_b128 v[138:141], v180 offset:16144
	v_pk_add_f32 v[20:21], v[20:21], v[22:23]
	ds_read_b128 v[118:121], v180 offset:3840
	ds_read_b128 v[122:125], v180 offset:3856
	v_add_f32_dpp v20, v20, v20 quad_perm:[1,0,3,2] row_mask:0xf bank_mask:0xf bound_ctrl:1
	v_add_f32_dpp v21, v21, v21 quad_perm:[1,0,3,2] row_mask:0xf bank_mask:0xf bound_ctrl:1
	ds_read_b128 v[126:129], v180 offset:12032
	v_add_f32_dpp v20, v20, v20 quad_perm:[2,3,0,1] row_mask:0xf bank_mask:0xf bound_ctrl:1
	v_add_f32_dpp v21, v21, v21 quad_perm:[2,3,0,1] row_mask:0xf bank_mask:0xf bound_ctrl:1
	ds_read_b128 v[130:133], v180 offset:12048
	v_add_f32_dpp v20, v20, v20 row_half_mirror row_mask:0xf bank_mask:0xf bound_ctrl:1
	v_add_f32_dpp v21, v21, v21 row_half_mirror row_mask:0xf bank_mask:0xf bound_ctrl:1
	ds_read_b128 v[142:145], v180 offset:20224
	ds_read_b128 v[146:149], v180 offset:20240
	v_add_f32_dpp v42, v42, v42 quad_perm:[1,0,3,2] row_mask:0xf bank_mask:0xf bound_ctrl:1
	v_add_f32_dpp v43, v43, v43 quad_perm:[1,0,3,2] row_mask:0xf bank_mask:0xf bound_ctrl:1
	v_pk_mul_f32 v[24:25], v[104:105], v[88:89] op_sel_hi:[1,0]
	v_add_f32_dpp v42, v42, v42 quad_perm:[2,3,0,1] row_mask:0xf bank_mask:0xf bound_ctrl:1
	v_add_f32_dpp v43, v43, v43 quad_perm:[2,3,0,1] row_mask:0xf bank_mask:0xf bound_ctrl:1
	v_pk_fma_f32 v[24:25], v[2:3], v[72:73], v[24:25] op_sel_hi:[1,0,1]
	v_add_f32_dpp v42, v42, v42 row_half_mirror row_mask:0xf bank_mask:0xf bound_ctrl:1
	v_add_f32_dpp v43, v43, v43 row_half_mirror row_mask:0xf bank_mask:0xf bound_ctrl:1
	v_pk_fma_f32 v[2:3], v[20:21], v[80:81], v[24:25] op_sel_hi:[1,0,1]
	v_pk_mul_f32 v[26:27], v[104:105], v[88:89] op_sel:[0,1]
	ds_write_b64 v184, v[42:43] offset:32000
	v_pk_mul_f32 v[28:29], v[104:105], v[90:91] op_sel_hi:[1,0]
	v_pk_fma_f32 v[26:27], v[4:5], v[72:73], v[26:27] op_sel:[0,1,0]
	v_pk_mul_f32 v[30:31], v[104:105], v[90:91] op_sel:[0,1]
	v_pk_fma_f32 v[28:29], v[6:7], v[74:75], v[28:29] op_sel_hi:[1,0,1]
	v_pk_fma_f32 v[4:5], v[20:21], v[80:81], v[26:27] op_sel:[0,1,0]
	v_pk_fma_f32 v[30:31], v[8:9], v[74:75], v[30:31] op_sel:[0,1,0]
	v_pk_fma_f32 v[6:7], v[20:21], v[82:83], v[28:29] op_sel_hi:[1,0,1]
	v_pk_mul_f32 v[32:33], v[104:105], v[92:93] op_sel_hi:[1,0]
	v_pk_fma_f32 v[8:9], v[20:21], v[82:83], v[30:31] op_sel:[0,1,0]
	v_pk_mul_f32 v[34:35], v[104:105], v[92:93] op_sel:[0,1]
	v_pk_fma_f32 v[32:33], v[10:11], v[76:77], v[32:33] op_sel_hi:[1,0,1]
	v_pk_mul_f32 v[36:37], v[104:105], v[94:95] op_sel_hi:[1,0]
	v_pk_fma_f32 v[34:35], v[12:13], v[76:77], v[34:35] op_sel:[0,1,0]
	v_pk_fma_f32 v[10:11], v[20:21], v[84:85], v[32:33] op_sel_hi:[1,0,1]
	v_pk_fma_f32 v[36:37], v[14:15], v[78:79], v[36:37] op_sel_hi:[1,0,1]
	v_pk_fma_f32 v[12:13], v[20:21], v[84:85], v[34:35] op_sel:[0,1,0]
	v_pk_mul_f32 v[38:39], v[104:105], v[94:95] op_sel:[0,1]
	v_pk_fma_f32 v[14:15], v[20:21], v[86:87], v[36:37] op_sel_hi:[1,0,1]
	v_pk_mul_f32 v[40:41], v[2:3], v[96:97] op_sel_hi:[1,0]
	v_pk_fma_f32 v[38:39], v[16:17], v[78:79], v[38:39] op_sel:[0,1,0]
	v_pk_mul_f32 v[44:45], v[10:11], v[100:101] op_sel_hi:[1,0]
	v_pk_fma_f32 v[40:41], v[4:5], v[96:97], v[40:41] op_sel:[0,1,0]
	v_pk_fma_f32 v[16:17], v[20:21], v[86:87], v[38:39] op_sel:[0,1,0]
	v_pk_fma_f32 v[44:45], v[12:13], v[100:101], v[44:45] op_sel:[0,1,0]
	v_pk_fma_f32 v[40:41], v[6:7], v[98:99], v[40:41] op_sel_hi:[1,0,1]
	v_pk_fma_f32 v[44:45], v[14:15], v[102:103], v[44:45] op_sel_hi:[1,0,1]
	v_pk_fma_f32 v[40:41], v[8:9], v[98:99], v[40:41] op_sel:[0,1,0]
	v_pk_fma_f32 v[44:45], v[16:17], v[102:103], v[44:45] op_sel:[0,1,0]
	v_pk_add_f32 v[40:41], v[40:41], v[44:45]
	s_waitcnt lgkmcnt(0)
; __device__ __forceinline__ void rwkv_block(KP p, int o, int b, int hd, LAS unsigned char* lds, const bf16_t* P, bf16_t* YB) {
;     ...
;             for (int tt = 0; tt < 16; ++tt) {
;                 const int o8 = tt * 64 + c * 8;
;                 const f32x4 ka = *(const LAS f32x4*)(KK + o8), kb = *(const LAS f32x4*)(KK + o8 + 4);
;                 const f32x4 wa = *(const LAS f32x4*)(Wd + o8), wb = *(const LAS f32x4*)(Wd + o8 + 4);
;                 const f32x4 ba = *(const LAS f32x4*)(BB + o8), bb = *(const LAS f32x4*)(BB + o8 + 4);
;                 const f32x4 ma = *(const LAS f32x4*)(KM + o8), mb = *(const LAS f32x4*)(KM + o8 + 4);
;                 const f32x4 ra = *(const LAS f32x4*)(Rr + o8), rb = *(const LAS f32x4*)(Rr + o8 + 4);
;                 const f32x2 v01 = *(const LAS f32x2*)(Vv + tt * 64 + 2 * rp);
;                 const f32x2 k2[4] = {{ka[0], ka[1]}, {ka[2], ka[3]}, {kb[0], kb[1]}, {kb[2], kb[3]}};
;                 const f32x2 w2[4] = {{wa[0], wa[1]}, {wa[2], wa[3]}, {wb[0], wb[1]}, {wb[2], wb[3]}};
;                 const f32x2 b2[4] = {{ba[0], ba[1]}, {ba[2], ba[3]}, {bb[0], bb[1]}, {bb[2], bb[3]}};
;                 const f32x2 m2[4] = {{ma[0], ma[1]}, {ma[2], ma[3]}, {mb[0], mb[1]}, {mb[2], mb[3]}};
;                 const f32x2 r2[4] = {{ra[0], ra[1]}, {ra[2], ra[3]}, {rb[0], rb[1]}, {rb[2], rb[3]}};
;                 f32x2 accA = s[0][0] * k2[0], accB = s[1][0] * k2[0], accA2 = s[0][2] * k2[2], accB2 = s[1][2] * k2[2];
;                 accA = s[0][1] * k2[1] + accA; accB = s[1][1] * k2[1] + accB; accA2 = s[0][3] * k2[3] + accA2; accB2 = s[1][3] * k2[3] + accB2;
;                 accA = accA + accA2; accB = accB + accB2;
;                 float sa0 = accA.x + accA.y, sa1 = accB.x + accB.y;
;                 sa0 += dpp_f<0xB1>(sa0); sa1 += dpp_f<0xB1>(sa1);
;                 sa0 += dpp_f<0x4E>(sa0); sa1 += dpp_f<0x4E>(sa1);
;                 sa0 += dpp_f<0x141>(sa0); sa1 += dpp_f<0x141>(sa1);
;                 const f32x2 saA = {sa0, sa0}, saB = {sa1, sa1}, vA = {v01.x, v01.x}, vB = {v01.y, v01.y};
;                 f32x2 yA, yB;
; #pragma unroll
;                 for (int j = 0; j < 4; ++j) {
;                     f32x2 tA = vA * m2[j], tB = vB * m2[j];
;                     tA = saA * b2[j] + tA; tB = saB * b2[j] + tB;
;                     s[0][j] = s[0][j] * w2[j] + tA; s[1][j] = s[1][j] * w2[j] + tB;
	v_pk_mul_f32 v[20:21], v[2:3], v[110:111] op_sel_hi:[1,0]
	v_pk_mul_f32 v[22:23], v[10:11], v[114:115] op_sel_hi:[1,0]
	v_add_f32_dpp v40, v40, v40 quad_perm:[1,0,3,2] row_mask:0xf bank_mask:0xf bound_ctrl:1
	v_pk_fma_f32 v[20:21], v[4:5], v[110:111], v[20:21] op_sel:[0,1,0]
	v_pk_fma_f32 v[22:23], v[12:13], v[114:115], v[22:23] op_sel:[0,1,0]
	v_add_f32_dpp v41, v41, v41 quad_perm:[1,0,3,2] row_mask:0xf bank_mask:0xf bound_ctrl:1
	v_pk_fma_f32 v[20:21], v[6:7], v[112:113], v[20:21] op_sel_hi:[1,0,1]
	v_pk_fma_f32 v[22:23], v[14:15], v[116:117], v[22:23] op_sel_hi:[1,0,1]
	v_add_f32_dpp v40, v40, v40 quad_perm:[2,3,0,1] row_mask:0xf bank_mask:0xf bound_ctrl:1
	v_pk_fma_f32 v[20:21], v[8:9], v[112:113], v[20:21] op_sel:[0,1,0]
	v_pk_fma_f32 v[22:23], v[16:17], v[116:117], v[22:23] op_sel:[0,1,0]
	v_add_f32_dpp v41, v41, v41 quad_perm:[2,3,0,1] row_mask:0xf bank_mask:0xf bound_ctrl:1
	v_add_f32_dpp v40, v40, v40 row_half_mirror row_mask:0xf bank_mask:0xf bound_ctrl:1
	v_pk_add_f32 v[20:21], v[20:21], v[22:23]
	v_add_f32_dpp v41, v41, v41 row_half_mirror row_mask:0xf bank_mask:0xf bound_ctrl:1
	v_pk_mul_f32 v[24:25], v[150:151], v[134:135] op_sel_hi:[1,0]
	v_add_f32_dpp v20, v20, v20 quad_perm:[1,0,3,2] row_mask:0xf bank_mask:0xf bound_ctrl:1
	v_add_f32_dpp v21, v21, v21 quad_perm:[1,0,3,2] row_mask:0xf bank_mask:0xf bound_ctrl:1
	ds_write_b64 v184, v[40:41] offset:32256
	v_add_f32_dpp v20, v20, v20 quad_perm:[2,3,0,1] row_mask:0xf bank_mask:0xf bound_ctrl:1
	v_add_f32_dpp v21, v21, v21 quad_perm:[2,3,0,1] row_mask:0xf bank_mask:0xf bound_ctrl:1
	v_pk_fma_f32 v[24:25], v[2:3], v[118:119], v[24:25] op_sel_hi:[1,0,1]
	v_add_f32_dpp v20, v20, v20 row_half_mirror row_mask:0xf bank_mask:0xf bound_ctrl:1
	v_add_f32_dpp v21, v21, v21 row_half_mirror row_mask:0xf bank_mask:0xf bound_ctrl:1
	v_pk_mul_f32 v[26:27], v[150:151], v[134:135] op_sel:[0,1]
	v_pk_mul_f32 v[28:29], v[150:151], v[136:137] op_sel_hi:[1,0]
	v_pk_fma_f32 v[2:3], v[20:21], v[126:127], v[24:25] op_sel_hi:[1,0,1]
	v_pk_fma_f32 v[26:27], v[4:5], v[118:119], v[26:27] op_sel:[0,1,0]
	v_pk_fma_f32 v[28:29], v[6:7], v[120:121], v[28:29] op_sel_hi:[1,0,1]
	v_pk_mul_f32 v[30:31], v[150:151], v[136:137] op_sel:[0,1]
	v_pk_fma_f32 v[4:5], v[20:21], v[126:127], v[26:27] op_sel:[0,1,0]
	v_pk_fma_f32 v[6:7], v[20:21], v[128:129], v[28:29] op_sel_hi:[1,0,1]
	v_pk_fma_f32 v[30:31], v[8:9], v[120:121], v[30:31] op_sel:[0,1,0]
	v_pk_mul_f32 v[32:33], v[150:151], v[138:139] op_sel_hi:[1,0]
	v_pk_mul_f32 v[34:35], v[150:151], v[138:139] op_sel:[0,1]
	v_pk_fma_f32 v[8:9], v[20:21], v[128:129], v[30:31] op_sel:[0,1,0]
	v_pk_fma_f32 v[32:33], v[10:11], v[122:123], v[32:33] op_sel_hi:[1,0,1]
	v_pk_fma_f32 v[34:35], v[12:13], v[122:123], v[34:35] op_sel:[0,1,0]
	v_pk_mul_f32 v[36:37], v[150:151], v[140:141] op_sel_hi:[1,0]
	v_pk_fma_f32 v[10:11], v[20:21], v[130:131], v[32:33] op_sel_hi:[1,0,1]
	v_pk_fma_f32 v[12:13], v[20:21], v[130:131], v[34:35] op_sel:[0,1,0]
	v_pk_fma_f32 v[36:37], v[14:15], v[124:125], v[36:37] op_sel_hi:[1,0,1]
	v_pk_mul_f32 v[38:39], v[150:151], v[140:141] op_sel:[0,1]
	v_pk_mul_f32 v[42:43], v[2:3], v[142:143] op_sel_hi:[1,0]
	v_pk_fma_f32 v[14:15], v[20:21], v[132:133], v[36:37] op_sel_hi:[1,0,1]
	v_pk_fma_f32 v[38:39], v[16:17], v[124:125], v[38:39] op_sel:[0,1,0]
	v_pk_mul_f32 v[44:45], v[10:11], v[146:147] op_sel_hi:[1,0]
	v_pk_fma_f32 v[42:43], v[4:5], v[142:143], v[42:43] op_sel:[0,1,0]
	v_pk_fma_f32 v[16:17], v[20:21], v[132:133], v[38:39] op_sel:[0,1,0]
	v_pk_fma_f32 v[44:45], v[12:13], v[146:147], v[44:45] op_sel:[0,1,0]
	v_pk_fma_f32 v[42:43], v[6:7], v[144:145], v[42:43] op_sel_hi:[1,0,1]
	v_pk_fma_f32 v[44:45], v[14:15], v[148:149], v[44:45] op_sel_hi:[1,0,1]
	v_pk_fma_f32 v[42:43], v[8:9], v[144:145], v[42:43] op_sel:[0,1,0]
	v_pk_fma_f32 v[44:45], v[16:17], v[148:149], v[44:45] op_sel:[0,1,0]
	v_pk_add_f32 v[42:43], v[42:43], v[44:45]
	s_nop 1
	v_add_f32_dpp v42, v42, v42 quad_perm:[1,0,3,2] row_mask:0xf bank_mask:0xf bound_ctrl:1
	v_add_f32_dpp v43, v43, v43 quad_perm:[1,0,3,2] row_mask:0xf bank_mask:0xf bound_ctrl:1
	s_nop 0
	v_add_f32_dpp v42, v42, v42 quad_perm:[2,3,0,1] row_mask:0xf bank_mask:0xf bound_ctrl:1
	v_add_f32_dpp v43, v43, v43 quad_perm:[2,3,0,1] row_mask:0xf bank_mask:0xf bound_ctrl:1
	s_nop 0
	v_add_f32_dpp v42, v42, v42 row_half_mirror row_mask:0xf bank_mask:0xf bound_ctrl:1
	v_add_f32_dpp v43, v43, v43 row_half_mirror row_mask:0xf bank_mask:0xf bound_ctrl:1
	ds_write_b64 v184, v[42:43] offset:32512
	s_waitcnt lgkmcnt(0)
	s_barrier
	s_add_i32 s1, s1, 1
	s_cmpk_eq_i32 s1, 0x100
	s_cbranch_scc0 .Lrk_scan_loop
	s_setprio 0
	s_branch .LBB0_156

; __device__ __forceinline__ unsigned f2bf(float f) { return pk2(f, f) & 0xFFFFu; }
; __device__ __forceinline__ float ldp(const bf16_t* P, size_t row, int col) { return bf2f(P[row * NPROJ + col]); }
; #define LDS_WAIT() asm volatile("s_waitcnt lgkmcnt(0)" ::: "memory")
; __device__ __forceinline__ void rg_block(KP p, int e, int b, int n, LAS unsigned char* lds, const bf16_t* P, bf16_t* YB) {
;     ...
;         float xm3 = t0 >= 3 ? ldp(P, rbase + t0 - 3, ch) : 0.f, xm2 = t0 >= 2 ? ldp(P, rbase + t0 - 2, ch) : 0.f, xm1 = t0 >= 1 ? ldp(P, rbase + t0 - 1, ch) : 0.f;
; #pragma unroll 1
;         for (int tile = 0; tile < 32; ++tile) {
;             const int tb = t0 + tile * 16;
;             float u[16];
; #pragma unroll
;             for (int tt = 0; tt < 16; ++tt) {
;                 const float x = ldp(P, rbase + tb + tt, ch);
;                 u[tt] = cb + cw0 * xm3 + cw1 * xm2 + cw2 * xm1 + cw3 * x; xm3 = xm2; xm2 = xm1; xm1 = x;
;                 U[tt * 72 + lane] = (bf16_t)f2bf(u[tt]);
;             }
;             LDS_WAIT(); asm volatile("" ::: "memory");
;     ...
;                     const float xg = ldp(P, rbase + tb + tt, 512 + ch);
.LBB0_382:
	v_lshl_add_u64 v[20:21], s[50:51], 0, v[14:15]
	v_add_co_u32_e32 v22, vcc, 0x12600000, v20
	s_mov_b32 s12, 0x12603000
	s_nop 0
	v_addc_co_u32_e32 v23, vcc, 0, v21, vcc
	v_add_co_u32_e32 v46, vcc, s64, v20
	s_waitcnt vmcnt(3)
	v_fma_f32 v61, v29, v44, v26
	v_addc_co_u32_e32 v47, vcc, 0, v21, vcc
	global_load_ushort v50, v[22:23], off
	global_load_ushort v51, v[46:47], off offset:2560
	v_add_co_u32_e32 v22, vcc, s12, v20
	s_mov_b32 s12, 0x12606000
	s_nop 0
	v_addc_co_u32_e32 v23, vcc, 0, v21, vcc
	global_load_ushort v52, v[22:23], off offset:1024
	v_add_co_u32_e32 v22, vcc, s65, v20
	v_fma_f32 v58, v29, v0, v26
	s_nop 0
	v_addc_co_u32_e32 v23, vcc, 0, v21, vcc
	global_load_ushort v23, v[22:23], off offset:3584
	v_fma_f32 v22, v29, v45, v26
	s_waitcnt vmcnt(6)
	v_fmac_f32_e32 v22, v30, v44
	v_add_co_u32_e32 v44, vcc, s12, v20
	s_mov_b32 s12, 0x12608000
	s_nop 0
	v_addc_co_u32_e32 v45, vcc, 0, v21, vcc
	global_load_ushort v54, v[44:45], off offset:2048
	v_add_co_u32_e32 v44, vcc, s12, v20
	s_mov_b32 s12, 0x1260b000
	s_nop 0
	v_addc_co_u32_e32 v45, vcc, 0, v21, vcc
	global_load_ushort v55, v[44:45], off offset:512
	v_add_co_u32_e32 v44, vcc, s66, v20
	v_fmac_f32_e32 v61, v30, v0
	s_nop 0
	v_addc_co_u32_e32 v45, vcc, 0, v21, vcc
	global_load_ushort v56, v[44:45], off offset:3072
	v_add_co_u32_e32 v44, vcc, s12, v20
	s_mov_b32 s12, 0x1260d000
	s_nop 0
	v_addc_co_u32_e32 v45, vcc, 0, v21, vcc
	global_load_ushort v62, v[44:45], off offset:1536
	v_add_co_u32_e32 v46, vcc, s12, v20
	s_mov_b32 s12, 0x1260e000
	s_nop 0
	v_addc_co_u32_e32 v47, vcc, 0, v21, vcc
	global_load_ushort v63, v[46:47], off
	v_add_co_u32_e32 v44, vcc, s12, v20
	s_mov_b32 s12, 0x12610000
	s_nop 0
	v_addc_co_u32_e32 v45, vcc, 0, v21, vcc
	v_add_co_u32_e32 v46, vcc, s12, v20
	s_mov_b32 s12, 0x12611000
	s_nop 0
	v_addc_co_u32_e32 v47, vcc, 0, v21, vcc
	global_load_ushort v64, v[44:45], off offset:2560
	v_add_co_u32_e32 v48, vcc, s12, v20
	s_waitcnt vmcnt(11)
	v_fmac_f32_e32 v22, v31, v0
	v_addc_co_u32_e32 v49, vcc, 0, v21, vcc
	global_load_ushort v0, v[46:47], off offset:1024
	s_nop 0
	global_load_ushort v48, v[48:49], off offset:3584
	s_mov_b32 s12, 0x12613000
	v_add_co_u32_e32 v44, vcc, s12, v20
	s_mov_b32 s12, 0x12615000
	s_nop 0
	v_addc_co_u32_e32 v45, vcc, 0, v21, vcc
	global_load_ushort v65, v[44:45], off offset:2048
	v_add_co_u32_e32 v44, vcc, s12, v20
	s_mov_b32 s12, 0x12616000
	s_nop 0
	v_addc_co_u32_e32 v45, vcc, 0, v21, vcc
	s_waitcnt vmcnt(12)
	v_lshlrev_b32_e32 v49, 16, v50
	v_fmac_f32_e32 v22, v32, v49
	s_waitcnt vmcnt(11)
	v_lshlrev_b32_e32 v50, 16, v51
	v_fmac_f32_e32 v61, v31, v49
	v_cvt_pk_bf16_f32 v46, v22, s0
	v_fmac_f32_e32 v61, v32, v50
	ds_write_b16 v33, v46 offset:18432
	v_cvt_pk_bf16_f32 v46, v61, s0
	ds_write_b16 v33, v46 offset:18576
	v_add_co_u32_e32 v46, vcc, s12, v20
	s_mov_b32 s12, 0x12618000
	s_nop 0
	v_addc_co_u32_e32 v47, vcc, 0, v21, vcc
	global_load_ushort v45, v[44:45], off offset:512
	s_nop 0
	global_load_ushort v44, v[46:47], off offset:3072
	v_add_co_u32_e32 v20, vcc, s12, v20
	v_fma_f32 v60, v29, v49, v26
	s_nop 0
	v_addc_co_u32_e32 v21, vcc, 0, v21, vcc
	global_load_ushort v20, v[20:21], off offset:1536
	v_lshl_add_u64 v[118:119], s[50:51], 0, v[16:17]
	v_add_co_u32_e32 v118, vcc, 0x12600d00, v118
	s_nop 1
	v_addc_co_u32_e32 v119, vcc, 0, v119, vcc
	global_load_ushort v100, v[118:119], off offset:-3328
	global_load_ushort v101, v[118:119], off offset:3328
	v_add_co_u32_e32 v118, vcc, 0x3400, v118
	s_nop 1
	v_addc_co_u32_e32 v119, vcc, 0, v119, vcc
	global_load_ushort v102, v[118:119], off offset:-3328
	global_load_ushort v103, v[118:119], off offset:3328
	v_add_co_u32_e32 v118, vcc, 0x3400, v118
	s_nop 1
	v_addc_co_u32_e32 v119, vcc, 0, v119, vcc
	global_load_ushort v104, v[118:119], off offset:-3328
	global_load_ushort v105, v[118:119], off offset:3328
	v_add_co_u32_e32 v118, vcc, 0x3400, v118
	s_nop 1
	v_addc_co_u32_e32 v119, vcc, 0, v119, vcc
	global_load_ushort v106, v[118:119], off offset:-3328
	global_load_ushort v107, v[118:119], off offset:3328
	v_add_co_u32_e32 v118, vcc, 0x3400, v118
	s_nop 1
	v_addc_co_u32_e32 v119, vcc, 0, v119, vcc
	global_load_ushort v108, v[118:119], off offset:-3328
	global_load_ushort v109, v[118:119], off offset:3328
	v_add_co_u32_e32 v118, vcc, 0x3400, v118
	s_nop 1
	v_addc_co_u32_e32 v119, vcc, 0, v119, vcc
	global_load_ushort v110, v[118:119], off offset:-3328
	global_load_ushort v111, v[118:119], off offset:3328
	v_add_co_u32_e32 v118, vcc, 0x3400, v118
	s_nop 1
	v_addc_co_u32_e32 v119, vcc, 0, v119, vcc
	global_load_ushort v112, v[118:119], off offset:-3328
	global_load_ushort v113, v[118:119], off offset:3328
	v_add_co_u32_e32 v118, vcc, 0x3400, v118
	s_nop 1
	v_addc_co_u32_e32 v119, vcc, 0, v119, vcc
	global_load_ushort v114, v[118:119], off offset:-3328
	global_load_ushort v115, v[118:119], off offset:3328
	s_waitcnt vmcnt(29)
	v_lshlrev_b32_e32 v51, 16, v52
	v_fmac_f32_e32 v60, v30, v50
	s_waitcnt vmcnt(28)
	v_lshlrev_b32_e32 v23, 16, v23
	v_fmac_f32_e32 v60, v31, v51
	v_fmac_f32_e32 v60, v32, v23
	v_fma_f32 v59, v29, v50, v26
	v_cvt_pk_bf16_f32 v21, v60, s0
	v_fmac_f32_e32 v59, v30, v51
	ds_write_b16 v33, v21 offset:18864
	s_waitcnt vmcnt(27)
	v_lshlrev_b32_e32 v21, 16, v54
	v_fmac_f32_e32 v59, v31, v23
	v_fmac_f32_e32 v59, v32, v21
	v_fma_f32 v57, v29, v51, v26
	v_cvt_pk_bf16_f32 v46, v59, s0
	v_fmac_f32_e32 v57, v30, v23
	ds_write_b16 v33, v46 offset:19008
	s_waitcnt vmcnt(26)
	v_lshlrev_b32_e32 v46, 16, v55
	v_fmac_f32_e32 v57, v31, v21
	v_fmac_f32_e32 v57, v32, v46
	v_cvt_pk_bf16_f32 v47, v57, s0
	ds_write_b16 v33, v47 offset:19152
	s_waitcnt vmcnt(25)
; #define LAS __attribute__((address_space(3)))
; __device__ __forceinline__ unsigned f2bf(float f) { return pk2(f, f) & 0xFFFFu; }
; __device__ __forceinline__ float sigmoidf_(float x) { return rcp_(1.0f + __expf(-x)); }
; __device__ __forceinline__ float ldp(const bf16_t* P, size_t row, int col) { return bf2f(P[row * NPROJ + col]); }
; __device__ __forceinline__ f32x4 mfma16(bf16x8 a, bf16x8 b, f32x4 c) { return __builtin_amdgcn_mfma_f32_16x16x32_bf16(a, b, c, 0, 0, 0); }
; #define LDS_WAIT() asm volatile("s_waitcnt lgkmcnt(0)" ::: "memory")
; __device__ __forceinline__ void rg_block(KP p, int e, int b, int n, LAS unsigned char* lds, const bf16_t* P, bf16_t* YB) {
;     ...
;             for (int tt = 0; tt < 16; ++tt) {
;                 const float x = ldp(P, rbase + tb + tt, ch);
;                 u[tt] = cb + cw0 * xm3 + cw1 * xm2 + cw2 * xm1 + cw3 * x; xm3 = xm2; xm2 = xm1; xm1 = x;
;                 U[tt * 72 + lane] = (bf16_t)f2bf(u[tt]);
;             }
;             LDS_WAIT(); asm volatile("" ::: "memory");
; #pragma unroll
;             for (int ct = 0; ct < 4; ++ct) {
;                 f32x4 ca = {0.f, 0.f, 0.f, 0.f}, cx = {0.f, 0.f, 0.f, 0.f};
; #pragma unroll
;                 for (int kb = 0; kb < 2; ++kb) {
;                     const bf16x8 af = *(const LAS bf16x8*)(U + fr * 72 + kb * 32 + fq * 8);
;                     const bf16x8 b1 = *(const LAS bf16x8*)(WaT + (ct * 16 + fr) * 72 + kb * 32 + fq * 8);
;                     const bf16x8 b2 = *(const LAS bf16x8*)(WxT + (ct * 16 + fr) * 72 + kb * 32 + fq * 8);
;                     ca = mfma16(af, b1, ca); cx = mfma16(af, b2, cx);
;                 }
; #pragma unroll
;                 for (int jj = 0; jj < 4; ++jj) { G0[(fq * 4 + jj) * 68 + ct * 16 + fr] = ca[jj]; G1[(fq * 4 + jj) * 68 + ct * 16 + fr] = cx[jj]; }
;             }
;             LDS_WAIT(); asm volatile("" ::: "memory");
; #pragma unroll
;             for (int tt = 0; tt < 16; ++tt) {
;                 const float r = sigmoidf_(G0[tt * 68 + lane] + ba), ig = sigmoidf_(G1[tt * 68 + lane] + bx);
;                 const float log_a = -sp8 * r;
;                 const float a = __expf(log_a);
;                 const float bb = __builtin_amdgcn_sqrtf(fmaxf(1.0f - a * a, 0.f)) * (ig * u[tt]);
;                 h = a * h + bb;
	v_lshlrev_b32_e32 v47, 16, v56
	v_fma_f32 v56, v29, v23, v26
	v_fmac_f32_e32 v56, v30, v21
	v_fmac_f32_e32 v56, v31, v46
	v_fmac_f32_e32 v56, v32, v47
	v_fma_f32 v55, v29, v21, v26
	v_cvt_pk_bf16_f32 v23, v56, s0
	v_fmac_f32_e32 v55, v30, v46
	ds_write_b16 v33, v23 offset:19296
	s_waitcnt vmcnt(24)
	v_lshlrev_b32_e32 v23, 16, v62
	v_fmac_f32_e32 v55, v31, v47
	v_fmac_f32_e32 v55, v32, v23
	v_fma_f32 v54, v29, v46, v26
	v_cvt_pk_bf16_f32 v21, v55, s0
	v_fmac_f32_e32 v54, v30, v47
	v_fmac_f32_e32 v58, v30, v49
	ds_write_b16 v33, v21 offset:19440
	s_waitcnt vmcnt(23)
	v_lshlrev_b32_e32 v21, 16, v63
	v_fmac_f32_e32 v54, v31, v23
	v_fmac_f32_e32 v58, v31, v50
	v_fmac_f32_e32 v54, v32, v21
	v_fmac_f32_e32 v58, v32, v51
	v_cvt_pk_bf16_f32 v46, v54, s0
	v_fma_f32 v51, v29, v23, v26
	ds_write_b16 v33, v46 offset:19584
	s_waitcnt vmcnt(22)
	v_lshlrev_b32_e32 v46, 16, v64
	v_fmac_f32_e32 v51, v30, v21
	v_cvt_pk_bf16_f32 v52, v58, s0
	s_waitcnt vmcnt(21)
	v_lshlrev_b32_e32 v0, 16, v0
	v_fmac_f32_e32 v51, v31, v46
	ds_write_b16 v33, v52 offset:18720
	v_fma_f32 v52, v29, v47, v26
	v_fmac_f32_e32 v51, v32, v0
	v_fma_f32 v50, v29, v21, v26
	v_fmac_f32_e32 v52, v30, v23
	v_cvt_pk_bf16_f32 v23, v51, s0
	v_fmac_f32_e32 v50, v30, v46
	v_fmac_f32_e32 v52, v31, v21
	ds_write_b16 v33, v23 offset:19872
	s_waitcnt vmcnt(20)
	v_lshlrev_b32_e32 v23, 16, v48
	v_fmac_f32_e32 v50, v31, v0
	v_fmac_f32_e32 v52, v32, v46
	v_fmac_f32_e32 v50, v32, v23
	v_fma_f32 v49, v29, v46, v26
	v_cvt_pk_bf16_f32 v47, v52, s0
	v_cvt_pk_bf16_f32 v21, v50, s0
	v_fmac_f32_e32 v49, v30, v0
	v_fma_f32 v48, v29, v0, v26
	ds_write_b16 v33, v47 offset:19728
	ds_write_b16 v33, v21 offset:20016
	s_waitcnt vmcnt(19)
	v_lshlrev_b32_e32 v21, 16, v65
	v_fmac_f32_e32 v49, v31, v23
	v_fmac_f32_e32 v48, v30, v23
	v_fma_f32 v47, v29, v23, v26
	v_fmac_f32_e32 v49, v32, v21
	v_fmac_f32_e32 v48, v31, v21
	s_waitcnt vmcnt(18)
	v_lshlrev_b32_e32 v45, 16, v45
	v_fmac_f32_e32 v47, v30, v21
	v_cvt_pk_bf16_f32 v46, v49, s0
	s_waitcnt vmcnt(17)
	v_lshlrev_b32_e32 v44, 16, v44
	v_fmac_f32_e32 v48, v32, v45
	v_fmac_f32_e32 v47, v31, v45
	ds_write_b16 v33, v46 offset:20160
	v_cvt_pk_bf16_f32 v0, v48, s0
	v_fmac_f32_e32 v47, v32, v44
	v_fma_f32 v46, v29, v21, v26
	ds_write_b16 v33, v0 offset:20304
	v_cvt_pk_bf16_f32 v0, v47, s0
	v_fmac_f32_e32 v46, v30, v45
	ds_write_b16 v33, v0 offset:20448
	s_waitcnt vmcnt(16)
	v_lshlrev_b32_e32 v0, 16, v20
	v_fmac_f32_e32 v46, v31, v44
	v_fmac_f32_e32 v46, v32, v0
	v_cvt_pk_bf16_f32 v20, v46, s0
	ds_write_b16 v33, v20 offset:20592
	s_waitcnt lgkmcnt(0)
	ds_read_b128 v[62:65], v34 offset:18432
	ds_read_b128 v[66:69], v37
	ds_read_b128 v[70:73], v34 offset:18496
	ds_read_b128 v[74:77], v37 offset:64
	ds_read_b128 v[78:81], v37 offset:9216
	ds_read_b128 v[82:85], v37 offset:9280
	s_waitcnt lgkmcnt(4)
	v_mfma_f32_16x16x32_bf16 v[66:69], v[62:65], v[66:69], 0
	v_add_u32_e32 v20, 0x5000, v38
	s_mov_b64 s[12:13], -1
	s_and_b64 vcc, exec, s[14:15]
	s_waitcnt lgkmcnt(1)
	v_mfma_f32_16x16x32_bf16 v[78:81], v[62:65], v[78:81], 0
	v_mfma_f32_16x16x32_bf16 v[66:69], v[70:73], v[74:77], v[66:69]
	s_waitcnt lgkmcnt(0)
	v_mfma_f32_16x16x32_bf16 v[74:77], v[70:73], v[82:85], v[78:81]
	s_nop 5
	ds_write_b32 v38, v66 offset:20736
	s_nop 0
	ds_write_b32 v38, v74 offset:25088
	ds_write2_b32 v20, v67, v68 offset0:132 offset1:200
	v_add_u32_e32 v20, 0x6200, v38
	ds_write2_b32 v20, v75, v76 offset0:68 offset1:136
	ds_write_b32 v38, v69 offset:21552
	ds_write_b32 v38, v77 offset:25904
	ds_read_b128 v[66:69], v37 offset:2304
	ds_read_b128 v[74:77], v37 offset:2368
	ds_read_b128 v[78:81], v37 offset:11520
	ds_read_b128 v[82:85], v37 offset:11584
	s_waitcnt lgkmcnt(3)
	v_mfma_f32_16x16x32_bf16 v[66:69], v[62:65], v[66:69], 0
	v_add_u32_e32 v20, 0x5000, v39
	s_waitcnt lgkmcnt(1)
	v_mfma_f32_16x16x32_bf16 v[78:81], v[62:65], v[78:81], 0
	v_mfma_f32_16x16x32_bf16 v[66:69], v[70:73], v[74:77], v[66:69]
	s_waitcnt lgkmcnt(0)
	v_mfma_f32_16x16x32_bf16 v[74:77], v[70:73], v[82:85], v[78:81]
	s_nop 5
	ds_write_b32 v38, v66 offset:20800
	s_nop 0
	ds_write_b32 v38, v74 offset:25152
	ds_write2_b32 v20, v67, v68 offset0:132 offset1:200
	v_add_u32_e32 v20, 0x6200, v39
	ds_write2_b32 v20, v75, v76 offset0:68 offset1:136
	ds_write_b32 v39, v69 offset:21552
	ds_write_b32 v39, v77 offset:25904
	ds_read_b128 v[66:69], v37 offset:4608
	ds_read_b128 v[74:77], v37 offset:4672
	ds_read_b128 v[78:81], v37 offset:13824
	ds_read_b128 v[82:85], v37 offset:13888
	s_waitcnt lgkmcnt(3)
	v_mfma_f32_16x16x32_bf16 v[66:69], v[62:65], v[66:69], 0
	v_add_u32_e32 v20, 0x5000, v40
	s_waitcnt lgkmcnt(1)
	v_mfma_f32_16x16x32_bf16 v[78:81], v[62:65], v[78:81], 0
	v_mfma_f32_16x16x32_bf16 v[66:69], v[70:73], v[74:77], v[66:69]
	s_waitcnt lgkmcnt(0)
	v_mfma_f32_16x16x32_bf16 v[74:77], v[70:73], v[82:85], v[78:81]
	s_nop 5
	ds_write_b32 v38, v66 offset:20864
	s_nop 0
	ds_write_b32 v38, v74 offset:25216
	ds_write2_b32 v20, v67, v68 offset0:132 offset1:200
	v_add_u32_e32 v20, 0x6200, v40
	ds_write2_b32 v20, v75, v76 offset0:68 offset1:136
	ds_write_b32 v40, v69 offset:21552
	ds_write_b32 v40, v77 offset:25904
	ds_read_b128 v[66:69], v37 offset:6912
	ds_read_b128 v[74:77], v37 offset:6976
	ds_read_b128 v[78:81], v37 offset:16128
	ds_read_b128 v[82:85], v37 offset:16192
	s_waitcnt lgkmcnt(3)
	v_mfma_f32_16x16x32_bf16 v[66:69], v[62:65], v[66:69], 0
	v_add_u32_e32 v20, 0x5000, v41
	s_waitcnt lgkmcnt(1)
	v_mfma_f32_16x16x32_bf16 v[62:65], v[62:65], v[78:81], 0
	v_mfma_f32_16x16x32_bf16 v[66:69], v[70:73], v[74:77], v[66:69]
	s_waitcnt lgkmcnt(0)
	v_mfma_f32_16x16x32_bf16 v[62:65], v[70:73], v[82:85], v[62:65]
	s_nop 5
	ds_write_b32 v38, v66 offset:20928
	s_nop 0
	ds_write_b32 v38, v62 offset:25280
	ds_write2_b32 v20, v67, v68 offset0:132 offset1:200
	v_add_u32_e32 v20, 0x6200, v41
	ds_write2_b32 v20, v63, v64 offset0:68 offset1:136
	ds_write_b32 v41, v69 offset:21552
	ds_write_b32 v41, v65 offset:25904
	s_waitcnt lgkmcnt(0)
	ds_read2st64_b32 v[20:21], v42 offset0:81 offset1:98
	s_waitcnt lgkmcnt(0)
	v_add_f32_e32 v20, v27, v20
	v_mul_f32_e32 v20, 0xbfb8aa3b, v20
	v_exp_f32_e32 v20, v20
	v_add_f32_e32 v21, v28, v21
	v_mul_f32_e32 v21, 0xbfb8aa3b, v21
	v_exp_f32_e32 v21, v21
	v_add_f32_e32 v20, 1.0, v20
	v_rcp_f32_e32 v20, v20
	s_nop 0
	v_mul_f32_e32 v20, v35, v20
	v_mul_f32_e32 v20, 0x3fb8aa3b, v20
	v_exp_f32_e32 v62, v20
	v_add_f32_e32 v20, 1.0, v21
	v_rcp_f32_e32 v20, v20
	v_fma_f32 v21, -v62, v62, 1.0
	v_max_f32_e32 v21, 0, v21
	v_sqrt_f32_e32 v21, v21
	v_mul_f32_e32 v20, v22, v20
	v_lshl_add_u64 v[22:23], s[50:51], 0, v[16:17]
	v_mul_f32_e32 v63, v20, v21
	v_fmac_f32_e32 v63, v53, v62
	v_lshl_add_u64 v[20:21], s[50:51], 0, v[18:19]
	s_cbranch_vccz .LBB0_384
; __device__ __forceinline__ unsigned f2bf(float f) { return pk2(f, f) & 0xFFFFu; }
; __device__ __forceinline__ float rcp_(float x) { return __builtin_amdgcn_rcpf(x); }
; __device__ __forceinline__ float ldp(const bf16_t* P, size_t row, int col) { return bf2f(P[row * NPROJ + col]); }
; __device__ __forceinline__ float tanhf_(float z) { return 1.0f - 2.0f * rcp_(1.0f + __expf(2.0f * z)); }
; __device__ __forceinline__ float gelu_tanh_(float x) { return 0.5f * x * (1.0f + tanhf_(0.7978845608028654f * (x + 0.044715f * x * x * x))); }
; __device__ __forceinline__ void rg_block(KP p, int e, int b, int n, LAS unsigned char* lds, const bf16_t* P, bf16_t* YB) {
;     ...
;                 else {
;                     const float xg = ldp(P, rbase + tb + tt, 512 + ch);
;                     YB[(rbase + tb + tt) * DM + ch] = (bf16_t)f2bf(h * gelu_tanh_(xg));
	v_add_co_u32_e32 v64, vcc, 0x12600000, v22
	s_mov_b64 s[12:13], 0
	s_nop 0
	v_addc_co_u32_e32 v65, vcc, 0, v23, vcc
	s_waitcnt vmcnt(15)
	v_lshlrev_b32_e32 v53, 16, v100
	v_mul_f32_e32 v65, 0x3d372713, v53
	v_mul_f32_e32 v65, v65, v53
	v_mul_f32_e32 v64, 0.5, v53
	v_fmac_f32_e32 v53, v65, v53
	v_mul_f32_e32 v53, 0x3f4c422a, v53
	v_add_f32_e32 v53, v53, v53
	v_mul_f32_e32 v53, 0x3fb8aa3b, v53
	v_exp_f32_e32 v53, v53
	s_nop 0
	v_add_f32_e32 v53, 1.0, v53
	v_rcp_f32_e32 v53, v53
	s_nop 0
	v_fma_f32 v53, v53, -2.0, 1.0
	v_add_f32_e32 v53, 1.0, v53
	v_mul_f32_e32 v53, v64, v53
	v_mul_f32_e32 v53, v63, v53
	v_add_co_u32_e32 v64, vcc, 0xa600000, v20
	v_cvt_pk_bf16_f32 v53, v53, s0
	s_nop 0
	v_addc_co_u32_e32 v65, vcc, 0, v21, vcc
	global_store_short v[64:65], v53, off

; __device__ __forceinline__ unsigned f2bf(float f) { return pk2(f, f) & 0xFFFFu; }
; __device__ __forceinline__ float sigmoidf_(float x) { return rcp_(1.0f + __expf(-x)); }
; __device__ __forceinline__ float gelu_tanh_(float x) { return 0.5f * x * (1.0f + tanhf_(0.7978845608028654f * (x + 0.044715f * x * x * x))); }
; __device__ __forceinline__ float ldp(const bf16_t* P, size_t row, int col) { return bf2f(P[row * NPROJ + col]); }
; __device__ __forceinline__ void rg_block(KP p, int e, int b, int n, LAS unsigned char* lds, const bf16_t* P, bf16_t* YB) {
;     ...
;             for (int tt = 0; tt < 16; ++tt) {
;                 const float r = sigmoidf_(G0[tt * 68 + lane] + ba), ig = sigmoidf_(G1[tt * 68 + lane] + bx);
;                 const float log_a = -sp8 * r;
;                 const float a = __expf(log_a);
;                 const float bb = __builtin_amdgcn_sqrtf(fmaxf(1.0f - a * a, 0.f)) * (ig * u[tt]);
;                 h = a * h + bb;
;                 if (pass == 0) aprod *= a;
;                 else {
;                     const float xg = ldp(P, rbase + tb + tt, 512 + ch);
;                     YB[(rbase + tb + tt) * DM + ch] = (bf16_t)f2bf(h * gelu_tanh_(xg));
.LBB0_386:
	v_add_u32_e32 v53, 16, v42
	ds_read2st64_b32 v[64:65], v53 offset0:82 offset1:99
	s_mov_b64 s[16:17], -1
	s_andn2_b64 vcc, exec, s[14:15]
	s_waitcnt lgkmcnt(0)
	v_add_f32_e32 v53, v27, v64
	v_mul_f32_e32 v53, 0xbfb8aa3b, v53
	v_exp_f32_e32 v53, v53
	v_add_f32_e32 v62, v28, v65
	v_mul_f32_e32 v62, 0xbfb8aa3b, v62
	v_exp_f32_e32 v62, v62
	v_add_f32_e32 v53, 1.0, v53
	v_rcp_f32_e32 v53, v53
	v_add_f32_e32 v62, 1.0, v62
	v_rcp_f32_e32 v64, v62
	v_mul_f32_e32 v53, v35, v53
	v_mul_f32_e32 v53, 0x3fb8aa3b, v53
	v_exp_f32_e32 v62, v53
	v_mul_f32_e32 v61, v61, v64
	v_fma_f32 v53, -v62, v62, 1.0
	v_max_f32_e32 v53, 0, v53
	v_sqrt_f32_e32 v53, v53
	s_nop 0
	v_mul_f32_e32 v53, v61, v53
	v_cndmask_b32_e64 v61, 0, 1, s[14:15]
	v_fmac_f32_e32 v53, v63, v62
	v_cmp_ne_u32_e64 s[12:13], 1, v61
	s_cbranch_vccnz .LBB0_388
	v_add_co_u32_e32 v64, vcc, 0x12601000, v22
	s_mov_b64 s[16:17], 0
	s_nop 0
	v_addc_co_u32_e32 v65, vcc, 0, v23, vcc
	s_waitcnt vmcnt(15)
	v_lshlrev_b32_e32 v61, 16, v101
	v_mul_f32_e32 v64, 0x3d372713, v61
	v_mul_f32_e32 v64, v64, v61
	v_mul_f32_e32 v63, 0.5, v61
	v_fmac_f32_e32 v61, v64, v61
	v_mul_f32_e32 v61, 0x3f4c422a, v61
	v_add_f32_e32 v61, v61, v61
	v_mul_f32_e32 v61, 0x3fb8aa3b, v61
	v_exp_f32_e32 v61, v61
	v_add_co_u32_e32 v64, vcc, 0xa600000, v20
	v_add_f32_e32 v61, 1.0, v61
	v_rcp_f32_e32 v61, v61
	v_addc_co_u32_e32 v65, vcc, 0, v21, vcc
	v_fma_f32 v61, v61, -2.0, 1.0
	v_add_f32_e32 v61, 1.0, v61
	v_mul_f32_e32 v61, v63, v61
	v_mul_f32_e32 v61, v53, v61
	v_cvt_pk_bf16_f32 v61, v61, s0
	global_store_short v[64:65], v61, off offset:2048

; __device__ __forceinline__ unsigned f2bf(float f) { return pk2(f, f) & 0xFFFFu; }
; __device__ __forceinline__ float sigmoidf_(float x) { return rcp_(1.0f + __expf(-x)); }
; __device__ __forceinline__ float gelu_tanh_(float x) { return 0.5f * x * (1.0f + tanhf_(0.7978845608028654f * (x + 0.044715f * x * x * x))); }
; __device__ __forceinline__ float ldp(const bf16_t* P, size_t row, int col) { return bf2f(P[row * NPROJ + col]); }
; __device__ __forceinline__ void rg_block(KP p, int e, int b, int n, LAS unsigned char* lds, const bf16_t* P, bf16_t* YB) {
;     ...
;             for (int tt = 0; tt < 16; ++tt) {
;                 const float r = sigmoidf_(G0[tt * 68 + lane] + ba), ig = sigmoidf_(G1[tt * 68 + lane] + bx);
;                 const float log_a = -sp8 * r;
;                 const float a = __expf(log_a);
;                 const float bb = __builtin_amdgcn_sqrtf(fmaxf(1.0f - a * a, 0.f)) * (ig * u[tt]);
;                 h = a * h + bb;
;                 if (pass == 0) aprod *= a;
;                 else {
;                     const float xg = ldp(P, rbase + tb + tt, 512 + ch);
;                     YB[(rbase + tb + tt) * DM + ch] = (bf16_t)f2bf(h * gelu_tanh_(xg));
.LBB0_390:
	v_add_u32_e32 v61, 32, v42
	ds_read2st64_b32 v[62:63], v61 offset0:83 offset1:100
	s_and_b64 vcc, exec, s[12:13]
	s_mov_b64 s[16:17], -1
	s_waitcnt lgkmcnt(0)
	v_add_f32_e32 v61, v27, v62
	v_mul_f32_e32 v61, 0xbfb8aa3b, v61
	v_exp_f32_e32 v61, v61
	v_add_f32_e32 v62, v28, v63
	v_mul_f32_e32 v62, 0xbfb8aa3b, v62
	v_exp_f32_e32 v62, v62
	v_add_f32_e32 v61, 1.0, v61
	v_rcp_f32_e32 v61, v61
	v_add_f32_e32 v62, 1.0, v62
	v_rcp_f32_e32 v62, v62
	v_mul_f32_e32 v61, v35, v61
	v_mul_f32_e32 v61, 0x3fb8aa3b, v61
	v_exp_f32_e32 v61, v61
	v_mul_f32_e32 v58, v58, v62
	v_fma_f32 v63, -v61, v61, 1.0
	v_max_f32_e32 v63, 0, v63
	v_sqrt_f32_e32 v63, v63
	s_nop 0
	v_mul_f32_e32 v58, v58, v63
	v_fmac_f32_e32 v58, v53, v61
	s_cbranch_vccnz .LBB0_392
	v_add_co_u32_e32 v62, vcc, 0x12603000, v22
	s_mov_b64 s[16:17], 0
	s_nop 0
	v_addc_co_u32_e32 v63, vcc, 0, v23, vcc
	s_waitcnt vmcnt(15)
	v_lshlrev_b32_e32 v53, 16, v102
	v_mul_f32_e32 v63, 0x3d372713, v53
	v_mul_f32_e32 v63, v63, v53
	v_mul_f32_e32 v62, 0.5, v53
	v_fmac_f32_e32 v53, v63, v53
	v_mul_f32_e32 v53, 0x3f4c422a, v53
	v_add_f32_e32 v53, v53, v53
	v_mul_f32_e32 v53, 0x3fb8aa3b, v53
	v_exp_f32_e32 v53, v53
	s_nop 0
	v_add_f32_e32 v53, 1.0, v53
	v_rcp_f32_e32 v53, v53
	s_nop 0
	v_fma_f32 v53, v53, -2.0, 1.0
	v_add_f32_e32 v53, 1.0, v53
	v_mul_f32_e32 v53, v62, v53
	v_mul_f32_e32 v53, v58, v53
	v_add_co_u32_e32 v62, vcc, 0xa601000, v20
	v_cvt_pk_bf16_f32 v53, v53, s0
	s_nop 0
	v_addc_co_u32_e32 v63, vcc, 0, v21, vcc
	global_store_short v[62:63], v53, off

; __device__ __forceinline__ unsigned f2bf(float f) { return pk2(f, f) & 0xFFFFu; }
; __device__ __forceinline__ float sigmoidf_(float x) { return rcp_(1.0f + __expf(-x)); }
; __device__ __forceinline__ float gelu_tanh_(float x) { return 0.5f * x * (1.0f + tanhf_(0.7978845608028654f * (x + 0.044715f * x * x * x))); }
; __device__ __forceinline__ float ldp(const bf16_t* P, size_t row, int col) { return bf2f(P[row * NPROJ + col]); }
; __device__ __forceinline__ void rg_block(KP p, int e, int b, int n, LAS unsigned char* lds, const bf16_t* P, bf16_t* YB) {
;     ...
;             for (int tt = 0; tt < 16; ++tt) {
;                 const float r = sigmoidf_(G0[tt * 68 + lane] + ba), ig = sigmoidf_(G1[tt * 68 + lane] + bx);
;                 const float log_a = -sp8 * r;
;                 const float a = __expf(log_a);
;                 const float bb = __builtin_amdgcn_sqrtf(fmaxf(1.0f - a * a, 0.f)) * (ig * u[tt]);
;                 h = a * h + bb;
;                 if (pass == 0) aprod *= a;
;                 else {
;                     const float xg = ldp(P, rbase + tb + tt, 512 + ch);
;                     YB[(rbase + tb + tt) * DM + ch] = (bf16_t)f2bf(h * gelu_tanh_(xg));
.LBB0_394:
	v_add_u32_e32 v53, 48, v42
	ds_read2st64_b32 v[62:63], v53 offset0:84 offset1:101
	s_and_b64 vcc, exec, s[12:13]
	s_mov_b64 s[16:17], -1
	s_waitcnt lgkmcnt(0)
	v_add_f32_e32 v53, v27, v62
	v_mul_f32_e32 v53, 0xbfb8aa3b, v53
	v_exp_f32_e32 v53, v53
	v_add_f32_e32 v61, v28, v63
	v_mul_f32_e32 v61, 0xbfb8aa3b, v61
	v_exp_f32_e32 v62, v61
	v_add_f32_e32 v53, 1.0, v53
	v_rcp_f32_e32 v53, v53
	s_nop 0
	v_mul_f32_e32 v53, v35, v53
	v_mul_f32_e32 v53, 0x3fb8aa3b, v53
	v_exp_f32_e32 v61, v53
	v_add_f32_e32 v53, 1.0, v62
	v_rcp_f32_e32 v53, v53
	v_fma_f32 v62, -v61, v61, 1.0
	v_max_f32_e32 v62, 0, v62
	v_sqrt_f32_e32 v62, v62
	v_mul_f32_e32 v53, v60, v53
	v_mul_f32_e32 v53, v53, v62
	v_fmac_f32_e32 v53, v58, v61
	s_cbranch_vccnz .LBB0_396
	v_add_co_u32_e32 v62, vcc, 0x12604000, v22
	s_mov_b64 s[16:17], 0
	s_nop 0
	v_addc_co_u32_e32 v63, vcc, 0, v23, vcc
	s_waitcnt vmcnt(15)
	v_lshlrev_b32_e32 v58, 16, v103
	v_mul_f32_e32 v62, 0x3d372713, v58
	v_mul_f32_e32 v62, v62, v58
	v_mul_f32_e32 v60, 0.5, v58
	v_fmac_f32_e32 v58, v62, v58
	v_mul_f32_e32 v58, 0x3f4c422a, v58
	v_add_f32_e32 v58, v58, v58
	v_mul_f32_e32 v58, 0x3fb8aa3b, v58
	v_exp_f32_e32 v58, v58
	v_add_co_u32_e32 v62, vcc, 0xa601000, v20
	v_add_f32_e32 v58, 1.0, v58
	v_rcp_f32_e32 v58, v58
	v_addc_co_u32_e32 v63, vcc, 0, v21, vcc
	v_fma_f32 v58, v58, -2.0, 1.0
	v_add_f32_e32 v58, 1.0, v58
	v_mul_f32_e32 v58, v60, v58
	v_mul_f32_e32 v58, v53, v58
	v_cvt_pk_bf16_f32 v58, v58, s0
	global_store_short v[62:63], v58, off offset:2048

; __device__ __forceinline__ unsigned f2bf(float f) { return pk2(f, f) & 0xFFFFu; }
; __device__ __forceinline__ float sigmoidf_(float x) { return rcp_(1.0f + __expf(-x)); }
; __device__ __forceinline__ float gelu_tanh_(float x) { return 0.5f * x * (1.0f + tanhf_(0.7978845608028654f * (x + 0.044715f * x * x * x))); }
; __device__ __forceinline__ float ldp(const bf16_t* P, size_t row, int col) { return bf2f(P[row * NPROJ + col]); }
; __device__ __forceinline__ void rg_block(KP p, int e, int b, int n, LAS unsigned char* lds, const bf16_t* P, bf16_t* YB) {
;     ...
;             for (int tt = 0; tt < 16; ++tt) {
;                 const float r = sigmoidf_(G0[tt * 68 + lane] + ba), ig = sigmoidf_(G1[tt * 68 + lane] + bx);
;                 const float log_a = -sp8 * r;
;                 const float a = __expf(log_a);
;                 const float bb = __builtin_amdgcn_sqrtf(fmaxf(1.0f - a * a, 0.f)) * (ig * u[tt]);
;                 h = a * h + bb;
;                 if (pass == 0) aprod *= a;
;                 else {
;                     const float xg = ldp(P, rbase + tb + tt, 512 + ch);
;                     YB[(rbase + tb + tt) * DM + ch] = (bf16_t)f2bf(h * gelu_tanh_(xg));
.LBB0_398:
	v_add_u32_e32 v58, 64, v42
	ds_read2st64_b32 v[60:61], v58 offset0:85 offset1:102
	s_and_b64 vcc, exec, s[12:13]
	s_mov_b64 s[16:17], -1
	s_waitcnt lgkmcnt(0)
	v_add_f32_e32 v58, v27, v60
	v_mul_f32_e32 v58, 0xbfb8aa3b, v58
	v_exp_f32_e32 v58, v58
	v_add_f32_e32 v60, v28, v61
	v_mul_f32_e32 v60, 0xbfb8aa3b, v60
	v_exp_f32_e32 v61, v60
	v_add_f32_e32 v58, 1.0, v58
	v_rcp_f32_e32 v58, v58
	s_nop 0
	v_mul_f32_e32 v58, v35, v58
	v_mul_f32_e32 v58, 0x3fb8aa3b, v58
	v_exp_f32_e32 v60, v58
	v_add_f32_e32 v58, 1.0, v61
	v_rcp_f32_e32 v58, v58
	v_fma_f32 v61, -v60, v60, 1.0
	v_max_f32_e32 v61, 0, v61
	v_sqrt_f32_e32 v61, v61
	v_mul_f32_e32 v58, v59, v58
	v_mul_f32_e32 v58, v58, v61
	v_fmac_f32_e32 v58, v53, v60
	s_cbranch_vccnz .LBB0_400
	v_add_co_u32_e32 v62, vcc, 0x12606000, v22
	s_mov_b64 s[16:17], 0
	s_nop 0
	v_addc_co_u32_e32 v63, vcc, 0, v23, vcc
	v_add_co_u32_e32 v62, vcc, 0xa602000, v20
	s_waitcnt vmcnt(15)
	v_lshlrev_b32_e32 v53, 16, v104
	v_mul_f32_e32 v61, 0x3d372713, v53
	v_mul_f32_e32 v61, v61, v53
	v_mul_f32_e32 v59, 0.5, v53
	v_fmac_f32_e32 v53, v61, v53
	v_mul_f32_e32 v53, 0x3f4c422a, v53
	v_add_f32_e32 v53, v53, v53
	v_mul_f32_e32 v53, 0x3fb8aa3b, v53
	v_exp_f32_e32 v53, v53
	v_addc_co_u32_e32 v63, vcc, 0, v21, vcc
	v_add_f32_e32 v53, 1.0, v53
	v_rcp_f32_e32 v53, v53
	s_nop 0
	v_fma_f32 v53, v53, -2.0, 1.0
	v_add_f32_e32 v53, 1.0, v53
	v_mul_f32_e32 v53, v59, v53
	v_mul_f32_e32 v53, v58, v53
	v_cvt_pk_bf16_f32 v53, v53, s0
	global_store_short v[62:63], v53, off

; __device__ __forceinline__ unsigned f2bf(float f) { return pk2(f, f) & 0xFFFFu; }
; __device__ __forceinline__ float sigmoidf_(float x) { return rcp_(1.0f + __expf(-x)); }
; __device__ __forceinline__ float gelu_tanh_(float x) { return 0.5f * x * (1.0f + tanhf_(0.7978845608028654f * (x + 0.044715f * x * x * x))); }
; __device__ __forceinline__ float ldp(const bf16_t* P, size_t row, int col) { return bf2f(P[row * NPROJ + col]); }
; __device__ __forceinline__ void rg_block(KP p, int e, int b, int n, LAS unsigned char* lds, const bf16_t* P, bf16_t* YB) {
;     ...
;             for (int tt = 0; tt < 16; ++tt) {
;                 const float r = sigmoidf_(G0[tt * 68 + lane] + ba), ig = sigmoidf_(G1[tt * 68 + lane] + bx);
;                 const float log_a = -sp8 * r;
;                 const float a = __expf(log_a);
;                 const float bb = __builtin_amdgcn_sqrtf(fmaxf(1.0f - a * a, 0.f)) * (ig * u[tt]);
;                 h = a * h + bb;
;                 if (pass == 0) aprod *= a;
;                 else {
;                     const float xg = ldp(P, rbase + tb + tt, 512 + ch);
;                     YB[(rbase + tb + tt) * DM + ch] = (bf16_t)f2bf(h * gelu_tanh_(xg));
.LBB0_402:
	v_add_u32_e32 v53, 0x50, v42
	ds_read2st64_b32 v[60:61], v53 offset0:86 offset1:103
	s_and_b64 vcc, exec, s[12:13]
	s_mov_b64 s[16:17], -1
	s_waitcnt lgkmcnt(0)
	v_add_f32_e32 v53, v27, v60
	v_mul_f32_e32 v53, 0xbfb8aa3b, v53
	v_exp_f32_e32 v53, v53
	v_add_f32_e32 v59, v28, v61
	v_mul_f32_e32 v59, 0xbfb8aa3b, v59
	v_exp_f32_e32 v60, v59
	v_add_f32_e32 v53, 1.0, v53
	v_rcp_f32_e32 v53, v53
	s_nop 0
	v_mul_f32_e32 v53, v35, v53
	v_mul_f32_e32 v53, 0x3fb8aa3b, v53
	v_exp_f32_e32 v59, v53
	v_add_f32_e32 v53, 1.0, v60
	v_rcp_f32_e32 v53, v53
	v_fma_f32 v60, -v59, v59, 1.0
	v_max_f32_e32 v60, 0, v60
	v_sqrt_f32_e32 v60, v60
	v_mul_f32_e32 v53, v57, v53
	v_mul_f32_e32 v53, v53, v60
	v_fmac_f32_e32 v53, v58, v59
	s_cbranch_vccnz .LBB0_404
	v_add_co_u32_e32 v60, vcc, 0x12608000, v22
	s_mov_b64 s[16:17], 0
	s_nop 0
	v_addc_co_u32_e32 v61, vcc, 0, v23, vcc
	s_waitcnt vmcnt(15)
	v_lshlrev_b32_e32 v57, 16, v105
	v_mul_f32_e32 v60, 0x3d372713, v57
	v_mul_f32_e32 v60, v60, v57
	v_mul_f32_e32 v58, 0.5, v57
	v_fmac_f32_e32 v57, v60, v57
	v_mul_f32_e32 v57, 0x3f4c422a, v57
	v_add_f32_e32 v57, v57, v57
	v_mul_f32_e32 v57, 0x3fb8aa3b, v57
	v_exp_f32_e32 v57, v57
	v_add_co_u32_e32 v60, vcc, 0xa602000, v20
	v_add_f32_e32 v57, 1.0, v57
	v_rcp_f32_e32 v57, v57
	v_addc_co_u32_e32 v61, vcc, 0, v21, vcc
	v_fma_f32 v57, v57, -2.0, 1.0
	v_add_f32_e32 v57, 1.0, v57
	v_mul_f32_e32 v57, v58, v57
	v_mul_f32_e32 v57, v53, v57
	v_cvt_pk_bf16_f32 v57, v57, s0
	global_store_short v[60:61], v57, off offset:2048

; __device__ __forceinline__ unsigned f2bf(float f) { return pk2(f, f) & 0xFFFFu; }
; __device__ __forceinline__ float sigmoidf_(float x) { return rcp_(1.0f + __expf(-x)); }
; __device__ __forceinline__ float gelu_tanh_(float x) { return 0.5f * x * (1.0f + tanhf_(0.7978845608028654f * (x + 0.044715f * x * x * x))); }
; __device__ __forceinline__ float ldp(const bf16_t* P, size_t row, int col) { return bf2f(P[row * NPROJ + col]); }
; __device__ __forceinline__ void rg_block(KP p, int e, int b, int n, LAS unsigned char* lds, const bf16_t* P, bf16_t* YB) {
;     ...
;             for (int tt = 0; tt < 16; ++tt) {
;                 const float r = sigmoidf_(G0[tt * 68 + lane] + ba), ig = sigmoidf_(G1[tt * 68 + lane] + bx);
;                 const float log_a = -sp8 * r;
;                 const float a = __expf(log_a);
;                 const float bb = __builtin_amdgcn_sqrtf(fmaxf(1.0f - a * a, 0.f)) * (ig * u[tt]);
;                 h = a * h + bb;
;                 if (pass == 0) aprod *= a;
;                 else {
;                     const float xg = ldp(P, rbase + tb + tt, 512 + ch);
;                     YB[(rbase + tb + tt) * DM + ch] = (bf16_t)f2bf(h * gelu_tanh_(xg));
.LBB0_406:
	v_add_u32_e32 v57, 0x60, v42
	ds_read2st64_b32 v[58:59], v57 offset0:87 offset1:104
	s_and_b64 vcc, exec, s[12:13]
	s_mov_b64 s[16:17], -1
	s_waitcnt lgkmcnt(0)
	v_add_f32_e32 v57, v27, v58
	v_mul_f32_e32 v57, 0xbfb8aa3b, v57
	v_exp_f32_e32 v57, v57
	v_add_f32_e32 v58, v28, v59
	v_mul_f32_e32 v58, 0xbfb8aa3b, v58
	v_exp_f32_e32 v58, v58
	v_add_f32_e32 v57, 1.0, v57
	v_rcp_f32_e32 v57, v57
	v_add_f32_e32 v58, 1.0, v58
	v_rcp_f32_e32 v58, v58
	v_mul_f32_e32 v57, v35, v57
	v_mul_f32_e32 v57, 0x3fb8aa3b, v57
	v_exp_f32_e32 v57, v57
	v_mul_f32_e32 v56, v56, v58
	v_fma_f32 v59, -v57, v57, 1.0
	v_max_f32_e32 v59, 0, v59
	v_sqrt_f32_e32 v59, v59
	s_nop 0
	v_mul_f32_e32 v56, v56, v59
	v_fmac_f32_e32 v56, v53, v57
	s_cbranch_vccnz .LBB0_408
	v_add_co_u32_e32 v58, vcc, 0x12609000, v22
	s_mov_b64 s[16:17], 0
	s_nop 0
	v_addc_co_u32_e32 v59, vcc, 0, v23, vcc
	s_waitcnt vmcnt(15)
	v_lshlrev_b32_e32 v53, 16, v106
	v_mul_f32_e32 v59, 0x3d372713, v53
	v_mul_f32_e32 v59, v59, v53
	v_mul_f32_e32 v58, 0.5, v53
	v_fmac_f32_e32 v53, v59, v53
	v_mul_f32_e32 v53, 0x3f4c422a, v53
	v_add_f32_e32 v53, v53, v53
	v_mul_f32_e32 v53, 0x3fb8aa3b, v53
	v_exp_f32_e32 v53, v53
	s_nop 0
	v_add_f32_e32 v53, 1.0, v53
	v_rcp_f32_e32 v53, v53
	s_nop 0
	v_fma_f32 v53, v53, -2.0, 1.0
	v_add_f32_e32 v53, 1.0, v53
	v_mul_f32_e32 v53, v58, v53
	v_mul_f32_e32 v53, v56, v53
	v_add_co_u32_e32 v58, vcc, 0xa603000, v20
	v_cvt_pk_bf16_f32 v53, v53, s0
	s_nop 0
	v_addc_co_u32_e32 v59, vcc, 0, v21, vcc
	global_store_short v[58:59], v53, off

; __device__ __forceinline__ unsigned f2bf(float f) { return pk2(f, f) & 0xFFFFu; }
; __device__ __forceinline__ float sigmoidf_(float x) { return rcp_(1.0f + __expf(-x)); }
; __device__ __forceinline__ float gelu_tanh_(float x) { return 0.5f * x * (1.0f + tanhf_(0.7978845608028654f * (x + 0.044715f * x * x * x))); }
; __device__ __forceinline__ float ldp(const bf16_t* P, size_t row, int col) { return bf2f(P[row * NPROJ + col]); }
; __device__ __forceinline__ void rg_block(KP p, int e, int b, int n, LAS unsigned char* lds, const bf16_t* P, bf16_t* YB) {
;     ...
;             for (int tt = 0; tt < 16; ++tt) {
;                 const float r = sigmoidf_(G0[tt * 68 + lane] + ba), ig = sigmoidf_(G1[tt * 68 + lane] + bx);
;                 const float log_a = -sp8 * r;
;                 const float a = __expf(log_a);
;                 const float bb = __builtin_amdgcn_sqrtf(fmaxf(1.0f - a * a, 0.f)) * (ig * u[tt]);
;                 h = a * h + bb;
;                 if (pass == 0) aprod *= a;
;                 else {
;                     const float xg = ldp(P, rbase + tb + tt, 512 + ch);
;                     YB[(rbase + tb + tt) * DM + ch] = (bf16_t)f2bf(h * gelu_tanh_(xg));
.LBB0_410:
	v_add_u32_e32 v53, 0x70, v42
	ds_read2st64_b32 v[58:59], v53 offset0:88 offset1:105
	s_and_b64 vcc, exec, s[12:13]
	s_mov_b64 s[16:17], -1
	s_waitcnt lgkmcnt(0)
	v_add_f32_e32 v53, v27, v58
	v_mul_f32_e32 v53, 0xbfb8aa3b, v53
	v_exp_f32_e32 v53, v53
	v_add_f32_e32 v57, v28, v59
	v_mul_f32_e32 v57, 0xbfb8aa3b, v57
	v_exp_f32_e32 v58, v57
	v_add_f32_e32 v53, 1.0, v53
	v_rcp_f32_e32 v53, v53
	s_nop 0
	v_mul_f32_e32 v53, v35, v53
	v_mul_f32_e32 v53, 0x3fb8aa3b, v53
	v_exp_f32_e32 v57, v53
	v_add_f32_e32 v53, 1.0, v58
	v_rcp_f32_e32 v53, v53
	v_fma_f32 v58, -v57, v57, 1.0
	v_max_f32_e32 v58, 0, v58
	v_sqrt_f32_e32 v58, v58
	v_mul_f32_e32 v53, v55, v53
	v_mul_f32_e32 v53, v53, v58
	v_fmac_f32_e32 v53, v56, v57
	s_cbranch_vccnz .LBB0_412
	v_add_co_u32_e32 v58, vcc, 0x1260b000, v22
	s_mov_b64 s[16:17], 0
	s_nop 0
	v_addc_co_u32_e32 v59, vcc, 0, v23, vcc
	s_waitcnt vmcnt(15)
	v_lshlrev_b32_e32 v55, 16, v107
	v_mul_f32_e32 v58, 0x3d372713, v55
	v_mul_f32_e32 v58, v58, v55
	v_mul_f32_e32 v56, 0.5, v55
	v_fmac_f32_e32 v55, v58, v55
	v_mul_f32_e32 v55, 0x3f4c422a, v55
	v_add_f32_e32 v55, v55, v55
	v_mul_f32_e32 v55, 0x3fb8aa3b, v55
	v_exp_f32_e32 v55, v55
	v_add_co_u32_e32 v58, vcc, 0xa603000, v20
	v_add_f32_e32 v55, 1.0, v55
	v_rcp_f32_e32 v55, v55
	v_addc_co_u32_e32 v59, vcc, 0, v21, vcc
	v_fma_f32 v55, v55, -2.0, 1.0
	v_add_f32_e32 v55, 1.0, v55
	v_mul_f32_e32 v55, v56, v55
	v_mul_f32_e32 v55, v53, v55
	v_cvt_pk_bf16_f32 v55, v55, s0
	global_store_short v[58:59], v55, off offset:2048

; __device__ __forceinline__ unsigned f2bf(float f) { return pk2(f, f) & 0xFFFFu; }
; __device__ __forceinline__ float sigmoidf_(float x) { return rcp_(1.0f + __expf(-x)); }
; __device__ __forceinline__ float gelu_tanh_(float x) { return 0.5f * x * (1.0f + tanhf_(0.7978845608028654f * (x + 0.044715f * x * x * x))); }
; __device__ __forceinline__ float ldp(const bf16_t* P, size_t row, int col) { return bf2f(P[row * NPROJ + col]); }
; __device__ __forceinline__ void rg_block(KP p, int e, int b, int n, LAS unsigned char* lds, const bf16_t* P, bf16_t* YB) {
;     ...
;             for (int tt = 0; tt < 16; ++tt) {
;                 const float r = sigmoidf_(G0[tt * 68 + lane] + ba), ig = sigmoidf_(G1[tt * 68 + lane] + bx);
;                 const float log_a = -sp8 * r;
;                 const float a = __expf(log_a);
;                 const float bb = __builtin_amdgcn_sqrtf(fmaxf(1.0f - a * a, 0.f)) * (ig * u[tt]);
;                 h = a * h + bb;
;                 if (pass == 0) aprod *= a;
;                 else {
;                     const float xg = ldp(P, rbase + tb + tt, 512 + ch);
;                     YB[(rbase + tb + tt) * DM + ch] = (bf16_t)f2bf(h * gelu_tanh_(xg));
.LBB0_414:
	v_add_u32_e32 v55, 0x80, v42
	ds_read2st64_b32 v[56:57], v55 offset0:89 offset1:106
	s_and_b64 vcc, exec, s[12:13]
	s_mov_b64 s[16:17], -1
	s_waitcnt lgkmcnt(0)
	v_add_f32_e32 v55, v27, v56
	v_mul_f32_e32 v55, 0xbfb8aa3b, v55
	v_exp_f32_e32 v55, v55
	v_add_f32_e32 v56, v28, v57
	v_mul_f32_e32 v56, 0xbfb8aa3b, v56
	v_exp_f32_e32 v56, v56
	v_add_f32_e32 v55, 1.0, v55
	v_rcp_f32_e32 v55, v55
	v_add_f32_e32 v56, 1.0, v56
	v_rcp_f32_e32 v56, v56
	v_mul_f32_e32 v55, v35, v55
	v_mul_f32_e32 v55, 0x3fb8aa3b, v55
	v_exp_f32_e32 v55, v55
	v_mul_f32_e32 v54, v54, v56
	v_fma_f32 v57, -v55, v55, 1.0
	v_max_f32_e32 v57, 0, v57
	v_sqrt_f32_e32 v57, v57
	s_nop 0
	v_mul_f32_e32 v54, v54, v57
	v_fmac_f32_e32 v54, v53, v55
	s_cbranch_vccnz .LBB0_416
	v_add_co_u32_e32 v56, vcc, 0x1260d000, v22
	s_mov_b64 s[16:17], 0
	s_nop 0
	v_addc_co_u32_e32 v57, vcc, 0, v23, vcc
	s_waitcnt vmcnt(15)
	v_lshlrev_b32_e32 v53, 16, v108
	v_mul_f32_e32 v57, 0x3d372713, v53
	v_mul_f32_e32 v57, v57, v53
	v_mul_f32_e32 v56, 0.5, v53
	v_fmac_f32_e32 v53, v57, v53
	v_mul_f32_e32 v53, 0x3f4c422a, v53
	v_add_f32_e32 v53, v53, v53
	v_mul_f32_e32 v53, 0x3fb8aa3b, v53
	v_exp_f32_e32 v53, v53
	s_nop 0
	v_add_f32_e32 v53, 1.0, v53
	v_rcp_f32_e32 v53, v53
	s_nop 0
	v_fma_f32 v53, v53, -2.0, 1.0
	v_add_f32_e32 v53, 1.0, v53
	v_mul_f32_e32 v53, v56, v53
	v_mul_f32_e32 v53, v54, v53
	v_add_co_u32_e32 v56, vcc, 0xa604000, v20
	v_cvt_pk_bf16_f32 v53, v53, s0
	s_nop 0
	v_addc_co_u32_e32 v57, vcc, 0, v21, vcc
	global_store_short v[56:57], v53, off

; __device__ __forceinline__ unsigned f2bf(float f) { return pk2(f, f) & 0xFFFFu; }
; __device__ __forceinline__ float sigmoidf_(float x) { return rcp_(1.0f + __expf(-x)); }
; __device__ __forceinline__ float gelu_tanh_(float x) { return 0.5f * x * (1.0f + tanhf_(0.7978845608028654f * (x + 0.044715f * x * x * x))); }
; __device__ __forceinline__ float ldp(const bf16_t* P, size_t row, int col) { return bf2f(P[row * NPROJ + col]); }
; __device__ __forceinline__ void rg_block(KP p, int e, int b, int n, LAS unsigned char* lds, const bf16_t* P, bf16_t* YB) {
;     ...
;             for (int tt = 0; tt < 16; ++tt) {
;                 const float r = sigmoidf_(G0[tt * 68 + lane] + ba), ig = sigmoidf_(G1[tt * 68 + lane] + bx);
;                 const float log_a = -sp8 * r;
;                 const float a = __expf(log_a);
;                 const float bb = __builtin_amdgcn_sqrtf(fmaxf(1.0f - a * a, 0.f)) * (ig * u[tt]);
;                 h = a * h + bb;
;                 if (pass == 0) aprod *= a;
;                 else {
;                     const float xg = ldp(P, rbase + tb + tt, 512 + ch);
;                     YB[(rbase + tb + tt) * DM + ch] = (bf16_t)f2bf(h * gelu_tanh_(xg));
.LBB0_418:
	v_add_u32_e32 v53, 0x90, v42
	ds_read2st64_b32 v[56:57], v53 offset0:90 offset1:107
	s_and_b64 vcc, exec, s[12:13]
	s_mov_b64 s[16:17], -1
	s_waitcnt lgkmcnt(0)
	v_add_f32_e32 v53, v27, v56
	v_mul_f32_e32 v53, 0xbfb8aa3b, v53
	v_exp_f32_e32 v53, v53
	v_add_f32_e32 v55, v28, v57
	v_mul_f32_e32 v55, 0xbfb8aa3b, v55
	v_exp_f32_e32 v55, v55
	v_add_f32_e32 v53, 1.0, v53
	v_rcp_f32_e32 v53, v53
	v_add_f32_e32 v55, 1.0, v55
	v_rcp_f32_e32 v55, v55
	v_mul_f32_e32 v53, v35, v53
	v_mul_f32_e32 v53, 0x3fb8aa3b, v53
	v_exp_f32_e32 v53, v53
	v_mul_f32_e32 v52, v52, v55
	v_fma_f32 v56, -v53, v53, 1.0
	v_max_f32_e32 v56, 0, v56
	v_sqrt_f32_e32 v56, v56
	s_nop 0
	v_mul_f32_e32 v52, v52, v56
	v_fmac_f32_e32 v52, v54, v53
	s_cbranch_vccnz .LBB0_420
	v_add_co_u32_e32 v54, vcc, 0x1260e000, v22
	s_mov_b64 s[16:17], 0
	s_nop 0
	v_addc_co_u32_e32 v55, vcc, 0, v23, vcc
	s_waitcnt vmcnt(15)
	v_lshlrev_b32_e32 v54, 16, v109
	v_mul_f32_e32 v56, 0x3d372713, v54
	v_mul_f32_e32 v56, v56, v54
	v_mul_f32_e32 v55, 0.5, v54
	v_fmac_f32_e32 v54, v56, v54
	v_mul_f32_e32 v54, 0x3f4c422a, v54
	v_add_f32_e32 v54, v54, v54
	v_mul_f32_e32 v54, 0x3fb8aa3b, v54
	v_exp_f32_e32 v54, v54
	s_nop 0
	v_add_f32_e32 v54, 1.0, v54
	v_rcp_f32_e32 v54, v54
	s_nop 0
	v_fma_f32 v54, v54, -2.0, 1.0
	v_add_f32_e32 v54, 1.0, v54
	v_mul_f32_e32 v54, v55, v54
	v_mul_f32_e32 v54, v52, v54
	v_cvt_pk_bf16_f32 v56, v54, s0
	v_add_co_u32_e32 v54, vcc, 0xa604000, v20
	s_nop 1
	v_addc_co_u32_e32 v55, vcc, 0, v21, vcc
	global_store_short v[54:55], v56, off offset:2048

; __device__ __forceinline__ unsigned f2bf(float f) { return pk2(f, f) & 0xFFFFu; }
; __device__ __forceinline__ float sigmoidf_(float x) { return rcp_(1.0f + __expf(-x)); }
; __device__ __forceinline__ float gelu_tanh_(float x) { return 0.5f * x * (1.0f + tanhf_(0.7978845608028654f * (x + 0.044715f * x * x * x))); }
; __device__ __forceinline__ float ldp(const bf16_t* P, size_t row, int col) { return bf2f(P[row * NPROJ + col]); }
; __device__ __forceinline__ void rg_block(KP p, int e, int b, int n, LAS unsigned char* lds, const bf16_t* P, bf16_t* YB) {
;     ...
;             for (int tt = 0; tt < 16; ++tt) {
;                 const float r = sigmoidf_(G0[tt * 68 + lane] + ba), ig = sigmoidf_(G1[tt * 68 + lane] + bx);
;                 const float log_a = -sp8 * r;
;                 const float a = __expf(log_a);
;                 const float bb = __builtin_amdgcn_sqrtf(fmaxf(1.0f - a * a, 0.f)) * (ig * u[tt]);
;                 h = a * h + bb;
;                 if (pass == 0) aprod *= a;
;                 else {
;                     const float xg = ldp(P, rbase + tb + tt, 512 + ch);
;                     YB[(rbase + tb + tt) * DM + ch] = (bf16_t)f2bf(h * gelu_tanh_(xg));
.LBB0_422:
	v_add_u32_e32 v53, 0xa0, v42
	ds_read2st64_b32 v[54:55], v53 offset0:91 offset1:108
	s_and_b64 vcc, exec, s[12:13]
	s_mov_b64 s[16:17], -1
	s_waitcnt lgkmcnt(0)
	v_add_f32_e32 v53, v27, v54
	v_mul_f32_e32 v53, 0xbfb8aa3b, v53
	v_exp_f32_e32 v53, v53
	v_add_f32_e32 v54, v28, v55
	v_mul_f32_e32 v54, 0xbfb8aa3b, v54
	v_exp_f32_e32 v54, v54
	v_add_f32_e32 v53, 1.0, v53
	v_rcp_f32_e32 v53, v53
	v_add_f32_e32 v54, 1.0, v54
	v_rcp_f32_e32 v54, v54
	v_mul_f32_e32 v53, v35, v53
	v_mul_f32_e32 v53, 0x3fb8aa3b, v53
	v_exp_f32_e32 v53, v53
	v_mul_f32_e32 v51, v51, v54
	v_fma_f32 v55, -v53, v53, 1.0
	v_max_f32_e32 v55, 0, v55
	v_sqrt_f32_e32 v55, v55
	s_nop 0
	v_mul_f32_e32 v51, v51, v55
	v_fmac_f32_e32 v51, v52, v53
	s_cbranch_vccnz .LBB0_424
	v_add_co_u32_e32 v54, vcc, 0x12610000, v22
	s_mov_b64 s[16:17], 0
	s_nop 0
	v_addc_co_u32_e32 v55, vcc, 0, v23, vcc
	s_waitcnt vmcnt(15)
	v_lshlrev_b32_e32 v52, 16, v110
	v_mul_f32_e32 v55, 0x3d372713, v52
	v_mul_f32_e32 v55, v55, v52
	v_mul_f32_e32 v54, 0.5, v52
	v_fmac_f32_e32 v52, v55, v52
	v_mul_f32_e32 v52, 0x3f4c422a, v52
	v_add_f32_e32 v52, v52, v52
	v_mul_f32_e32 v52, 0x3fb8aa3b, v52
	v_exp_f32_e32 v52, v52
	s_nop 0
	v_add_f32_e32 v52, 1.0, v52
	v_rcp_f32_e32 v52, v52
	s_nop 0
	v_fma_f32 v52, v52, -2.0, 1.0
	v_add_f32_e32 v52, 1.0, v52
	v_mul_f32_e32 v52, v54, v52
	v_mul_f32_e32 v52, v51, v52
	v_add_co_u32_e32 v54, vcc, 0xa605000, v20
	v_cvt_pk_bf16_f32 v52, v52, s0
	s_nop 0
	v_addc_co_u32_e32 v55, vcc, 0, v21, vcc
	global_store_short v[54:55], v52, off

; __device__ __forceinline__ unsigned f2bf(float f) { return pk2(f, f) & 0xFFFFu; }
; __device__ __forceinline__ float sigmoidf_(float x) { return rcp_(1.0f + __expf(-x)); }
; __device__ __forceinline__ float gelu_tanh_(float x) { return 0.5f * x * (1.0f + tanhf_(0.7978845608028654f * (x + 0.044715f * x * x * x))); }
; __device__ __forceinline__ float ldp(const bf16_t* P, size_t row, int col) { return bf2f(P[row * NPROJ + col]); }
; __device__ __forceinline__ void rg_block(KP p, int e, int b, int n, LAS unsigned char* lds, const bf16_t* P, bf16_t* YB) {
;     ...
;             for (int tt = 0; tt < 16; ++tt) {
;                 const float r = sigmoidf_(G0[tt * 68 + lane] + ba), ig = sigmoidf_(G1[tt * 68 + lane] + bx);
;                 const float log_a = -sp8 * r;
;                 const float a = __expf(log_a);
;                 const float bb = __builtin_amdgcn_sqrtf(fmaxf(1.0f - a * a, 0.f)) * (ig * u[tt]);
;                 h = a * h + bb;
;                 if (pass == 0) aprod *= a;
;                 else {
;                     const float xg = ldp(P, rbase + tb + tt, 512 + ch);
;                     YB[(rbase + tb + tt) * DM + ch] = (bf16_t)f2bf(h * gelu_tanh_(xg));
.LBB0_426:
	v_add_u32_e32 v52, 0xb0, v42
	ds_read2st64_b32 v[52:53], v52 offset0:92 offset1:109
	s_and_b64 vcc, exec, s[12:13]
	s_mov_b64 s[16:17], -1
	s_waitcnt lgkmcnt(0)
	v_add_f32_e32 v52, v27, v52
	v_mul_f32_e32 v52, 0xbfb8aa3b, v52
	v_exp_f32_e32 v52, v52
	v_add_f32_e32 v53, v28, v53
	v_mul_f32_e32 v53, 0xbfb8aa3b, v53
	v_exp_f32_e32 v53, v53
	v_add_f32_e32 v52, 1.0, v52
	v_rcp_f32_e32 v52, v52
	v_add_f32_e32 v53, 1.0, v53
	v_rcp_f32_e32 v53, v53
	v_mul_f32_e32 v52, v35, v52
	v_mul_f32_e32 v52, 0x3fb8aa3b, v52
	v_exp_f32_e32 v52, v52
	v_mul_f32_e32 v50, v50, v53
	v_fma_f32 v54, -v52, v52, 1.0
	v_max_f32_e32 v54, 0, v54
	v_sqrt_f32_e32 v54, v54
	s_nop 0
	v_mul_f32_e32 v50, v50, v54
	v_fmac_f32_e32 v50, v51, v52
	s_cbranch_vccnz .LBB0_428
	v_add_co_u32_e32 v54, vcc, 0x12611000, v22
	s_mov_b64 s[16:17], 0
	s_nop 0
	v_addc_co_u32_e32 v55, vcc, 0, v23, vcc
	s_waitcnt vmcnt(15)
	v_lshlrev_b32_e32 v51, 16, v111
	v_mul_f32_e32 v54, 0x3d372713, v51
	v_mul_f32_e32 v54, v54, v51
	v_mul_f32_e32 v53, 0.5, v51
	v_fmac_f32_e32 v51, v54, v51
	v_mul_f32_e32 v51, 0x3f4c422a, v51
	v_add_f32_e32 v51, v51, v51
	v_mul_f32_e32 v51, 0x3fb8aa3b, v51
	v_exp_f32_e32 v51, v51
	v_add_co_u32_e32 v54, vcc, 0xa605000, v20
	v_add_f32_e32 v51, 1.0, v51
	v_rcp_f32_e32 v51, v51
	v_addc_co_u32_e32 v55, vcc, 0, v21, vcc
	v_fma_f32 v51, v51, -2.0, 1.0
	v_add_f32_e32 v51, 1.0, v51
	v_mul_f32_e32 v51, v53, v51
	v_mul_f32_e32 v51, v50, v51
	v_cvt_pk_bf16_f32 v51, v51, s0
	global_store_short v[54:55], v51, off offset:2048

; __device__ __forceinline__ unsigned f2bf(float f) { return pk2(f, f) & 0xFFFFu; }
; __device__ __forceinline__ float sigmoidf_(float x) { return rcp_(1.0f + __expf(-x)); }
; __device__ __forceinline__ float gelu_tanh_(float x) { return 0.5f * x * (1.0f + tanhf_(0.7978845608028654f * (x + 0.044715f * x * x * x))); }
; __device__ __forceinline__ float ldp(const bf16_t* P, size_t row, int col) { return bf2f(P[row * NPROJ + col]); }
; __device__ __forceinline__ void rg_block(KP p, int e, int b, int n, LAS unsigned char* lds, const bf16_t* P, bf16_t* YB) {
;     ...
;             for (int tt = 0; tt < 16; ++tt) {
;                 const float r = sigmoidf_(G0[tt * 68 + lane] + ba), ig = sigmoidf_(G1[tt * 68 + lane] + bx);
;                 const float log_a = -sp8 * r;
;                 const float a = __expf(log_a);
;                 const float bb = __builtin_amdgcn_sqrtf(fmaxf(1.0f - a * a, 0.f)) * (ig * u[tt]);
;                 h = a * h + bb;
;                 if (pass == 0) aprod *= a;
;                 else {
;                     const float xg = ldp(P, rbase + tb + tt, 512 + ch);
;                     YB[(rbase + tb + tt) * DM + ch] = (bf16_t)f2bf(h * gelu_tanh_(xg));
.LBB0_430:
	v_add_u32_e32 v51, 0xc0, v42
	ds_read2st64_b32 v[52:53], v51 offset0:93 offset1:110
	s_and_b64 vcc, exec, s[12:13]
	s_mov_b64 s[16:17], -1
	s_waitcnt lgkmcnt(0)
	v_add_f32_e32 v51, v27, v52
	v_mul_f32_e32 v51, 0xbfb8aa3b, v51
	v_exp_f32_e32 v51, v51
	v_add_f32_e32 v52, v28, v53
	v_mul_f32_e32 v52, 0xbfb8aa3b, v52
	v_exp_f32_e32 v52, v52
	v_add_f32_e32 v51, 1.0, v51
	v_rcp_f32_e32 v51, v51
	v_add_f32_e32 v52, 1.0, v52
	v_rcp_f32_e32 v52, v52
	v_mul_f32_e32 v51, v35, v51
	v_mul_f32_e32 v51, 0x3fb8aa3b, v51
	v_exp_f32_e32 v51, v51
	v_mul_f32_e32 v49, v49, v52
	v_fma_f32 v53, -v51, v51, 1.0
	v_max_f32_e32 v53, 0, v53
	v_sqrt_f32_e32 v53, v53
	s_nop 0
	v_mul_f32_e32 v49, v49, v53
	v_fmac_f32_e32 v49, v50, v51
	s_cbranch_vccnz .LBB0_432
	v_add_co_u32_e32 v52, vcc, 0x12613000, v22
	s_mov_b64 s[16:17], 0
	s_nop 0
	v_addc_co_u32_e32 v53, vcc, 0, v23, vcc
	s_waitcnt vmcnt(15)
	v_lshlrev_b32_e32 v50, 16, v112
	v_mul_f32_e32 v53, 0x3d372713, v50
	v_mul_f32_e32 v53, v53, v50
	v_mul_f32_e32 v52, 0.5, v50
	v_fmac_f32_e32 v50, v53, v50
	v_mul_f32_e32 v50, 0x3f4c422a, v50
	v_add_f32_e32 v50, v50, v50
	v_mul_f32_e32 v50, 0x3fb8aa3b, v50
	v_exp_f32_e32 v50, v50
	s_nop 0
	v_add_f32_e32 v50, 1.0, v50
	v_rcp_f32_e32 v50, v50
	s_nop 0
	v_fma_f32 v50, v50, -2.0, 1.0
	v_add_f32_e32 v50, 1.0, v50
	v_mul_f32_e32 v50, v52, v50
	v_mul_f32_e32 v50, v49, v50
	v_add_co_u32_e32 v52, vcc, 0xa606000, v20
	v_cvt_pk_bf16_f32 v50, v50, s0
	s_nop 0
	v_addc_co_u32_e32 v53, vcc, 0, v21, vcc
	global_store_short v[52:53], v50, off

; __device__ __forceinline__ unsigned f2bf(float f) { return pk2(f, f) & 0xFFFFu; }
; __device__ __forceinline__ float sigmoidf_(float x) { return rcp_(1.0f + __expf(-x)); }
; __device__ __forceinline__ float gelu_tanh_(float x) { return 0.5f * x * (1.0f + tanhf_(0.7978845608028654f * (x + 0.044715f * x * x * x))); }
; __device__ __forceinline__ float ldp(const bf16_t* P, size_t row, int col) { return bf2f(P[row * NPROJ + col]); }
; __device__ __forceinline__ void rg_block(KP p, int e, int b, int n, LAS unsigned char* lds, const bf16_t* P, bf16_t* YB) {
;     ...
;             for (int tt = 0; tt < 16; ++tt) {
;                 const float r = sigmoidf_(G0[tt * 68 + lane] + ba), ig = sigmoidf_(G1[tt * 68 + lane] + bx);
;                 const float log_a = -sp8 * r;
;                 const float a = __expf(log_a);
;                 const float bb = __builtin_amdgcn_sqrtf(fmaxf(1.0f - a * a, 0.f)) * (ig * u[tt]);
;                 h = a * h + bb;
;                 if (pass == 0) aprod *= a;
;                 else {
;                     const float xg = ldp(P, rbase + tb + tt, 512 + ch);
;                     YB[(rbase + tb + tt) * DM + ch] = (bf16_t)f2bf(h * gelu_tanh_(xg));
.LBB0_434:
	v_add_u32_e32 v50, 0xd0, v42
	ds_read2st64_b32 v[50:51], v50 offset0:94 offset1:111
	s_and_b64 vcc, exec, s[12:13]
	s_mov_b64 s[16:17], -1
	s_waitcnt lgkmcnt(0)
	v_add_f32_e32 v50, v27, v50
	v_mul_f32_e32 v50, 0xbfb8aa3b, v50
	v_exp_f32_e32 v50, v50
	v_add_f32_e32 v51, v28, v51
	v_mul_f32_e32 v51, 0xbfb8aa3b, v51
	v_exp_f32_e32 v51, v51
	v_add_f32_e32 v50, 1.0, v50
	v_rcp_f32_e32 v50, v50
	v_add_f32_e32 v51, 1.0, v51
	v_rcp_f32_e32 v51, v51
	v_mul_f32_e32 v50, v35, v50
	v_mul_f32_e32 v50, 0x3fb8aa3b, v50
	v_exp_f32_e32 v50, v50
	v_mul_f32_e32 v48, v48, v51
	v_fma_f32 v52, -v50, v50, 1.0
	v_max_f32_e32 v52, 0, v52
	v_sqrt_f32_e32 v52, v52
	s_nop 0
	v_mul_f32_e32 v48, v48, v52
	v_fmac_f32_e32 v48, v49, v50
	s_cbranch_vccnz .LBB0_436
	v_add_co_u32_e32 v52, vcc, 0x12615000, v22
	s_mov_b64 s[16:17], 0
	s_nop 0
	v_addc_co_u32_e32 v53, vcc, 0, v23, vcc
	s_waitcnt vmcnt(15)
	v_lshlrev_b32_e32 v49, 16, v113
	v_mul_f32_e32 v52, 0x3d372713, v49
	v_mul_f32_e32 v52, v52, v49
	v_mul_f32_e32 v51, 0.5, v49
	v_fmac_f32_e32 v49, v52, v49
	v_mul_f32_e32 v49, 0x3f4c422a, v49
	v_add_f32_e32 v49, v49, v49
	v_mul_f32_e32 v49, 0x3fb8aa3b, v49
	v_exp_f32_e32 v49, v49
	v_add_co_u32_e32 v52, vcc, 0xa606000, v20
	v_add_f32_e32 v49, 1.0, v49
	v_rcp_f32_e32 v49, v49
	v_addc_co_u32_e32 v53, vcc, 0, v21, vcc
	v_fma_f32 v49, v49, -2.0, 1.0
	v_add_f32_e32 v49, 1.0, v49
	v_mul_f32_e32 v49, v51, v49
	v_mul_f32_e32 v49, v48, v49
	v_cvt_pk_bf16_f32 v49, v49, s0
	global_store_short v[52:53], v49, off offset:2048

; __device__ __forceinline__ unsigned f2bf(float f) { return pk2(f, f) & 0xFFFFu; }
; __device__ __forceinline__ float sigmoidf_(float x) { return rcp_(1.0f + __expf(-x)); }
; __device__ __forceinline__ float gelu_tanh_(float x) { return 0.5f * x * (1.0f + tanhf_(0.7978845608028654f * (x + 0.044715f * x * x * x))); }
; __device__ __forceinline__ float ldp(const bf16_t* P, size_t row, int col) { return bf2f(P[row * NPROJ + col]); }
; __device__ __forceinline__ void rg_block(KP p, int e, int b, int n, LAS unsigned char* lds, const bf16_t* P, bf16_t* YB) {
;     ...
;             for (int tt = 0; tt < 16; ++tt) {
;                 const float r = sigmoidf_(G0[tt * 68 + lane] + ba), ig = sigmoidf_(G1[tt * 68 + lane] + bx);
;                 const float log_a = -sp8 * r;
;                 const float a = __expf(log_a);
;                 const float bb = __builtin_amdgcn_sqrtf(fmaxf(1.0f - a * a, 0.f)) * (ig * u[tt]);
;                 h = a * h + bb;
;                 if (pass == 0) aprod *= a;
;                 else {
;                     const float xg = ldp(P, rbase + tb + tt, 512 + ch);
;                     YB[(rbase + tb + tt) * DM + ch] = (bf16_t)f2bf(h * gelu_tanh_(xg));
.LBB0_438:
	v_add_u32_e32 v49, 0xe0, v42
	ds_read2st64_b32 v[50:51], v49 offset0:95 offset1:112
	s_and_b64 vcc, exec, s[12:13]
	s_mov_b64 s[16:17], -1
	s_waitcnt lgkmcnt(0)
	v_add_f32_e32 v49, v27, v50
	v_mul_f32_e32 v49, 0xbfb8aa3b, v49
	v_exp_f32_e32 v49, v49
	v_add_f32_e32 v50, v28, v51
	v_mul_f32_e32 v50, 0xbfb8aa3b, v50
	v_exp_f32_e32 v50, v50
	v_add_f32_e32 v49, 1.0, v49
	v_rcp_f32_e32 v49, v49
	v_add_f32_e32 v50, 1.0, v50
	v_rcp_f32_e32 v50, v50
	v_mul_f32_e32 v49, v35, v49
	v_mul_f32_e32 v49, 0x3fb8aa3b, v49
	v_exp_f32_e32 v49, v49
	v_mul_f32_e32 v47, v47, v50
	v_fma_f32 v51, -v49, v49, 1.0
	v_max_f32_e32 v51, 0, v51
	v_sqrt_f32_e32 v51, v51
	s_nop 0
	v_mul_f32_e32 v47, v47, v51
	v_fmac_f32_e32 v47, v48, v49
	s_cbranch_vccnz .LBB0_440
	v_add_co_u32_e32 v50, vcc, 0x12616000, v22
	s_mov_b64 s[16:17], 0
	s_nop 0
	v_addc_co_u32_e32 v51, vcc, 0, v23, vcc
	s_waitcnt vmcnt(15)
	v_lshlrev_b32_e32 v48, 16, v114
	v_mul_f32_e32 v51, 0x3d372713, v48
	v_mul_f32_e32 v51, v51, v48
	v_mul_f32_e32 v50, 0.5, v48
	v_fmac_f32_e32 v48, v51, v48
	v_mul_f32_e32 v48, 0x3f4c422a, v48
	v_add_f32_e32 v48, v48, v48
	v_mul_f32_e32 v48, 0x3fb8aa3b, v48
	v_exp_f32_e32 v48, v48
	s_nop 0
	v_add_f32_e32 v48, 1.0, v48
	v_rcp_f32_e32 v48, v48
	s_nop 0
	v_fma_f32 v48, v48, -2.0, 1.0
	v_add_f32_e32 v48, 1.0, v48
	v_mul_f32_e32 v48, v50, v48
	v_mul_f32_e32 v48, v47, v48
	v_add_co_u32_e32 v50, vcc, 0xa607000, v20
	v_cvt_pk_bf16_f32 v48, v48, s0
	s_nop 0
	v_addc_co_u32_e32 v51, vcc, 0, v21, vcc
	global_store_short v[50:51], v48, off

; __device__ __forceinline__ unsigned f2bf(float f) { return pk2(f, f) & 0xFFFFu; }
; __device__ __forceinline__ float sigmoidf_(float x) { return rcp_(1.0f + __expf(-x)); }
; __device__ __forceinline__ float gelu_tanh_(float x) { return 0.5f * x * (1.0f + tanhf_(0.7978845608028654f * (x + 0.044715f * x * x * x))); }
; __device__ __forceinline__ float ldp(const bf16_t* P, size_t row, int col) { return bf2f(P[row * NPROJ + col]); }
; __device__ __forceinline__ void rg_block(KP p, int e, int b, int n, LAS unsigned char* lds, const bf16_t* P, bf16_t* YB) {
;     ...
;             for (int tt = 0; tt < 16; ++tt) {
;                 const float r = sigmoidf_(G0[tt * 68 + lane] + ba), ig = sigmoidf_(G1[tt * 68 + lane] + bx);
;                 const float log_a = -sp8 * r;
;                 const float a = __expf(log_a);
;                 const float bb = __builtin_amdgcn_sqrtf(fmaxf(1.0f - a * a, 0.f)) * (ig * u[tt]);
;                 h = a * h + bb;
;                 if (pass == 0) aprod *= a;
;                 else {
;                     const float xg = ldp(P, rbase + tb + tt, 512 + ch);
;                     YB[(rbase + tb + tt) * DM + ch] = (bf16_t)f2bf(h * gelu_tanh_(xg));
.LBB0_442:
	v_add_u32_e32 v48, 0xf0, v42
	ds_read2st64_b32 v[48:49], v48 offset0:96 offset1:113
	s_and_b64 vcc, exec, s[12:13]
	s_mov_b64 s[12:13], -1
	s_waitcnt lgkmcnt(0)
	v_add_f32_e32 v48, v27, v48
	v_mul_f32_e32 v48, 0xbfb8aa3b, v48
	v_exp_f32_e32 v48, v48
	v_add_f32_e32 v49, v28, v49
	v_mul_f32_e32 v49, 0xbfb8aa3b, v49
	v_exp_f32_e32 v49, v49
	v_add_f32_e32 v48, 1.0, v48
	v_rcp_f32_e32 v48, v48
	v_add_f32_e32 v49, 1.0, v49
	v_rcp_f32_e32 v49, v49
	v_mul_f32_e32 v48, v35, v48
	v_mul_f32_e32 v48, 0x3fb8aa3b, v48
	v_exp_f32_e32 v48, v48
	v_mul_f32_e32 v46, v46, v49
	v_fma_f32 v50, -v48, v48, 1.0
	v_max_f32_e32 v50, 0, v50
	v_sqrt_f32_e32 v50, v50
	s_nop 0
	v_mul_f32_e32 v53, v46, v50
	v_fmac_f32_e32 v53, v47, v48
	s_cbranch_vccnz .LBB0_444
	v_add_co_u32_e32 v22, vcc, 0x12618000, v22
	s_mov_b64 s[12:13], 0
	s_nop 0
	v_addc_co_u32_e32 v23, vcc, 0, v23, vcc
	v_add_co_u32_e32 v20, vcc, 0xa607000, v20
	s_waitcnt vmcnt(15)
	v_lshlrev_b32_e32 v22, 16, v115
	v_mul_f32_e32 v46, 0x3d372713, v22
	v_mul_f32_e32 v46, v46, v22
	v_mul_f32_e32 v23, 0.5, v22
	v_fmac_f32_e32 v22, v46, v22
	v_mul_f32_e32 v22, 0x3f4c422a, v22
	v_add_f32_e32 v22, v22, v22
	v_mul_f32_e32 v22, 0x3fb8aa3b, v22
	v_exp_f32_e32 v22, v22
	v_addc_co_u32_e32 v21, vcc, 0, v21, vcc
	v_add_f32_e32 v22, 1.0, v22
	v_rcp_f32_e32 v22, v22
	s_nop 0
	v_fma_f32 v22, v22, -2.0, 1.0
	v_add_f32_e32 v22, 1.0, v22
	v_mul_f32_e32 v22, v23, v22
	v_mul_f32_e32 v22, v53, v22
	v_cvt_pk_bf16_f32 v22, v22, s0
	global_store_short v[20:21], v22, off offset:2048

;     __device__ __forceinline__ void operator()(const f32x4 (&acc)[2][2][4][2], const Unit& u, int wr, int wc, int fr, int fq) const {
;     ...
;             f32x4 xv[2][2][2]; f32x2 ms[2];
; #pragma unroll
;             for (int m2 = 0; m2 < 2; ++m2) {
;                 const int row = row0 + ai * 128 + (2 * mh + m2) * 16;
;                 const size_t off = (size_t)row * DM + col0;
;                 ms[m2] = ln ? st[row] : (f32x2){0.f, 1.f};
; #pragma unroll
;                 for (int bj = 0; bj < 2; ++bj)
; #pragma unroll
;                     for (int n = 0; n < 2; ++n) xv[m2][bj][n] = *(const f32x4*)(src + off + bj * 128 + n * 16);
.LBB0_646:
	v_lshl_add_u32 v222, s44, 8, v253
	v_ashrrev_i32_e32 v223, 31, v222
	v_mov_b32_e32 v226, 1.0
	v_mov_b32_e32 v228, 0
	s_and_b64 vcc, exec, s[12:13]
	v_mov_b32_e32 v232, 0
	v_mov_b32_e32 v234, 1.0
	s_cbranch_vccnz .LBB0_648
	v_lshl_add_u64 v[164:165], v[222:223], 3, s[20:21]
	global_load_dwordx2 v[232:233], v[164:165], off
.LBB0_648:
	v_lshl_add_u64 v[224:225], v[162:163], 2, s[28:29]
	v_lshlrev_b64 v[236:237], 12, v[222:223]
	v_lshl_add_u64 v[162:163], v[224:225], 0, v[236:237]
	global_load_dwordx4 v[190:193], v[162:163], off
	global_load_dwordx4 v[186:189], v[162:163], off offset:64
	global_load_dwordx4 v[182:185], v[162:163], off offset:512
	global_load_dwordx4 v[178:181], v[162:163], off offset:576
	v_or_b32_e32 v162, 16, v222
	s_and_b64 vcc, exec, s[12:13]
	v_ashrrev_i32_e32 v163, 31, v162
	s_cbranch_vccnz .LBB0_650
	v_lshl_add_u64 v[164:165], v[162:163], 3, s[20:21]
	global_load_dwordx2 v[228:229], v[164:165], off
;     __device__ __forceinline__ void operator()(const f32x4 (&acc)[2][2][4][2], const Unit& u, int wr, int wc, int fr, int fq) const {
;     ...
;         for (int ai = 0; ai < 2; ++ai)
; #pragma unroll
;         for (int mh = 0; mh < 2; ++mh) {
;             f32x4 xv[2][2][2]; f32x2 ms[2];
; #pragma unroll
;             for (int m2 = 0; m2 < 2; ++m2) {
;                 const int row = row0 + ai * 128 + (2 * mh + m2) * 16;
;                 const size_t off = (size_t)row * DM + col0;
;                 ms[m2] = ln ? st[row] : (f32x2){0.f, 1.f};
; #pragma unroll
;                 for (int bj = 0; bj < 2; ++bj)
; #pragma unroll
;                     for (int n = 0; n < 2; ++n) xv[m2][bj][n] = *(const f32x4*)(src + off + bj * 128 + n * 16);
;             }
;             asm volatile("" ::: "memory");
; #pragma unroll
;             for (int m2 = 0; m2 < 2; ++m2) {
;                 const int m = 2 * mh + m2;
;                 const size_t off = (size_t)(row0 + ai * 128 + m * 16) * DM + col0;
; #pragma unroll
;                 for (int bj = 0; bj < 2; ++bj)
; #pragma unroll
;                     for (int n = 0; n < 2; ++n) {
;                         const f32x4 x = (xv[m2][bj][n] - ms[m2].x) * ms[m2].y * gv[bj][n] + bv[bj][n];
;                         *(f32x4*)(dst + off + bj * 128 + n * 16) = x * DN_ALPHA + acc[ai][bj][m][n] * scale;
;                     }
;             }
;             asm volatile("" ::: "memory");
.LBB0_650:
	v_lshlrev_b64 v[230:231], 12, v[162:163]
	v_lshl_add_u64 v[162:163], v[224:225], 0, v[230:231]
	global_load_dwordx4 v[174:177], v[162:163], off
	global_load_dwordx4 v[170:173], v[162:163], off offset:64
	global_load_dwordx4 v[166:169], v[162:163], off offset:512
	s_nop 0
	global_load_dwordx4 v[162:165], v[162:163], off offset:576
	s_waitcnt vmcnt(0)
	v_cndmask_b32_e64 v234, v233, v234, s[12:13]
	v_cndmask_b32_e64 v226, v229, v226, s[12:13]
	v_sub_f32_e32 v191, v191, v232
	v_sub_f32_e32 v190, v190, v232
	v_sub_f32_e32 v193, v193, v232
	v_sub_f32_e32 v192, v192, v232
	v_pk_mul_f32 v[190:191], v[234:235], v[190:191] op_sel_hi:[0,1]
	v_pk_mul_f32 v[192:193], v[234:235], v[192:193] op_sel_hi:[0,1]
	v_pk_fma_f32 v[190:191], v[106:107], v[190:191], v[110:111]
	v_mov_b32_e32 v211, v210
	v_pk_mul_f32 v[158:159], v[158:159], v[214:215]
	v_pk_fma_f32 v[192:193], v[108:109], v[192:193], v[112:113]
	v_pk_mul_f32 v[160:161], v[160:161], v[210:211]
	v_pk_fma_f32 v[158:159], v[190:191], s[88:89], v[158:159] op_sel_hi:[1,0,1]
	v_lshl_add_u64 v[190:191], s[48:49], 0, v[236:237]
	v_pk_fma_f32 v[160:161], v[192:193], s[88:89], v[160:161] op_sel_hi:[1,0,1]
	v_lshl_add_u64 v[190:191], v[190:191], 0, v[220:221]
	global_store_dwordx4 v[190:191], v[158:161], off
	v_pk_mul_f32 v[156:157], v[156:157], v[210:211]
	v_pk_mul_f32 v[154:155], v[154:155], v[214:215]
	v_sub_f32_e32 v159, v187, v232
	v_sub_f32_e32 v158, v186, v232
	v_sub_f32_e32 v161, v189, v232
	v_sub_f32_e32 v160, v188, v232
	v_pk_mul_f32 v[160:161], v[234:235], v[160:161] op_sel_hi:[0,1]
	v_pk_mul_f32 v[158:159], v[234:235], v[158:159] op_sel_hi:[0,1]
	v_pk_fma_f32 v[158:159], v[98:99], v[158:159], v[102:103]
	v_pk_fma_f32 v[160:161], v[100:101], v[160:161], v[104:105]
	v_pk_fma_f32 v[154:155], v[158:159], s[88:89], v[154:155] op_sel_hi:[1,0,1]
	v_pk_fma_f32 v[156:157], v[160:161], s[88:89], v[156:157] op_sel_hi:[1,0,1]
	global_store_dwordx4 v[190:191], v[154:157], off offset:64
	v_pk_mul_f32 v[152:153], v[152:153], v[210:211]
	v_pk_mul_f32 v[150:151], v[150:151], v[214:215]
	v_sub_f32_e32 v155, v183, v232
	v_sub_f32_e32 v154, v182, v232
	v_sub_f32_e32 v157, v185, v232
	v_sub_f32_e32 v156, v184, v232
	v_pk_mul_f32 v[156:157], v[234:235], v[156:157] op_sel_hi:[0,1]
	v_pk_mul_f32 v[154:155], v[234:235], v[154:155] op_sel_hi:[0,1]
	v_pk_fma_f32 v[154:155], v[122:123], v[154:155], v[126:127]
	v_pk_fma_f32 v[156:157], v[124:125], v[156:157], v[128:129]
	v_pk_fma_f32 v[150:151], v[154:155], s[88:89], v[150:151] op_sel_hi:[1,0,1]
	v_pk_fma_f32 v[152:153], v[156:157], s[88:89], v[152:153] op_sel_hi:[1,0,1]
	global_store_dwordx4 v[190:191], v[150:153], off offset:512
	v_pk_mul_f32 v[148:149], v[148:149], v[210:211]
	v_pk_mul_f32 v[146:147], v[146:147], v[214:215]
	v_sub_f32_e32 v151, v179, v232
	v_sub_f32_e32 v150, v178, v232
	v_sub_f32_e32 v153, v181, v232
	v_sub_f32_e32 v152, v180, v232
	v_pk_mul_f32 v[152:153], v[234:235], v[152:153] op_sel_hi:[0,1]
	v_pk_mul_f32 v[150:151], v[234:235], v[150:151] op_sel_hi:[0,1]
	v_pk_fma_f32 v[150:151], v[114:115], v[150:151], v[118:119]
	v_pk_fma_f32 v[152:153], v[116:117], v[152:153], v[120:121]
	v_pk_fma_f32 v[146:147], v[150:151], s[88:89], v[146:147] op_sel_hi:[1,0,1]
	v_pk_fma_f32 v[148:149], v[152:153], s[88:89], v[148:149] op_sel_hi:[1,0,1]
	global_store_dwordx4 v[190:191], v[146:149], off offset:576
	v_pk_mul_f32 v[144:145], v[144:145], v[210:211]
	v_pk_mul_f32 v[142:143], v[142:143], v[214:215]
	v_pk_mul_f32 v[140:141], v[140:141], v[210:211]
	v_pk_mul_f32 v[138:139], v[138:139], v[214:215]
	v_pk_mul_f32 v[136:137], v[136:137], v[210:211]
	v_pk_mul_f32 v[134:135], v[134:135], v[214:215]
	s_and_b64 vcc, exec, s[12:13]
	v_mov_b32_e32 v152, 0
	v_sub_f32_e32 v147, v175, v228
	v_sub_f32_e32 v146, v174, v228
	v_sub_f32_e32 v149, v177, v228
	v_sub_f32_e32 v148, v176, v228
	v_pk_mul_f32 v[148:149], v[226:227], v[148:149] op_sel_hi:[0,1]
	v_pk_mul_f32 v[146:147], v[226:227], v[146:147] op_sel_hi:[0,1]
	v_pk_fma_f32 v[150:151], v[106:107], v[146:147], v[110:111]
	v_pk_fma_f32 v[146:147], v[108:109], v[148:149], v[112:113]
	v_mov_b32_e32 v148, 0
	v_pk_fma_f32 v[146:147], v[146:147], s[88:89], v[144:145] op_sel_hi:[1,0,1]
	v_pk_fma_f32 v[144:145], v[150:151], s[88:89], v[142:143] op_sel_hi:[1,0,1]
	v_lshl_add_u64 v[142:143], s[48:49], 0, v[230:231]
	v_lshl_add_u64 v[142:143], v[142:143], 0, v[220:221]
	global_store_dwordx4 v[142:143], v[144:147], off
	v_mov_b32_e32 v150, 1.0
	s_nop 0
	v_sub_f32_e32 v145, v171, v228
	v_sub_f32_e32 v144, v170, v228
	v_sub_f32_e32 v147, v173, v228
	v_sub_f32_e32 v146, v172, v228
	v_pk_mul_f32 v[146:147], v[226:227], v[146:147] op_sel_hi:[0,1]
	v_pk_mul_f32 v[144:145], v[226:227], v[144:145] op_sel_hi:[0,1]
	v_pk_fma_f32 v[144:145], v[98:99], v[144:145], v[102:103]
	v_pk_fma_f32 v[146:147], v[100:101], v[146:147], v[104:105]
	v_pk_fma_f32 v[138:139], v[144:145], s[88:89], v[138:139] op_sel_hi:[1,0,1]
	v_pk_fma_f32 v[140:141], v[146:147], s[88:89], v[140:141] op_sel_hi:[1,0,1]
	global_store_dwordx4 v[142:143], v[138:141], off offset:64
	v_mov_b32_e32 v146, 1.0
	s_nop 0
	v_sub_f32_e32 v139, v167, v228
	v_sub_f32_e32 v138, v166, v228
	v_sub_f32_e32 v141, v169, v228
	v_sub_f32_e32 v140, v168, v228
	v_pk_mul_f32 v[140:141], v[226:227], v[140:141] op_sel_hi:[0,1]
	v_pk_mul_f32 v[138:139], v[226:227], v[138:139] op_sel_hi:[0,1]
	v_pk_fma_f32 v[138:139], v[122:123], v[138:139], v[126:127]
	v_pk_fma_f32 v[140:141], v[124:125], v[140:141], v[128:129]
	v_pk_fma_f32 v[134:135], v[138:139], s[88:89], v[134:135] op_sel_hi:[1,0,1]
	v_pk_fma_f32 v[136:137], v[140:141], s[88:89], v[136:137] op_sel_hi:[1,0,1]
	global_store_dwordx4 v[142:143], v[134:137], off offset:512
	s_nop 1
	v_sub_f32_e32 v135, v165, v228
	v_sub_f32_e32 v134, v164, v228
	v_sub_f32_e32 v137, v163, v228
	v_sub_f32_e32 v136, v162, v228
	v_pk_mul_f32 v[136:137], v[226:227], v[136:137] op_sel_hi:[0,1]
	v_pk_mul_f32 v[134:135], v[226:227], v[134:135] op_sel_hi:[0,1]
	v_pk_fma_f32 v[134:135], v[116:117], v[134:135], v[120:121]
	v_pk_fma_f32 v[136:137], v[114:115], v[136:137], v[118:119]
	v_pk_mul_f32 v[134:135], v[134:135], s[88:89] op_sel_hi:[1,0]
	v_pk_mul_f32 v[136:137], v[136:137], s[88:89] op_sel_hi:[1,0]
	v_pk_fma_f32 v[132:133], v[132:133], v[210:211], v[134:135]
	v_pk_fma_f32 v[130:131], v[130:131], v[214:215], v[136:137]
	global_store_dwordx4 v[142:143], v[130:133], off offset:576
	s_nop 1
	v_or_b32_e32 v130, 32, v222
	v_ashrrev_i32_e32 v131, 31, v130
	s_cbranch_vccnz .LBB0_652
	v_lshl_add_u64 v[132:133], v[130:131], 3, s[20:21]
	global_load_dwordx2 v[152:153], v[132:133], off

;     __device__ __forceinline__ void operator()(const f32x4 (&acc)[2][2][4][2], const Unit& u, int wr, int wc, int fr, int fq) const {
;     ...
;         for (int ai = 0; ai < 2; ++ai)
; #pragma unroll
;         for (int mh = 0; mh < 2; ++mh) {
;             f32x4 xv[2][2][2]; f32x2 ms[2];
; #pragma unroll
;             for (int m2 = 0; m2 < 2; ++m2) {
;                 const int row = row0 + ai * 128 + (2 * mh + m2) * 16;
;                 const size_t off = (size_t)row * DM + col0;
;                 ms[m2] = ln ? st[row] : (f32x2){0.f, 1.f};
; #pragma unroll
;                 for (int bj = 0; bj < 2; ++bj)
; #pragma unroll
;                     for (int n = 0; n < 2; ++n) xv[m2][bj][n] = *(const f32x4*)(src + off + bj * 128 + n * 16);
;             }
;             asm volatile("" ::: "memory");
; #pragma unroll
;             for (int m2 = 0; m2 < 2; ++m2) {
;                 const int m = 2 * mh + m2;
;                 const size_t off = (size_t)(row0 + ai * 128 + m * 16) * DM + col0;
; #pragma unroll
;                 for (int bj = 0; bj < 2; ++bj)
; #pragma unroll
;                     for (int n = 0; n < 2; ++n) {
;                         const f32x4 x = (xv[m2][bj][n] - ms[m2].x) * ms[m2].y * gv[bj][n] + bv[bj][n];
;                         *(f32x4*)(dst + off + bj * 128 + n * 16) = x * DN_ALPHA + acc[ai][bj][m][n] * scale;
;                     }
;             }
;             asm volatile("" ::: "memory");
.LBB0_654:
	v_lshlrev_b64 v[164:165], 12, v[156:157]
	v_lshl_add_u64 v[166:167], v[224:225], 0, v[164:165]
	global_load_dwordx4 v[156:159], v[166:167], off
	global_load_dwordx4 v[160:163], v[166:167], off offset:64
	s_waitcnt vmcnt(5)
	v_cndmask_b32_e64 v150, v153, v150, s[12:13]
	v_sub_f32_e32 v169, v145, v152
	v_sub_f32_e32 v168, v144, v152
	v_sub_f32_e32 v171, v143, v152
	v_sub_f32_e32 v170, v142, v152
	global_load_dwordx4 v[142:145], v[166:167], off offset:512
	s_waitcnt vmcnt(5)
	v_sub_f32_e32 v141, v141, v152
	v_sub_f32_e32 v140, v140, v152
	v_sub_f32_e32 v139, v139, v152
	v_sub_f32_e32 v138, v138, v152
	s_waitcnt vmcnt(4)
	v_sub_f32_e32 v137, v137, v152
	v_sub_f32_e32 v136, v136, v152
	v_sub_f32_e32 v135, v135, v152
	v_sub_f32_e32 v134, v134, v152
	s_waitcnt vmcnt(3)
	v_cndmask_b32_e64 v146, v149, v146, s[12:13]
	v_sub_f32_e32 v173, v133, v152
	v_sub_f32_e32 v172, v132, v152
	v_sub_f32_e32 v153, v131, v152
	v_sub_f32_e32 v152, v130, v152
	global_load_dwordx4 v[130:133], v[166:167], off offset:576
	v_pk_mul_f32 v[166:167], v[150:151], v[170:171] op_sel_hi:[0,1]
	v_pk_mul_f32 v[168:169], v[150:151], v[168:169] op_sel_hi:[0,1]
	v_pk_mul_f32 v[134:135], v[150:151], v[134:135] op_sel_hi:[0,1]
	v_pk_mul_f32 v[136:137], v[150:151], v[136:137] op_sel_hi:[0,1]
	v_pk_mul_f32 v[138:139], v[150:151], v[138:139] op_sel_hi:[0,1]
	v_pk_mul_f32 v[140:141], v[150:151], v[140:141] op_sel_hi:[0,1]
	v_pk_mul_f32 v[152:153], v[150:151], v[152:153] op_sel_hi:[0,1]
	v_pk_mul_f32 v[150:151], v[150:151], v[172:173] op_sel_hi:[0,1]
	v_pk_fma_f32 v[168:169], v[108:109], v[168:169], v[112:113]
	v_pk_fma_f32 v[166:167], v[106:107], v[166:167], v[110:111]
	v_pk_fma_f32 v[136:137], v[124:125], v[136:137], v[128:129]
	v_pk_fma_f32 v[134:135], v[122:123], v[134:135], v[126:127]
	v_mov_b32_e32 v211, v210
	v_lshl_add_u64 v[154:155], s[48:49], 0, v[154:155]
	v_pk_fma_f32 v[140:141], v[100:101], v[140:141], v[104:105]
	v_pk_fma_f32 v[138:139], v[98:99], v[138:139], v[102:103]
	v_pk_fma_f32 v[150:151], v[116:117], v[150:151], v[120:121]
	v_pk_fma_f32 v[152:153], v[114:115], v[152:153], v[118:119]
	v_pk_mul_f32 v[166:167], v[166:167], s[88:89] op_sel_hi:[1,0]
	v_pk_mul_f32 v[168:169], v[168:169], s[88:89] op_sel_hi:[1,0]
	v_pk_mul_f32 v[134:135], v[134:135], s[88:89] op_sel_hi:[1,0]
	v_pk_mul_f32 v[136:137], v[136:137], s[88:89] op_sel_hi:[1,0]
	v_lshl_add_u64 v[154:155], v[154:155], 0, v[220:221]
	v_pk_mul_f32 v[138:139], v[138:139], s[88:89] op_sel_hi:[1,0]
	v_pk_mul_f32 v[140:141], v[140:141], s[88:89] op_sel_hi:[1,0]
	v_pk_mul_f32 v[152:153], v[152:153], s[88:89] op_sel_hi:[1,0]
	v_pk_mul_f32 v[150:151], v[150:151], s[88:89] op_sel_hi:[1,0]
	v_pk_fma_f32 v[96:97], v[96:97], v[210:211], v[168:169]
	v_pk_fma_f32 v[94:95], v[94:95], v[214:215], v[166:167]
	v_pk_fma_f32 v[88:89], v[88:89], v[210:211], v[136:137]
	v_pk_fma_f32 v[86:87], v[86:87], v[214:215], v[134:135]
	v_pk_fma_f32 v[92:93], v[92:93], v[210:211], v[140:141]
	v_pk_fma_f32 v[90:91], v[90:91], v[214:215], v[138:139]
	v_pk_fma_f32 v[84:85], v[84:85], v[210:211], v[150:151]
	v_pk_fma_f32 v[82:83], v[82:83], v[214:215], v[152:153]
	global_store_dwordx4 v[154:155], v[94:97], off
	global_store_dwordx4 v[154:155], v[90:93], off offset:64
	global_store_dwordx4 v[154:155], v[86:89], off offset:512
	global_store_dwordx4 v[154:155], v[82:85], off offset:576
	v_lshl_add_u64 v[164:165], s[48:49], 0, v[164:165]
	v_lshl_add_u64 v[164:165], v[164:165], 0, v[220:221]
	s_and_b64 vcc, exec, s[12:13]
	s_waitcnt vmcnt(7)
	v_sub_f32_e32 v83, v159, v148
	s_waitcnt vmcnt(6)
	v_sub_f32_e32 v87, v163, v148
	v_sub_f32_e32 v86, v162, v148
	v_sub_f32_e32 v89, v161, v148
	v_sub_f32_e32 v88, v160, v148
	v_pk_mul_f32 v[88:89], v[146:147], v[88:89] op_sel_hi:[0,1]
	v_pk_mul_f32 v[86:87], v[146:147], v[86:87] op_sel_hi:[0,1]
	v_pk_fma_f32 v[86:87], v[100:101], v[86:87], v[104:105]
	v_pk_fma_f32 v[88:89], v[98:99], v[88:89], v[102:103]
	v_pk_mul_f32 v[86:87], v[86:87], s[88:89] op_sel_hi:[1,0]
	v_pk_mul_f32 v[88:89], v[88:89], s[88:89] op_sel_hi:[1,0]
	v_pk_fma_f32 v[76:77], v[76:77], v[210:211], v[86:87]
	v_pk_fma_f32 v[74:75], v[74:75], v[214:215], v[88:89]
	global_store_dwordx4 v[164:165], v[74:77], off offset:64
	v_sub_f32_e32 v82, v158, v148
	v_sub_f32_e32 v85, v157, v148
	s_waitcnt vmcnt(6)
	v_sub_f32_e32 v75, v145, v148
	v_sub_f32_e32 v74, v144, v148
	v_sub_f32_e32 v77, v143, v148
	v_sub_f32_e32 v76, v142, v148
	v_pk_mul_f32 v[76:77], v[146:147], v[76:77] op_sel_hi:[0,1]
	v_pk_mul_f32 v[74:75], v[146:147], v[74:75] op_sel_hi:[0,1]
	v_pk_fma_f32 v[74:75], v[124:125], v[74:75], v[128:129]
	v_pk_fma_f32 v[76:77], v[122:123], v[76:77], v[126:127]
	v_pk_mul_f32 v[74:75], v[74:75], s[88:89] op_sel_hi:[1,0]
	v_pk_mul_f32 v[76:77], v[76:77], s[88:89] op_sel_hi:[1,0]
	v_pk_fma_f32 v[72:73], v[72:73], v[210:211], v[74:75]
	v_pk_fma_f32 v[70:71], v[70:71], v[214:215], v[76:77]
	v_sub_f32_e32 v84, v156, v148
	global_store_dwordx4 v[164:165], v[70:73], off offset:512
	v_pk_mul_f32 v[84:85], v[146:147], v[84:85] op_sel_hi:[0,1]
	v_pk_mul_f32 v[82:83], v[146:147], v[82:83] op_sel_hi:[0,1]
	s_waitcnt vmcnt(6)
	v_sub_f32_e32 v71, v133, v148
	v_sub_f32_e32 v70, v132, v148
	v_sub_f32_e32 v73, v131, v148
	v_sub_f32_e32 v72, v130, v148
	v_pk_mul_f32 v[72:73], v[146:147], v[72:73] op_sel_hi:[0,1]
	v_pk_mul_f32 v[70:71], v[146:147], v[70:71] op_sel_hi:[0,1]
	v_pk_fma_f32 v[82:83], v[108:109], v[82:83], v[112:113]
	v_pk_fma_f32 v[84:85], v[106:107], v[84:85], v[110:111]
	v_pk_fma_f32 v[70:71], v[116:117], v[70:71], v[120:121]
	v_pk_fma_f32 v[72:73], v[114:115], v[72:73], v[118:119]
	v_pk_mul_f32 v[84:85], v[84:85], s[88:89] op_sel_hi:[1,0]
	v_pk_mul_f32 v[82:83], v[82:83], s[88:89] op_sel_hi:[1,0]
	v_pk_mul_f32 v[72:73], v[72:73], s[88:89] op_sel_hi:[1,0]
	v_pk_mul_f32 v[70:71], v[70:71], s[88:89] op_sel_hi:[1,0]
	v_pk_fma_f32 v[80:81], v[80:81], v[210:211], v[82:83]
	v_pk_fma_f32 v[78:79], v[78:79], v[214:215], v[84:85]
	v_pk_fma_f32 v[68:69], v[68:69], v[210:211], v[70:71]
	v_pk_fma_f32 v[66:67], v[66:67], v[214:215], v[72:73]
	global_store_dwordx4 v[164:165], v[78:81], off
	global_store_dwordx4 v[164:165], v[66:69], off offset:576
	v_mov_b32_e32 v82, 1.0
	v_mov_b32_e32 v84, 0
	v_add_u32_e32 v66, 0x80, v222
	v_ashrrev_i32_e32 v67, 31, v66
	v_mov_b32_e32 v88, 0
	v_mov_b32_e32 v86, 1.0
	s_cbranch_vccnz .LBB0_656
	v_lshl_add_u64 v[68:69], v[66:67], 3, s[20:21]
	global_load_dwordx2 v[88:89], v[68:69], off

;     __device__ __forceinline__ void operator()(const f32x4 (&acc)[2][2][4][2], const Unit& u, int wr, int wc, int fr, int fq) const {
;     ...
;         for (int ai = 0; ai < 2; ++ai)
; #pragma unroll
;         for (int mh = 0; mh < 2; ++mh) {
;             f32x4 xv[2][2][2]; f32x2 ms[2];
; #pragma unroll
;             for (int m2 = 0; m2 < 2; ++m2) {
;                 const int row = row0 + ai * 128 + (2 * mh + m2) * 16;
;                 const size_t off = (size_t)row * DM + col0;
;                 ms[m2] = ln ? st[row] : (f32x2){0.f, 1.f};
; #pragma unroll
;                 for (int bj = 0; bj < 2; ++bj)
; #pragma unroll
;                     for (int n = 0; n < 2; ++n) xv[m2][bj][n] = *(const f32x4*)(src + off + bj * 128 + n * 16);
;             }
;             asm volatile("" ::: "memory");
; #pragma unroll
;             for (int m2 = 0; m2 < 2; ++m2) {
;                 const int m = 2 * mh + m2;
;                 const size_t off = (size_t)(row0 + ai * 128 + m * 16) * DM + col0;
; #pragma unroll
;                 for (int bj = 0; bj < 2; ++bj)
; #pragma unroll
;                     for (int n = 0; n < 2; ++n) {
;                         const f32x4 x = (xv[m2][bj][n] - ms[m2].x) * ms[m2].y * gv[bj][n] + bv[bj][n];
;                         *(f32x4*)(dst + off + bj * 128 + n * 16) = x * DN_ALPHA + acc[ai][bj][m][n] * scale;
;                     }
;             }
;             asm volatile("" ::: "memory");
.LBB0_658:
	v_lshlrev_b64 v[96:97], 12, v[92:93]
	v_lshl_add_u64 v[134:135], v[224:225], 0, v[96:97]
	global_load_dwordx4 v[92:95], v[134:135], off
	global_load_dwordx4 v[130:133], v[134:135], off offset:64
	s_waitcnt vmcnt(5)
	v_cndmask_b32_e64 v86, v89, v86, s[12:13]
	v_sub_f32_e32 v137, v81, v88
	v_sub_f32_e32 v136, v80, v88
	v_sub_f32_e32 v139, v79, v88
	v_sub_f32_e32 v138, v78, v88
	global_load_dwordx4 v[78:81], v[134:135], off offset:512
	s_waitcnt vmcnt(5)
	v_sub_f32_e32 v77, v77, v88
	v_sub_f32_e32 v76, v76, v88
	v_sub_f32_e32 v75, v75, v88
	v_sub_f32_e32 v74, v74, v88
	s_waitcnt vmcnt(4)
	v_sub_f32_e32 v73, v73, v88
	v_sub_f32_e32 v72, v72, v88
	v_sub_f32_e32 v71, v71, v88
	v_sub_f32_e32 v70, v70, v88
	s_waitcnt vmcnt(3)
	v_cndmask_b32_e64 v82, v85, v82, s[12:13]
	v_sub_f32_e32 v141, v69, v88
	v_sub_f32_e32 v140, v68, v88
	v_sub_f32_e32 v89, v67, v88
	v_sub_f32_e32 v88, v66, v88
	global_load_dwordx4 v[66:69], v[134:135], off offset:576
	v_pk_mul_f32 v[134:135], v[86:87], v[138:139] op_sel_hi:[0,1]
	v_pk_mul_f32 v[136:137], v[86:87], v[136:137] op_sel_hi:[0,1]
	v_pk_mul_f32 v[70:71], v[86:87], v[70:71] op_sel_hi:[0,1]
	v_pk_mul_f32 v[72:73], v[86:87], v[72:73] op_sel_hi:[0,1]
	v_pk_mul_f32 v[74:75], v[86:87], v[74:75] op_sel_hi:[0,1]
	v_pk_mul_f32 v[76:77], v[86:87], v[76:77] op_sel_hi:[0,1]
	v_pk_mul_f32 v[88:89], v[86:87], v[88:89] op_sel_hi:[0,1]
	v_pk_mul_f32 v[86:87], v[86:87], v[140:141] op_sel_hi:[0,1]
	v_pk_fma_f32 v[136:137], v[108:109], v[136:137], v[112:113]
	v_pk_fma_f32 v[134:135], v[106:107], v[134:135], v[110:111]
	v_pk_fma_f32 v[72:73], v[124:125], v[72:73], v[128:129]
	v_pk_fma_f32 v[70:71], v[122:123], v[70:71], v[126:127]
	v_mov_b32_e32 v211, v210
	v_lshl_add_u64 v[90:91], s[48:49], 0, v[90:91]
	v_pk_fma_f32 v[76:77], v[100:101], v[76:77], v[104:105]
	v_pk_fma_f32 v[74:75], v[98:99], v[74:75], v[102:103]
	v_pk_fma_f32 v[86:87], v[116:117], v[86:87], v[120:121]
	v_pk_fma_f32 v[88:89], v[114:115], v[88:89], v[118:119]
	v_pk_mul_f32 v[134:135], v[134:135], s[88:89] op_sel_hi:[1,0]
	v_pk_mul_f32 v[136:137], v[136:137], s[88:89] op_sel_hi:[1,0]
	v_pk_mul_f32 v[70:71], v[70:71], s[88:89] op_sel_hi:[1,0]
	v_pk_mul_f32 v[72:73], v[72:73], s[88:89] op_sel_hi:[1,0]
	v_lshl_add_u64 v[90:91], v[90:91], 0, v[220:221]
	v_pk_mul_f32 v[74:75], v[74:75], s[88:89] op_sel_hi:[1,0]
	v_pk_mul_f32 v[76:77], v[76:77], s[88:89] op_sel_hi:[1,0]
	v_pk_mul_f32 v[88:89], v[88:89], s[88:89] op_sel_hi:[1,0]
	v_pk_mul_f32 v[86:87], v[86:87], s[88:89] op_sel_hi:[1,0]
	v_pk_fma_f32 v[64:65], v[64:65], v[210:211], v[136:137]
	v_pk_fma_f32 v[62:63], v[62:63], v[214:215], v[134:135]
	v_pk_fma_f32 v[56:57], v[56:57], v[210:211], v[72:73]
	v_pk_fma_f32 v[54:55], v[54:55], v[214:215], v[70:71]
	v_pk_fma_f32 v[60:61], v[60:61], v[210:211], v[76:77]
	v_pk_fma_f32 v[58:59], v[58:59], v[214:215], v[74:75]
	v_pk_fma_f32 v[52:53], v[52:53], v[210:211], v[86:87]
	v_pk_fma_f32 v[50:51], v[50:51], v[214:215], v[88:89]
	global_store_dwordx4 v[90:91], v[62:65], off
	global_store_dwordx4 v[90:91], v[58:61], off offset:64
	global_store_dwordx4 v[90:91], v[54:57], off offset:512
	global_store_dwordx4 v[90:91], v[50:53], off offset:576
	v_lshl_add_u64 v[96:97], s[48:49], 0, v[96:97]
	v_lshl_add_u64 v[96:97], v[96:97], 0, v[220:221]
	s_and_b64 vcc, exec, s[12:13]
	s_waitcnt vmcnt(7)
	v_sub_f32_e32 v51, v95, v84
	s_waitcnt vmcnt(6)
	v_sub_f32_e32 v55, v133, v84
	v_sub_f32_e32 v54, v132, v84
	v_sub_f32_e32 v57, v131, v84
	v_sub_f32_e32 v56, v130, v84
	v_pk_mul_f32 v[56:57], v[82:83], v[56:57] op_sel_hi:[0,1]
	v_pk_mul_f32 v[54:55], v[82:83], v[54:55] op_sel_hi:[0,1]
	v_pk_fma_f32 v[54:55], v[100:101], v[54:55], v[104:105]
	v_pk_fma_f32 v[56:57], v[98:99], v[56:57], v[102:103]
	v_pk_mul_f32 v[54:55], v[54:55], s[88:89] op_sel_hi:[1,0]
	v_pk_mul_f32 v[56:57], v[56:57], s[88:89] op_sel_hi:[1,0]
	v_pk_fma_f32 v[44:45], v[44:45], v[210:211], v[54:55]
	v_pk_fma_f32 v[42:43], v[42:43], v[214:215], v[56:57]
	global_store_dwordx4 v[96:97], v[42:45], off offset:64
	v_sub_f32_e32 v50, v94, v84
	v_sub_f32_e32 v53, v93, v84
	s_waitcnt vmcnt(6)
	v_sub_f32_e32 v43, v81, v84
	v_sub_f32_e32 v42, v80, v84
	v_sub_f32_e32 v45, v79, v84
	v_sub_f32_e32 v44, v78, v84
	v_pk_mul_f32 v[44:45], v[82:83], v[44:45] op_sel_hi:[0,1]
	v_pk_mul_f32 v[42:43], v[82:83], v[42:43] op_sel_hi:[0,1]
	v_pk_fma_f32 v[42:43], v[124:125], v[42:43], v[128:129]
	v_pk_fma_f32 v[44:45], v[122:123], v[44:45], v[126:127]
	v_pk_mul_f32 v[42:43], v[42:43], s[88:89] op_sel_hi:[1,0]
	v_pk_mul_f32 v[44:45], v[44:45], s[88:89] op_sel_hi:[1,0]
	v_pk_fma_f32 v[40:41], v[40:41], v[210:211], v[42:43]
	v_pk_fma_f32 v[38:39], v[38:39], v[214:215], v[44:45]
	v_sub_f32_e32 v52, v92, v84
	global_store_dwordx4 v[96:97], v[38:41], off offset:512
	v_pk_mul_f32 v[52:53], v[82:83], v[52:53] op_sel_hi:[0,1]
	v_pk_mul_f32 v[50:51], v[82:83], v[50:51] op_sel_hi:[0,1]
	s_waitcnt vmcnt(6)
	v_sub_f32_e32 v39, v69, v84
	v_sub_f32_e32 v38, v68, v84
	v_sub_f32_e32 v41, v67, v84
	v_sub_f32_e32 v40, v66, v84
	v_pk_mul_f32 v[40:41], v[82:83], v[40:41] op_sel_hi:[0,1]
	v_pk_mul_f32 v[38:39], v[82:83], v[38:39] op_sel_hi:[0,1]
	v_pk_fma_f32 v[50:51], v[108:109], v[50:51], v[112:113]
	v_pk_fma_f32 v[52:53], v[106:107], v[52:53], v[110:111]
	v_pk_fma_f32 v[38:39], v[116:117], v[38:39], v[120:121]
	v_pk_fma_f32 v[40:41], v[114:115], v[40:41], v[118:119]
	v_pk_mul_f32 v[52:53], v[52:53], s[88:89] op_sel_hi:[1,0]
	v_pk_mul_f32 v[50:51], v[50:51], s[88:89] op_sel_hi:[1,0]
	v_pk_mul_f32 v[40:41], v[40:41], s[88:89] op_sel_hi:[1,0]
	v_pk_mul_f32 v[38:39], v[38:39], s[88:89] op_sel_hi:[1,0]
	v_pk_fma_f32 v[48:49], v[48:49], v[210:211], v[50:51]
	v_pk_fma_f32 v[46:47], v[46:47], v[214:215], v[52:53]
	v_pk_fma_f32 v[36:37], v[36:37], v[210:211], v[38:39]
	v_pk_fma_f32 v[34:35], v[34:35], v[214:215], v[40:41]
	global_store_dwordx4 v[96:97], v[46:49], off
	global_store_dwordx4 v[96:97], v[34:37], off offset:576
	v_mov_b32_e32 v50, 1.0
	v_mov_b32_e32 v52, 0
	v_add_u32_e32 v34, 0xa0, v222
	v_ashrrev_i32_e32 v35, 31, v34
	v_mov_b32_e32 v56, 0
	v_mov_b32_e32 v54, 1.0
	s_cbranch_vccnz .LBB0_660
	v_lshl_add_u64 v[36:37], v[34:35], 3, s[20:21]
	global_load_dwordx2 v[56:57], v[36:37], off

;     __device__ __forceinline__ void done(const pg8::Unit& u) const {
;         asm volatile("s_waitcnt vmcnt(0)" ::: "memory");
;         const int owner = (u.pm >> 5) + 8 * ((u.pm & 7) + 8 * ((u.pm >> 3) & 3));
;         if ((unsigned)xcc_of[owner] != myx) { __builtin_amdgcn_fence(__ATOMIC_RELEASE, "agent"); asm volatile("s_waitcnt vmcnt(0)" ::: "memory"); }
;     __device__ __forceinline__ void operator()(const f32x4 (&acc)[2][2][4][2], const Unit& u, int wr, int wc, int fr, int fq) const {
;     ...
;         for (int ai = 0; ai < 2; ++ai)
; #pragma unroll
;         for (int mh = 0; mh < 2; ++mh) {
;             f32x4 xv[2][2][2]; f32x2 ms[2];
; #pragma unroll
;             for (int m2 = 0; m2 < 2; ++m2) {
;                 const int row = row0 + ai * 128 + (2 * mh + m2) * 16;
;                 const size_t off = (size_t)row * DM + col0;
;                 ms[m2] = ln ? st[row] : (f32x2){0.f, 1.f};
; #pragma unroll
;                 for (int bj = 0; bj < 2; ++bj)
; #pragma unroll
;                     for (int n = 0; n < 2; ++n) xv[m2][bj][n] = *(const f32x4*)(src + off + bj * 128 + n * 16);
;             }
;             asm volatile("" ::: "memory");
; #pragma unroll
;             for (int m2 = 0; m2 < 2; ++m2) {
;                 const int m = 2 * mh + m2;
;                 const size_t off = (size_t)(row0 + ai * 128 + m * 16) * DM + col0;
; #pragma unroll
;                 for (int bj = 0; bj < 2; ++bj)
; #pragma unroll
;                     for (int n = 0; n < 2; ++n) {
;                         const f32x4 x = (xv[m2][bj][n] - ms[m2].x) * ms[m2].y * gv[bj][n] + bv[bj][n];
;                         *(f32x4*)(dst + off + bj * 128 + n * 16) = x * DN_ALPHA + acc[ai][bj][m][n] * scale;
;                     }
;             }
;             asm volatile("" ::: "memory");
.LBB0_662:
	v_lshlrev_b64 v[68:69], 12, v[60:61]
	v_lshl_add_u64 v[70:71], v[224:225], 0, v[68:69]
	global_load_dwordx4 v[60:63], v[70:71], off
	global_load_dwordx4 v[64:67], v[70:71], off offset:64
	s_waitcnt vmcnt(5)
	v_cndmask_b32_e64 v54, v57, v54, s[12:13]
	v_sub_f32_e32 v73, v49, v56
	v_sub_f32_e32 v72, v48, v56
	v_sub_f32_e32 v75, v47, v56
	v_sub_f32_e32 v74, v46, v56
	global_load_dwordx4 v[46:49], v[70:71], off offset:512
	s_waitcnt vmcnt(5)
	v_sub_f32_e32 v45, v45, v56
	v_sub_f32_e32 v44, v44, v56
	v_sub_f32_e32 v43, v43, v56
	v_sub_f32_e32 v42, v42, v56
	s_waitcnt vmcnt(4)
	v_sub_f32_e32 v41, v41, v56
	v_sub_f32_e32 v40, v40, v56
	v_sub_f32_e32 v39, v39, v56
	v_sub_f32_e32 v38, v38, v56
	s_waitcnt vmcnt(3)
	v_cndmask_b32_e64 v50, v53, v50, s[12:13]
	v_sub_f32_e32 v77, v37, v56
	v_sub_f32_e32 v76, v36, v56
	v_sub_f32_e32 v57, v35, v56
	v_sub_f32_e32 v56, v34, v56
	global_load_dwordx4 v[34:37], v[70:71], off offset:576
	v_pk_mul_f32 v[70:71], v[54:55], v[74:75] op_sel_hi:[0,1]
	v_pk_mul_f32 v[72:73], v[54:55], v[72:73] op_sel_hi:[0,1]
	v_pk_mul_f32 v[38:39], v[54:55], v[38:39] op_sel_hi:[0,1]
	v_pk_mul_f32 v[40:41], v[54:55], v[40:41] op_sel_hi:[0,1]
	v_pk_mul_f32 v[42:43], v[54:55], v[42:43] op_sel_hi:[0,1]
	v_pk_mul_f32 v[44:45], v[54:55], v[44:45] op_sel_hi:[0,1]
	v_pk_mul_f32 v[56:57], v[54:55], v[56:57] op_sel_hi:[0,1]
	v_pk_mul_f32 v[54:55], v[54:55], v[76:77] op_sel_hi:[0,1]
	v_pk_fma_f32 v[72:73], v[108:109], v[72:73], v[112:113]
	v_pk_fma_f32 v[70:71], v[106:107], v[70:71], v[110:111]
	v_pk_fma_f32 v[40:41], v[124:125], v[40:41], v[128:129]
	v_pk_fma_f32 v[38:39], v[122:123], v[38:39], v[126:127]
	v_mov_b32_e32 v211, v210
	v_lshl_add_u64 v[58:59], s[48:49], 0, v[58:59]
	v_pk_fma_f32 v[44:45], v[100:101], v[44:45], v[104:105]
	v_pk_fma_f32 v[42:43], v[98:99], v[42:43], v[102:103]
	v_pk_fma_f32 v[54:55], v[116:117], v[54:55], v[120:121]
	v_pk_fma_f32 v[56:57], v[114:115], v[56:57], v[118:119]
	v_pk_mul_f32 v[70:71], v[70:71], s[88:89] op_sel_hi:[1,0]
	v_pk_mul_f32 v[72:73], v[72:73], s[88:89] op_sel_hi:[1,0]
	v_pk_mul_f32 v[38:39], v[38:39], s[88:89] op_sel_hi:[1,0]
	v_pk_mul_f32 v[40:41], v[40:41], s[88:89] op_sel_hi:[1,0]
	v_lshl_add_u64 v[58:59], v[58:59], 0, v[220:221]
	v_pk_mul_f32 v[42:43], v[42:43], s[88:89] op_sel_hi:[1,0]
	v_pk_mul_f32 v[44:45], v[44:45], s[88:89] op_sel_hi:[1,0]
	v_pk_mul_f32 v[56:57], v[56:57], s[88:89] op_sel_hi:[1,0]
	v_pk_mul_f32 v[54:55], v[54:55], s[88:89] op_sel_hi:[1,0]
	v_pk_fma_f32 v[32:33], v[32:33], v[210:211], v[72:73]
	v_pk_fma_f32 v[30:31], v[30:31], v[214:215], v[70:71]
	v_pk_fma_f32 v[24:25], v[24:25], v[210:211], v[40:41]
	v_pk_fma_f32 v[22:23], v[22:23], v[214:215], v[38:39]
	v_pk_fma_f32 v[28:29], v[28:29], v[210:211], v[44:45]
	v_pk_fma_f32 v[26:27], v[26:27], v[214:215], v[42:43]
	v_pk_fma_f32 v[20:21], v[20:21], v[210:211], v[54:55]
	v_pk_fma_f32 v[18:19], v[18:19], v[214:215], v[56:57]
	global_store_dwordx4 v[58:59], v[30:33], off
	global_store_dwordx4 v[58:59], v[26:29], off offset:64
	global_store_dwordx4 v[58:59], v[22:25], off offset:512
	global_store_dwordx4 v[58:59], v[18:21], off offset:576
	v_lshl_add_u64 v[68:69], s[48:49], 0, v[68:69]
	v_lshl_add_u64 v[68:69], v[68:69], 0, v[220:221]
	s_lshl_b32 s13, s44, 3
	s_ashr_i32 s12, s44, 5
	s_and_b32 s13, s13, 0xf8
	s_add_i32 s13, s13, s12
	s_ashr_i32 s33, s13, 31
	s_add_u32 s12, s90, s13
	s_addc_u32 s13, s91, s33
	s_waitcnt vmcnt(7)
	v_sub_f32_e32 v19, v63, v52
	s_waitcnt vmcnt(6)
	v_sub_f32_e32 v23, v67, v52
	v_sub_f32_e32 v22, v66, v52
	v_sub_f32_e32 v25, v65, v52
	v_sub_f32_e32 v24, v64, v52
	v_pk_mul_f32 v[24:25], v[50:51], v[24:25] op_sel_hi:[0,1]
	v_pk_mul_f32 v[22:23], v[50:51], v[22:23] op_sel_hi:[0,1]
	v_pk_fma_f32 v[22:23], v[100:101], v[22:23], v[104:105]
	v_pk_fma_f32 v[24:25], v[98:99], v[24:25], v[102:103]
	v_pk_mul_f32 v[22:23], v[22:23], s[88:89] op_sel_hi:[1,0]
	v_pk_mul_f32 v[24:25], v[24:25], s[88:89] op_sel_hi:[1,0]
	v_pk_fma_f32 v[12:13], v[12:13], v[210:211], v[22:23]
	v_pk_fma_f32 v[10:11], v[10:11], v[214:215], v[24:25]
	global_store_dwordx4 v[68:69], v[10:13], off offset:64
	v_sub_f32_e32 v18, v62, v52
	v_sub_f32_e32 v21, v61, v52
	s_waitcnt vmcnt(6)
	v_sub_f32_e32 v11, v49, v52
	v_sub_f32_e32 v10, v48, v52
	v_sub_f32_e32 v13, v47, v52
	v_sub_f32_e32 v12, v46, v52
	v_pk_mul_f32 v[12:13], v[50:51], v[12:13] op_sel_hi:[0,1]
	v_pk_mul_f32 v[10:11], v[50:51], v[10:11] op_sel_hi:[0,1]
	v_pk_fma_f32 v[10:11], v[124:125], v[10:11], v[128:129]
	v_pk_fma_f32 v[12:13], v[122:123], v[12:13], v[126:127]
	v_pk_mul_f32 v[10:11], v[10:11], s[88:89] op_sel_hi:[1,0]
	v_pk_mul_f32 v[12:13], v[12:13], s[88:89] op_sel_hi:[1,0]
	v_pk_fma_f32 v[8:9], v[8:9], v[210:211], v[10:11]
	v_pk_fma_f32 v[6:7], v[6:7], v[214:215], v[12:13]
	v_sub_f32_e32 v20, v60, v52
	global_store_dwordx4 v[68:69], v[6:9], off offset:512
	v_pk_mul_f32 v[20:21], v[50:51], v[20:21] op_sel_hi:[0,1]
	v_pk_mul_f32 v[18:19], v[50:51], v[18:19] op_sel_hi:[0,1]
	s_waitcnt vmcnt(6)
	v_sub_f32_e32 v7, v37, v52
	v_sub_f32_e32 v6, v36, v52
	v_sub_f32_e32 v9, v35, v52
	v_sub_f32_e32 v8, v34, v52
	v_pk_mul_f32 v[8:9], v[50:51], v[8:9] op_sel_hi:[0,1]
	v_pk_mul_f32 v[6:7], v[50:51], v[6:7] op_sel_hi:[0,1]
	v_pk_fma_f32 v[18:19], v[108:109], v[18:19], v[112:113]
	v_pk_fma_f32 v[20:21], v[106:107], v[20:21], v[110:111]
	v_pk_fma_f32 v[6:7], v[116:117], v[6:7], v[120:121]
	v_pk_fma_f32 v[8:9], v[114:115], v[8:9], v[118:119]
	v_pk_mul_f32 v[20:21], v[20:21], s[88:89] op_sel_hi:[1,0]
	v_pk_mul_f32 v[18:19], v[18:19], s[88:89] op_sel_hi:[1,0]
	v_pk_mul_f32 v[8:9], v[8:9], s[88:89] op_sel_hi:[1,0]
	v_pk_mul_f32 v[6:7], v[6:7], s[88:89] op_sel_hi:[1,0]
	v_pk_fma_f32 v[16:17], v[16:17], v[210:211], v[18:19]
	v_pk_fma_f32 v[14:15], v[14:15], v[214:215], v[20:21]
	v_pk_fma_f32 v[4:5], v[4:5], v[210:211], v[6:7]
	v_pk_fma_f32 v[2:3], v[2:3], v[214:215], v[8:9]
	global_store_dwordx4 v[68:69], v[14:17], off
	global_store_dwordx4 v[68:69], v[2:5], off offset:576
	s_waitcnt vmcnt(0)
	global_load_ubyte v2, v1, s[12:13]
	s_waitcnt vmcnt(0)
	v_cmp_eq_u32_e32 vcc, s96, v2
	s_cbranch_vccnz .LBB0_664
	buffer_wbl2 sc1
	s_waitcnt vmcnt(0)
